# streamed GEMM phases: the 128 accumulator clears of each unit issued behind the previous unit's last epilogue store (inside the wait for the stores) instead of at the head of the unit
# speedup vs baseline: 1.0033x; 1.0033x over previous
; #define STAGE(P_, BASE, br, kt) do { const u16* _gb = (BASE) + (long)(br) * K + (long)(kt) * BK; \
;     _Pragma("unroll") for (int _i = 0; _i < 2; ++_i) { \
;       __builtin_amdgcn_global_load_lds((const unsigned*)(_gb + (long)_i * 64 * K + lane_off), \
;         (unsigned*)((char*)(P_) + lds_wbase + _i * 8192), 16, 0, 0); } } while (0)
; #define WAIT_V(n) asm volatile("s_waitcnt vmcnt(" #n ")" ::: "memory")
; #define BAR __builtin_amdgcn_s_barrier()
; template <int PRE> ...
;     ...
;   if (PRE == 2) {
;     STAGE(SB(0, 0), Bt, bcol, 0); STAGE(SA(0, 0), A, brow, 0);
;     STAGE(SB(0, 1), Bt, bcol + HALF, 0); STAGE(SA(0, 1), A, brow + HALF, 0);
;     if (wr == 1) BAR;
;     WAIT_V(4); BAR;
;     STAGE(SB(1, 0), Bt, bcol, 1); STAGE(SA(1, 0), A, brow, 1); STAGE(SB(1, 1), Bt, bcol + HALF, 1);
;     WAIT_V(6); BAR;
;     return;
;     ...
; #pragma unroll
;     for (int a = 0; a < 2; ++a)
; #pragma unroll
;       for (int b = 0; b < 2; ++b)
; #pragma unroll
;         for (int m = 0; m < 4; ++m)
; #pragma unroll
;           for (int n = 0; n < 2; ++n) acc[a][b][m][n] = f32x4{0.f, 0.f, 0.f, 0.f};
.LBB0_176:
	s_mov_b64 s[2:3], 0x80
	s_add_i32 s23, s12, 0x18000
	v_lshl_add_u64 v[12:13], v[0:1], 0, s[2:3]
	s_mov_b32 m0, s23
	s_mov_b64 s[4:5], 0x40080
	s_add_i32 s24, s12, 0x1a000
	s_waitcnt vmcnt(4)
	s_barrier
	global_load_lds_dwordx4 v[12:13], off
	v_lshl_add_u64 v[0:1], v[0:1], 0, s[4:5]
	s_mov_b32 m0, s24
	s_add_i32 s25, s12, 0x8000
	global_load_lds_dwordx4 v[0:1], off
	v_lshl_add_u64 v[0:1], v[2:3], 0, s[2:3]
	s_mov_b32 m0, s25
	s_add_i32 s26, s12, 0xa000
	global_load_lds_dwordx4 v[0:1], off
	v_lshl_add_u64 v[0:1], v[2:3], 0, s[4:5]
	s_mov_b32 m0, s26
	s_add_i32 s27, s12, 0x1c000
	global_load_lds_dwordx4 v[0:1], off
	v_lshl_add_u64 v[0:1], v[4:5], 0, s[2:3]
	s_mov_b32 m0, s27
	s_add_i32 s28, s12, 0x1e000
	global_load_lds_dwordx4 v[0:1], off
	v_lshl_add_u64 v[0:1], v[4:5], 0, s[4:5]
	s_mov_b32 m0, s28
	v_lshlrev_b32_e32 v3, 2, v6
	global_load_lds_dwordx4 v[0:1], off
	v_and_b32_e32 v0, 15, v6
	v_and_b32_e32 v1, 48, v6
	v_lshlrev_b32_e32 v2, 6, v0
	v_and_b32_e32 v3, 32, v3
	v_readlane_b32 s1, v246, 52
	v_bitop3_b32 v141, v2, v3, v1 bitop3:0x36
	v_readlane_b32 s2, v244, 16
	v_or_b32_e32 v2, s1, v0
	v_lshlrev_b32_e32 v3, 6, v2
	v_lshlrev_b32_e32 v2, 2, v2
	v_and_b32_e32 v3, 0x3c0, v3
	v_and_b32_e32 v2, 32, v2
	v_readlane_b32 s1, v246, 51
	v_bitop3_b32 v2, v3, v2, v1 bitop3:0x36
	s_waitcnt vmcnt(6)
	v_readlane_b32 s3, v244, 17
	v_or_b32_e32 v3, s1, v0
	v_lshlrev_b32_e32 v4, 6, v3
	v_lshlrev_b32_e32 v3, 2, v3
	v_and_b32_e32 v4, 0x3c0, v4
	v_and_b32_e32 v3, 32, v3
	v_readlane_b32 s1, v246, 53
	v_bitop3_b32 v3, v4, v3, v1 bitop3:0x36
	v_and_b32_e32 v140, 63, v6
	v_or_b32_e32 v4, s1, v0
	v_lshlrev_b32_e32 v5, 6, v4
	v_lshlrev_b32_e32 v4, 2, v4
	v_readlane_b32 s1, v246, 54
	v_and_b32_e32 v5, 0x3c0, v5
	v_and_b32_e32 v4, 32, v4
	v_or_b32_e32 v0, s1, v0
	v_bitop3_b32 v4, v5, v4, v1 bitop3:0x36
	v_lshlrev_b32_e32 v5, 6, v0
	v_lshlrev_b32_e32 v0, 2, v0
	v_and_b32_e32 v5, 0x3c0, v5
	v_and_b32_e32 v0, 32, v0
	v_bitop3_b32 v0, v5, v0, v1 bitop3:0x36
	v_lshlrev_b32_e32 v1, 14, v7
	v_and_b32_e32 v1, 0xffff8000, v1
	v_lshl_add_u32 v1, v8, 11, v1
	v_readlane_b32 s1, v244, 12
	v_or_b32_e32 v1, v1, v9
	v_add_u32_sdwa v144, v1, sext(v10) dst_sel:DWORD dst_unused:UNUSED_PAD src0_sel:DWORD src1_sel:WORD_0
	v_add_u32_e32 v142, s1, v2
	v_readlane_b32 s1, v244, 13
	v_lshl_add_u64 v[132:133], v[144:145], 1, s[2:3]
	s_barrier
	v_add_u32_e32 v143, s1, v3
	v_readlane_b32 s1, v244, 14
	s_nop 1
	v_add_u32_e32 v144, s1, v4
	v_readlane_b32 s1, v244, 15
	s_nop 1
	v_add_u32_e32 v146, s1, v0
	v_mov_b32_e32 v0, 0
	v_mov_b32_e32 v1, v0
	v_mov_b32_e32 v2, v0
	v_mov_b32_e32 v3, v0
	v_mov_b32_e32 v4, v0
	v_mov_b32_e32 v5, v0
	v_mov_b32_e32 v6, v0
	v_mov_b32_e32 v7, v0
	v_mov_b32_e32 v8, v0
	v_mov_b32_e32 v9, v0
	v_mov_b32_e32 v10, v0
	v_mov_b32_e32 v11, v0
	v_mov_b32_e32 v12, v0
	v_mov_b32_e32 v13, v0
	v_mov_b32_e32 v14, v0
	v_mov_b32_e32 v15, v0
	v_mov_b32_e32 v16, v0
	v_mov_b32_e32 v17, v0
	v_mov_b32_e32 v18, v0
	v_mov_b32_e32 v19, v0
	v_mov_b32_e32 v20, v0
	v_mov_b32_e32 v21, v0
	v_mov_b32_e32 v22, v0
	v_mov_b32_e32 v23, v0
	v_mov_b32_e32 v24, v0
	v_mov_b32_e32 v25, v0
	v_mov_b32_e32 v26, v0
	v_mov_b32_e32 v27, v0
	v_mov_b32_e32 v28, v0
	v_mov_b32_e32 v29, v0
	v_mov_b32_e32 v30, v0
	v_mov_b32_e32 v31, v0
	v_mov_b32_e32 v32, v0
	v_mov_b32_e32 v33, v0
	v_mov_b32_e32 v34, v0
	v_mov_b32_e32 v35, v0
	v_mov_b32_e32 v36, v0
	v_mov_b32_e32 v37, v0
	v_mov_b32_e32 v38, v0
	v_mov_b32_e32 v39, v0
	v_mov_b32_e32 v40, v0
	v_mov_b32_e32 v41, v0
	v_mov_b32_e32 v42, v0
	v_mov_b32_e32 v43, v0
	v_mov_b32_e32 v44, v0
	v_mov_b32_e32 v45, v0
	v_mov_b32_e32 v46, v0
	v_mov_b32_e32 v47, v0
	v_mov_b32_e32 v48, v0
	v_mov_b32_e32 v49, v0
	v_mov_b32_e32 v50, v0
	v_mov_b32_e32 v51, v0
	v_mov_b32_e32 v52, v0
	v_mov_b32_e32 v53, v0
	v_mov_b32_e32 v54, v0
	v_mov_b32_e32 v55, v0
	v_mov_b32_e32 v56, v0
	v_mov_b32_e32 v57, v0
	v_mov_b32_e32 v58, v0
	v_mov_b32_e32 v59, v0
	v_mov_b32_e32 v60, v0
	v_mov_b32_e32 v61, v0
	v_mov_b32_e32 v62, v0
	v_mov_b32_e32 v63, v0
	v_mov_b32_e32 v64, v0
	v_mov_b32_e32 v65, v0
	v_mov_b32_e32 v66, v0
	v_mov_b32_e32 v67, v0
	v_mov_b32_e32 v70, v0
	v_mov_b32_e32 v71, v0
	v_mov_b32_e32 v72, v0
	v_mov_b32_e32 v73, v0
	v_mov_b32_e32 v74, v0
	v_mov_b32_e32 v75, v0
	v_mov_b32_e32 v76, v0
	v_mov_b32_e32 v77, v0
	v_mov_b32_e32 v78, v0
	v_mov_b32_e32 v79, v0
	v_mov_b32_e32 v80, v0
	v_mov_b32_e32 v81, v0
	v_mov_b32_e32 v82, v0
	v_mov_b32_e32 v83, v0
	v_mov_b32_e32 v84, v0
	v_mov_b32_e32 v85, v0
	v_mov_b32_e32 v86, v0
	v_mov_b32_e32 v87, v0
	v_mov_b32_e32 v88, v0
	v_mov_b32_e32 v89, v0
	v_mov_b32_e32 v90, v0
	v_mov_b32_e32 v91, v0
	v_mov_b32_e32 v92, v0
	v_mov_b32_e32 v93, v0
	v_mov_b32_e32 v94, v0
	v_mov_b32_e32 v95, v0
	v_mov_b32_e32 v96, v0
	v_mov_b32_e32 v97, v0
	v_mov_b32_e32 v98, v0
	v_mov_b32_e32 v99, v0
	v_mov_b32_e32 v100, v0
	v_mov_b32_e32 v101, v0
	v_mov_b32_e32 v102, v0
	v_mov_b32_e32 v103, v0
	v_mov_b32_e32 v104, v0
	v_mov_b32_e32 v105, v0
	v_mov_b32_e32 v106, v0
	v_mov_b32_e32 v107, v0
	v_mov_b32_e32 v108, v0
	v_mov_b32_e32 v109, v0
	v_mov_b32_e32 v110, v0
	v_mov_b32_e32 v111, v0
	v_mov_b32_e32 v112, v0
	v_mov_b32_e32 v113, v0
	v_mov_b32_e32 v114, v0
	v_mov_b32_e32 v115, v0
	v_mov_b32_e32 v116, v0
	v_mov_b32_e32 v117, v0
	v_mov_b32_e32 v118, v0
	v_mov_b32_e32 v119, v0
	v_mov_b32_e32 v120, v0
	v_mov_b32_e32 v121, v0
	v_mov_b32_e32 v122, v0
	v_mov_b32_e32 v123, v0
	v_mov_b32_e32 v124, v0
	v_mov_b32_e32 v125, v0
	v_mov_b32_e32 v126, v0
	v_mov_b32_e32 v127, v0
	v_mov_b32_e32 v128, v0
	v_mov_b32_e32 v129, v0
	s_branch .LBB0_178

;     ...
;   for (int u = vb; u < nunits; u += ustride) {
;     const int tm = u % nM, tn = u / nM + ((tn_skip >= 0 && u / nM >= tn_skip) ? 1 : 0);
;     const int brow = tn * 256, bcol = tm * 256;
;     const int un = u + ustride;
;     const bool has_next = un < nunits;
;     const int tn_n = un / nM + ((tn_skip >= 0 && un / nM >= tn_skip) ? 1 : 0);
;     const int brow_n = has_next ? tn_n * 256 : brow, bcol_n = has_next ? (un % nM) * 256 : bcol;
.LBB0_180:
	s_ashr_i32 s3, s1, 6
	s_cmpk_gt_i32 s0, 0x3bf
	s_cselect_b64 s[0:1], -1, 0
	s_cmp_lg_u64 s[0:1], 0
	s_addc_u32 s30, s3, 0
	s_lshl_b32 s0, s30, 8
	s_cmpk_gt_i32 s29, 0x3bf
	s_cselect_b64 s[6:7], -1, 0
	s_cmp_lg_u64 s[6:7], 0
	s_addc_u32 s1, s2, 0
	s_lshl_b32 s1, s1, 8
	s_and_b64 s[2:3], s[8:9], exec
	s_cselect_b32 s31, s1, s0
	s_ashr_i32 s1, s0, 31
	s_lshl_b64 s[2:3], s[0:1], 12
	s_mov_b32 s38, 0
	s_or_b32 s34, s0, 0x80
	s_or_b32 s35, s11, 0x80
	s_or_b32 s36, s10, 0x80
	s_or_b32 s37, s31, 0x80
	v_lshl_add_u64 v[134:135], v[132:133], 0, s[2:3]

;     ...
; #pragma unroll
;     for (int a = 0; a < 2; ++a)
; #pragma unroll
;       for (int b = 0; b < 2; ++b)
; #pragma unroll
;         for (int m = 0; m < 4; ++m)
; #pragma unroll
;           for (int n = 0; n < 2; ++n) acc[a][b][m][n] = f32x4{0.f, 0.f, 0.f, 0.f};
;     ...
;     asm volatile("s_waitcnt vmcnt(0)" ::: "memory");
;     if (has_next && wr == 1) __builtin_amdgcn_s_barrier();
.LBB0_268:
	s_nop 1
	v_mov_b32_e32 v0, 0
	v_mov_b32_e32 v1, v0
	v_mov_b32_e32 v2, v0
	v_mov_b32_e32 v3, v0
	v_mov_b32_e32 v4, v0
	v_mov_b32_e32 v5, v0
	v_mov_b32_e32 v6, v0
	v_mov_b32_e32 v7, v0
	v_mov_b32_e32 v8, v0
	v_mov_b32_e32 v9, v0
	v_mov_b32_e32 v10, v0
	v_mov_b32_e32 v11, v0
	v_mov_b32_e32 v12, v0
	v_mov_b32_e32 v13, v0
	v_mov_b32_e32 v14, v0
	v_mov_b32_e32 v15, v0
	v_mov_b32_e32 v16, v0
	v_mov_b32_e32 v17, v0
	v_mov_b32_e32 v18, v0
	v_mov_b32_e32 v19, v0
	v_mov_b32_e32 v20, v0
	v_mov_b32_e32 v21, v0
	v_mov_b32_e32 v22, v0
	v_mov_b32_e32 v23, v0
	v_mov_b32_e32 v24, v0
	v_mov_b32_e32 v25, v0
	v_mov_b32_e32 v26, v0
	v_mov_b32_e32 v27, v0
	v_mov_b32_e32 v28, v0
	v_mov_b32_e32 v29, v0
	v_mov_b32_e32 v30, v0
	v_mov_b32_e32 v31, v0
	v_mov_b32_e32 v32, v0
	v_mov_b32_e32 v33, v0
	v_mov_b32_e32 v34, v0
	v_mov_b32_e32 v35, v0
	v_mov_b32_e32 v36, v0
	v_mov_b32_e32 v37, v0
	v_mov_b32_e32 v38, v0
	v_mov_b32_e32 v39, v0
	v_mov_b32_e32 v40, v0
	v_mov_b32_e32 v41, v0
	v_mov_b32_e32 v42, v0
	v_mov_b32_e32 v43, v0
	v_mov_b32_e32 v44, v0
	v_mov_b32_e32 v45, v0
	v_mov_b32_e32 v46, v0
	v_mov_b32_e32 v47, v0
	v_mov_b32_e32 v48, v0
	v_mov_b32_e32 v49, v0
	v_mov_b32_e32 v50, v0
	v_mov_b32_e32 v51, v0
	v_mov_b32_e32 v52, v0
	v_mov_b32_e32 v53, v0
	v_mov_b32_e32 v54, v0
	v_mov_b32_e32 v55, v0
	v_mov_b32_e32 v56, v0
	v_mov_b32_e32 v57, v0
	v_mov_b32_e32 v58, v0
	v_mov_b32_e32 v59, v0
	v_mov_b32_e32 v60, v0
	v_mov_b32_e32 v61, v0
	v_mov_b32_e32 v62, v0
	v_mov_b32_e32 v63, v0
	v_mov_b32_e32 v64, v0
	v_mov_b32_e32 v65, v0
	v_mov_b32_e32 v66, v0
	v_mov_b32_e32 v67, v0
	v_mov_b32_e32 v70, v0
	v_mov_b32_e32 v71, v0
	v_mov_b32_e32 v72, v0
	v_mov_b32_e32 v73, v0
	v_mov_b32_e32 v74, v0
	v_mov_b32_e32 v75, v0
	v_mov_b32_e32 v76, v0
	v_mov_b32_e32 v77, v0
	v_mov_b32_e32 v78, v0
	v_mov_b32_e32 v79, v0
	v_mov_b32_e32 v80, v0
	v_mov_b32_e32 v81, v0
	v_mov_b32_e32 v82, v0
	v_mov_b32_e32 v83, v0
	v_mov_b32_e32 v84, v0
	v_mov_b32_e32 v85, v0
	v_mov_b32_e32 v86, v0
	v_mov_b32_e32 v87, v0
	v_mov_b32_e32 v88, v0
	v_mov_b32_e32 v89, v0
	v_mov_b32_e32 v90, v0
	v_mov_b32_e32 v91, v0
	v_mov_b32_e32 v92, v0
	v_mov_b32_e32 v93, v0
	v_mov_b32_e32 v94, v0
	v_mov_b32_e32 v95, v0
	v_mov_b32_e32 v96, v0
	v_mov_b32_e32 v97, v0
	v_mov_b32_e32 v98, v0
	v_mov_b32_e32 v99, v0
	v_mov_b32_e32 v100, v0
	v_mov_b32_e32 v101, v0
	v_mov_b32_e32 v102, v0
	v_mov_b32_e32 v103, v0
	v_mov_b32_e32 v104, v0
	v_mov_b32_e32 v105, v0
	v_mov_b32_e32 v106, v0
	v_mov_b32_e32 v107, v0
	v_mov_b32_e32 v108, v0
	v_mov_b32_e32 v109, v0
	v_mov_b32_e32 v110, v0
	v_mov_b32_e32 v111, v0
	v_mov_b32_e32 v112, v0
	v_mov_b32_e32 v113, v0
	v_mov_b32_e32 v114, v0
	v_mov_b32_e32 v115, v0
	v_mov_b32_e32 v116, v0
	v_mov_b32_e32 v117, v0
	v_mov_b32_e32 v118, v0
	v_mov_b32_e32 v119, v0
	v_mov_b32_e32 v120, v0
	v_mov_b32_e32 v121, v0
	v_mov_b32_e32 v122, v0
	v_mov_b32_e32 v123, v0
	v_mov_b32_e32 v124, v0
	v_mov_b32_e32 v125, v0
	v_mov_b32_e32 v126, v0
	v_mov_b32_e32 v127, v0
	v_mov_b32_e32 v128, v0
	v_mov_b32_e32 v129, v0
	s_waitcnt vmcnt(0)
	s_and_b64 s[0:1], s[56:57], s[8:9]
	s_andn2_b64 vcc, exec, s[0:1]
	s_cbranch_vccnz .LBB0_177
	s_barrier
	s_branch .LBB0_177

; #define STAGE(P_, BASE, br, kt) do { const u16* _gb = (BASE) + (long)(br) * K + (long)(kt) * BK; \
;     _Pragma("unroll") for (int _i = 0; _i < 2; ++_i) { \
;       __builtin_amdgcn_global_load_lds((const unsigned*)(_gb + (long)_i * 64 * K + lane_off), \
;         (unsigned*)((char*)(P_) + lds_wbase + _i * 8192), 16, 0, 0); } } while (0)
; #define WAIT_V(n) asm volatile("s_waitcnt vmcnt(" #n ")" ::: "memory")
; #define BAR __builtin_amdgcn_s_barrier()
; template <int PRE> ...
;     ...
;   const int wid = wvi, lane = tid & 63, wr = wid >> 2, wc = wid & 3, fr = lane & 15, fq = lane >> 4;
;   bf16x8 At[4][2], B0[2][2], B1[2][2];
;   const int nt = K / BK;
;   const unsigned lds_wbase = wid * 1024;
;   unsigned lane_off;
;   { int _r, _c; stage_rc(tid * 16, _r, _c); lane_off = (unsigned)(_r * K + _c); }
;     ...
;   if (PRE == 2) {
;     STAGE(SB(0, 0), Bt, bcol, 0); STAGE(SA(0, 0), A, brow, 0);
;     STAGE(SB(0, 1), Bt, bcol + HALF, 0); STAGE(SA(0, 1), A, brow + HALF, 0);
;     if (wr == 1) BAR;
;     WAIT_V(4); BAR;
;     STAGE(SB(1, 0), Bt, bcol, 1); STAGE(SA(1, 0), A, brow, 1); STAGE(SB(1, 1), Bt, bcol + HALF, 1);
;     WAIT_V(6); BAR;
;     return;
;   }
;     ...
; #pragma unroll
;     for (int a = 0; a < 2; ++a)
; #pragma unroll
;       for (int b = 0; b < 2; ++b)
; #pragma unroll
;         for (int m = 0; m < 4; ++m)
; #pragma unroll
;           for (int n = 0; n < 2; ++n) acc[a][b][m][n] = f32x4{0.f, 0.f, 0.f, 0.f};
.LBB0_451:
	s_mov_b64 s[2:3], 0x80
	s_add_i32 s24, s14, 0x18000
	v_lshl_add_u64 v[10:11], v[0:1], 0, s[2:3]
	s_mov_b32 m0, s24
	s_mov_b64 s[4:5], 0x40080
	s_add_i32 s25, s14, 0x1a000
	s_waitcnt vmcnt(4)
	s_barrier
	global_load_lds_dwordx4 v[10:11], off
	v_lshl_add_u64 v[0:1], v[0:1], 0, s[4:5]
	s_mov_b32 m0, s25
	s_add_i32 s26, s14, 0x8000
	global_load_lds_dwordx4 v[0:1], off
	v_lshl_add_u64 v[0:1], v[2:3], 0, s[2:3]
	s_mov_b32 m0, s26
	s_add_i32 s27, s14, 0xa000
	global_load_lds_dwordx4 v[0:1], off
	v_lshl_add_u64 v[0:1], v[2:3], 0, s[4:5]
	s_mov_b32 m0, s27
	s_add_i32 s28, s14, 0x1c000
	global_load_lds_dwordx4 v[0:1], off
	v_lshl_add_u64 v[0:1], v[144:145], 1, s[0:1]
	s_mov_b64 s[0:1], 0x80080
	v_lshl_add_u64 v[2:3], v[0:1], 0, s[0:1]
	s_mov_b32 m0, s28
	s_mov_b64 s[0:1], 0xc0080
	s_add_i32 s29, s14, 0x1e000
	global_load_lds_dwordx4 v[2:3], off
	v_lshl_add_u64 v[0:1], v[0:1], 0, s[0:1]
	s_mov_b32 m0, s29
	v_lshlrev_b32_e32 v3, 2, v8
	global_load_lds_dwordx4 v[0:1], off
	v_and_b32_e32 v0, 15, v8
	v_and_b32_e32 v1, 48, v8
	v_lshlrev_b32_e32 v2, 6, v0
	v_and_b32_e32 v3, 32, v3
	v_readlane_b32 s0, v246, 52
	v_bitop3_b32 v139, v2, v3, v1 bitop3:0x36
	v_and_b32_e32 v138, 63, v8
	v_or_b32_e32 v2, s0, v0
	v_lshlrev_b32_e32 v3, 6, v2
	v_lshlrev_b32_e32 v2, 2, v2
	v_and_b32_e32 v3, 0x3c0, v3
	v_and_b32_e32 v2, 32, v2
	v_readlane_b32 s0, v246, 51
	v_bitop3_b32 v2, v3, v2, v1 bitop3:0x36
	s_waitcnt vmcnt(6)
	s_mov_b32 s31, s13
	v_or_b32_e32 v3, s0, v0
	v_lshlrev_b32_e32 v8, 6, v3
	v_lshlrev_b32_e32 v3, 2, v3
	v_and_b32_e32 v8, 0x3c0, v8
	v_and_b32_e32 v3, 32, v3
	v_readlane_b32 s0, v246, 53
	v_bitop3_b32 v3, v8, v3, v1 bitop3:0x36
	s_barrier
	v_or_b32_e32 v8, s0, v0
	v_lshlrev_b32_e32 v9, 6, v8
	v_lshlrev_b32_e32 v8, 2, v8
	v_readlane_b32 s0, v246, 54
	v_and_b32_e32 v9, 0x3c0, v9
	v_and_b32_e32 v8, 32, v8
	v_or_b32_e32 v0, s0, v0
	v_bitop3_b32 v8, v9, v8, v1 bitop3:0x36
	v_lshlrev_b32_e32 v9, 6, v0
	v_lshlrev_b32_e32 v0, 2, v0
	v_and_b32_e32 v9, 0x3c0, v9
	v_and_b32_e32 v0, 32, v0
	v_bitop3_b32 v0, v9, v0, v1 bitop3:0x36
	v_lshlrev_b32_e32 v1, 14, v4
	v_and_b32_e32 v1, 0xffff8000, v1
	v_lshl_add_u32 v1, v5, 11, v1
	v_or_b32_e32 v1, v1, v6
	v_readlane_b32 s0, v244, 23
	v_add_u32_sdwa v144, v1, sext(v7) dst_sel:DWORD dst_unused:UNUSED_PAD src0_sel:DWORD src1_sel:WORD_0
	v_readlane_b32 s1, v244, 24
	s_nop 1
	v_lshl_add_u64 v[132:133], v[144:145], 1, s[0:1]
	v_readlane_b32 s0, v244, 12
	s_nop 1
	v_add_u32_e32 v140, s0, v2
	v_readlane_b32 s0, v244, 13
	s_nop 1
	v_add_u32_e32 v141, s0, v3
	v_readlane_b32 s0, v244, 14
	s_nop 1
	v_add_u32_e32 v142, s0, v8
	v_readlane_b32 s0, v244, 15
	s_nop 1
	v_add_u32_e32 v143, s0, v0
	v_mov_b32_e32 v0, 0
	v_mov_b32_e32 v1, v0
	v_mov_b32_e32 v2, v0
	v_mov_b32_e32 v3, v0
	v_mov_b32_e32 v4, v0
	v_mov_b32_e32 v5, v0
	v_mov_b32_e32 v6, v0
	v_mov_b32_e32 v7, v0
	v_mov_b32_e32 v8, v0
	v_mov_b32_e32 v9, v0
	v_mov_b32_e32 v10, v0
	v_mov_b32_e32 v11, v0
	v_mov_b32_e32 v12, v0
	v_mov_b32_e32 v13, v0
	v_mov_b32_e32 v14, v0
	v_mov_b32_e32 v15, v0
	v_mov_b32_e32 v16, v0
	v_mov_b32_e32 v17, v0
	v_mov_b32_e32 v18, v0
	v_mov_b32_e32 v19, v0
	v_mov_b32_e32 v20, v0
	v_mov_b32_e32 v21, v0
	v_mov_b32_e32 v22, v0
	v_mov_b32_e32 v23, v0
	v_mov_b32_e32 v24, v0
	v_mov_b32_e32 v25, v0
	v_mov_b32_e32 v26, v0
	v_mov_b32_e32 v27, v0
	v_mov_b32_e32 v28, v0
	v_mov_b32_e32 v29, v0
	v_mov_b32_e32 v30, v0
	v_mov_b32_e32 v31, v0
	v_mov_b32_e32 v32, v0
	v_mov_b32_e32 v33, v0
	v_mov_b32_e32 v34, v0
	v_mov_b32_e32 v35, v0
	v_mov_b32_e32 v36, v0
	v_mov_b32_e32 v37, v0
	v_mov_b32_e32 v38, v0
	v_mov_b32_e32 v39, v0
	v_mov_b32_e32 v40, v0
	v_mov_b32_e32 v41, v0
	v_mov_b32_e32 v42, v0
	v_mov_b32_e32 v43, v0
	v_mov_b32_e32 v44, v0
	v_mov_b32_e32 v45, v0
	v_mov_b32_e32 v46, v0
	v_mov_b32_e32 v47, v0
	v_mov_b32_e32 v48, v0
	v_mov_b32_e32 v49, v0
	v_mov_b32_e32 v50, v0
	v_mov_b32_e32 v51, v0
	v_mov_b32_e32 v52, v0
	v_mov_b32_e32 v53, v0
	v_mov_b32_e32 v54, v0
	v_mov_b32_e32 v55, v0
	v_mov_b32_e32 v56, v0
	v_mov_b32_e32 v57, v0
	v_mov_b32_e32 v58, v0
	v_mov_b32_e32 v59, v0
	v_mov_b32_e32 v60, v0
	v_mov_b32_e32 v61, v0
	v_mov_b32_e32 v62, v0
	v_mov_b32_e32 v63, v0
	v_mov_b32_e32 v64, v0
	v_mov_b32_e32 v65, v0
	v_mov_b32_e32 v66, v0
	v_mov_b32_e32 v67, v0
	v_mov_b32_e32 v70, v0
	v_mov_b32_e32 v71, v0
	v_mov_b32_e32 v72, v0
	v_mov_b32_e32 v73, v0
	v_mov_b32_e32 v74, v0
	v_mov_b32_e32 v75, v0
	v_mov_b32_e32 v76, v0
	v_mov_b32_e32 v77, v0
	v_mov_b32_e32 v78, v0
	v_mov_b32_e32 v79, v0
	v_mov_b32_e32 v80, v0
	v_mov_b32_e32 v81, v0
	v_mov_b32_e32 v82, v0
	v_mov_b32_e32 v83, v0
	v_mov_b32_e32 v84, v0
	v_mov_b32_e32 v85, v0
	v_mov_b32_e32 v86, v0
	v_mov_b32_e32 v87, v0
	v_mov_b32_e32 v88, v0
	v_mov_b32_e32 v89, v0
	v_mov_b32_e32 v90, v0
	v_mov_b32_e32 v91, v0
	v_mov_b32_e32 v92, v0
	v_mov_b32_e32 v93, v0
	v_mov_b32_e32 v94, v0
	v_mov_b32_e32 v95, v0
	v_mov_b32_e32 v96, v0
	v_mov_b32_e32 v97, v0
	v_mov_b32_e32 v98, v0
	v_mov_b32_e32 v99, v0
	v_mov_b32_e32 v100, v0
	v_mov_b32_e32 v101, v0
	v_mov_b32_e32 v102, v0
	v_mov_b32_e32 v103, v0
	v_mov_b32_e32 v104, v0
	v_mov_b32_e32 v105, v0
	v_mov_b32_e32 v106, v0
	v_mov_b32_e32 v107, v0
	v_mov_b32_e32 v108, v0
	v_mov_b32_e32 v109, v0
	v_mov_b32_e32 v110, v0
	v_mov_b32_e32 v111, v0
	v_mov_b32_e32 v112, v0
	v_mov_b32_e32 v113, v0
	v_mov_b32_e32 v114, v0
	v_mov_b32_e32 v115, v0
	v_mov_b32_e32 v116, v0
	v_mov_b32_e32 v117, v0
	v_mov_b32_e32 v118, v0
	v_mov_b32_e32 v119, v0
	v_mov_b32_e32 v120, v0
	v_mov_b32_e32 v121, v0
	v_mov_b32_e32 v122, v0
	v_mov_b32_e32 v123, v0
	v_mov_b32_e32 v124, v0
	v_mov_b32_e32 v125, v0
	v_mov_b32_e32 v126, v0
	v_mov_b32_e32 v127, v0
	v_mov_b32_e32 v128, v0
	v_mov_b32_e32 v129, v0
	s_branch .LBB0_453

;     ...
;   for (int u = vb; u < nunits; u += ustride) {
;     const int tm = u % nM, tn = u / nM + ((tn_skip >= 0 && u / nM >= tn_skip) ? 1 : 0);
;     const int brow = tn * 256, bcol = tm * 256;
;     const int un = u + ustride;
;     const bool has_next = un < nunits;
;     const int tn_n = un / nM + ((tn_skip >= 0 && un / nM >= tn_skip) ? 1 : 0);
;     const int brow_n = has_next ? tn_n * 256 : brow, bcol_n = has_next ? (un % nM) * 256 : bcol;
.LBB0_455:
	s_ashr_i32 s35, s0, 6
	s_lshl_b32 s0, s35, 8
	s_lshl_b32 s1, s1, 8
	s_and_b64 s[2:3], s[10:11], exec
	s_cselect_b32 s36, s1, s0
	s_ashr_i32 s1, s0, 31
	s_lshl_b64 s[2:3], s[0:1], 12
	s_or_b32 s37, s0, 0x80
	s_or_b32 s38, s9, 0x80
	s_or_b32 s39, s8, 0x80
	s_or_b32 s40, s36, 0x80
	v_lshl_add_u64 v[134:135], v[132:133], 0, s[2:3]
	s_mov_b32 s1, 0
	s_waitcnt vmcnt(0)

;     ...
; #pragma unroll
;     for (int a = 0; a < 2; ++a)
; #pragma unroll
;       for (int b = 0; b < 2; ++b)
; #pragma unroll
;         for (int m = 0; m < 4; ++m)
; #pragma unroll
;           for (int n = 0; n < 2; ++n) acc[a][b][m][n] = f32x4{0.f, 0.f, 0.f, 0.f};
;     ...
;     asm volatile("s_waitcnt vmcnt(0)" ::: "memory");
;     if (has_next && wr == 1) __builtin_amdgcn_s_barrier();
.LBB0_543:
	s_nop 1
	v_mov_b32_e32 v0, 0
	v_mov_b32_e32 v1, v0
	v_mov_b32_e32 v2, v0
	v_mov_b32_e32 v3, v0
	v_mov_b32_e32 v4, v0
	v_mov_b32_e32 v5, v0
	v_mov_b32_e32 v6, v0
	v_mov_b32_e32 v7, v0
	v_mov_b32_e32 v8, v0
	v_mov_b32_e32 v9, v0
	v_mov_b32_e32 v10, v0
	v_mov_b32_e32 v11, v0
	v_mov_b32_e32 v12, v0
	v_mov_b32_e32 v13, v0
	v_mov_b32_e32 v14, v0
	v_mov_b32_e32 v15, v0
	v_mov_b32_e32 v16, v0
	v_mov_b32_e32 v17, v0
	v_mov_b32_e32 v18, v0
	v_mov_b32_e32 v19, v0
	v_mov_b32_e32 v20, v0
	v_mov_b32_e32 v21, v0
	v_mov_b32_e32 v22, v0
	v_mov_b32_e32 v23, v0
	v_mov_b32_e32 v24, v0
	v_mov_b32_e32 v25, v0
	v_mov_b32_e32 v26, v0
	v_mov_b32_e32 v27, v0
	v_mov_b32_e32 v28, v0
	v_mov_b32_e32 v29, v0
	v_mov_b32_e32 v30, v0
	v_mov_b32_e32 v31, v0
	v_mov_b32_e32 v32, v0
	v_mov_b32_e32 v33, v0
	v_mov_b32_e32 v34, v0
	v_mov_b32_e32 v35, v0
	v_mov_b32_e32 v36, v0
	v_mov_b32_e32 v37, v0
	v_mov_b32_e32 v38, v0
	v_mov_b32_e32 v39, v0
	v_mov_b32_e32 v40, v0
	v_mov_b32_e32 v41, v0
	v_mov_b32_e32 v42, v0
	v_mov_b32_e32 v43, v0
	v_mov_b32_e32 v44, v0
	v_mov_b32_e32 v45, v0
	v_mov_b32_e32 v46, v0
	v_mov_b32_e32 v47, v0
	v_mov_b32_e32 v48, v0
	v_mov_b32_e32 v49, v0
	v_mov_b32_e32 v50, v0
	v_mov_b32_e32 v51, v0
	v_mov_b32_e32 v52, v0
	v_mov_b32_e32 v53, v0
	v_mov_b32_e32 v54, v0
	v_mov_b32_e32 v55, v0
	v_mov_b32_e32 v56, v0
	v_mov_b32_e32 v57, v0
	v_mov_b32_e32 v58, v0
	v_mov_b32_e32 v59, v0
	v_mov_b32_e32 v60, v0
	v_mov_b32_e32 v61, v0
	v_mov_b32_e32 v62, v0
	v_mov_b32_e32 v63, v0
	v_mov_b32_e32 v64, v0
	v_mov_b32_e32 v65, v0
	v_mov_b32_e32 v66, v0
	v_mov_b32_e32 v67, v0
	v_mov_b32_e32 v70, v0
	v_mov_b32_e32 v71, v0
	v_mov_b32_e32 v72, v0
	v_mov_b32_e32 v73, v0
	v_mov_b32_e32 v74, v0
	v_mov_b32_e32 v75, v0
	v_mov_b32_e32 v76, v0
	v_mov_b32_e32 v77, v0
	v_mov_b32_e32 v78, v0
	v_mov_b32_e32 v79, v0
	v_mov_b32_e32 v80, v0
	v_mov_b32_e32 v81, v0
	v_mov_b32_e32 v82, v0
	v_mov_b32_e32 v83, v0
	v_mov_b32_e32 v84, v0
	v_mov_b32_e32 v85, v0
	v_mov_b32_e32 v86, v0
	v_mov_b32_e32 v87, v0
	v_mov_b32_e32 v88, v0
	v_mov_b32_e32 v89, v0
	v_mov_b32_e32 v90, v0
	v_mov_b32_e32 v91, v0
	v_mov_b32_e32 v92, v0
	v_mov_b32_e32 v93, v0
	v_mov_b32_e32 v94, v0
	v_mov_b32_e32 v95, v0
	v_mov_b32_e32 v96, v0
	v_mov_b32_e32 v97, v0
	v_mov_b32_e32 v98, v0
	v_mov_b32_e32 v99, v0
	v_mov_b32_e32 v100, v0
	v_mov_b32_e32 v101, v0
	v_mov_b32_e32 v102, v0
	v_mov_b32_e32 v103, v0
	v_mov_b32_e32 v104, v0
	v_mov_b32_e32 v105, v0
	v_mov_b32_e32 v106, v0
	v_mov_b32_e32 v107, v0
	v_mov_b32_e32 v108, v0
	v_mov_b32_e32 v109, v0
	v_mov_b32_e32 v110, v0
	v_mov_b32_e32 v111, v0
	v_mov_b32_e32 v112, v0
	v_mov_b32_e32 v113, v0
	v_mov_b32_e32 v114, v0
	v_mov_b32_e32 v115, v0
	v_mov_b32_e32 v116, v0
	v_mov_b32_e32 v117, v0
	v_mov_b32_e32 v118, v0
	v_mov_b32_e32 v119, v0
	v_mov_b32_e32 v120, v0
	v_mov_b32_e32 v121, v0
	v_mov_b32_e32 v122, v0
	v_mov_b32_e32 v123, v0
	v_mov_b32_e32 v124, v0
	v_mov_b32_e32 v125, v0
	v_mov_b32_e32 v126, v0
	v_mov_b32_e32 v127, v0
	v_mov_b32_e32 v128, v0
	v_mov_b32_e32 v129, v0
	s_waitcnt vmcnt(0)
	s_and_b64 s[0:1], s[56:57], s[10:11]
	s_andn2_b64 vcc, exec, s[0:1]
	s_cbranch_vccnz .LBB0_452
	s_barrier
	s_branch .LBB0_452

; #define STAGE(P_, BASE, br, kt) do { const u16* _gb = (BASE) + (long)(br) * K + (long)(kt) * BK; \
;     _Pragma("unroll") for (int _i = 0; _i < 2; ++_i) { \
;       __builtin_amdgcn_global_load_lds((const unsigned*)(_gb + (long)_i * 64 * K + lane_off), \
;         (unsigned*)((char*)(P_) + lds_wbase + _i * 8192), 16, 0, 0); } } while (0)
; #define WAIT_V(n) asm volatile("s_waitcnt vmcnt(" #n ")" ::: "memory")
; #define BAR __builtin_amdgcn_s_barrier()
; template <int PRE> ...
;     ...
;   const int wid = wvi, lane = tid & 63, wr = wid >> 2, wc = wid & 3, fr = lane & 15, fq = lane >> 4;
;   bf16x8 At[4][2], B0[2][2], B1[2][2];
;   const int nt = K / BK;
;   const unsigned lds_wbase = wid * 1024;
;   unsigned lane_off;
;   { int _r, _c; stage_rc(tid * 16, _r, _c); lane_off = (unsigned)(_r * K + _c); }
;     ...
;   if (PRE == 2) {
;     STAGE(SB(0, 0), Bt, bcol, 0); STAGE(SA(0, 0), A, brow, 0);
;     STAGE(SB(0, 1), Bt, bcol + HALF, 0); STAGE(SA(0, 1), A, brow + HALF, 0);
;     if (wr == 1) BAR;
;     WAIT_V(4); BAR;
;     STAGE(SB(1, 0), Bt, bcol, 1); STAGE(SA(1, 0), A, brow, 1); STAGE(SB(1, 1), Bt, bcol + HALF, 1);
;     WAIT_V(6); BAR;
;     return;
;   }
;     ...
; #pragma unroll
;     for (int a = 0; a < 2; ++a)
; #pragma unroll
;       for (int b = 0; b < 2; ++b)
; #pragma unroll
;         for (int m = 0; m < 4; ++m)
; #pragma unroll
;           for (int n = 0; n < 2; ++n) acc[a][b][m][n] = f32x4{0.f, 0.f, 0.f, 0.f};
.LBB0_803:
	s_mov_b64 s[4:5], 0x80
	s_add_i32 s20, s10, 0x18000
	v_lshl_add_u64 v[12:13], v[0:1], 0, s[4:5]
	s_mov_b32 m0, s20
	s_mov_b64 s[2:3], 0x80080
	s_add_i32 s21, s10, 0x1a000
	s_waitcnt vmcnt(4)
	s_barrier
	global_load_lds_dwordx4 v[12:13], off
	v_lshl_add_u64 v[0:1], v[0:1], 0, s[2:3]
	s_mov_b32 m0, s21
	s_add_i32 s22, s10, 0x8000
	global_load_lds_dwordx4 v[0:1], off
	v_lshl_add_u64 v[0:1], v[2:3], 0, s[4:5]
	s_mov_b32 m0, s22
	s_add_i32 s23, s10, 0xa000
	global_load_lds_dwordx4 v[0:1], off
	v_lshl_add_u64 v[0:1], v[2:3], 0, s[2:3]
	s_mov_b32 m0, s23
	s_add_i32 s24, s10, 0x1c000
	global_load_lds_dwordx4 v[0:1], off
	v_lshl_add_u64 v[0:1], v[4:5], 0, s[4:5]
	s_mov_b32 m0, s24
	s_add_i32 s25, s10, 0x1e000
	global_load_lds_dwordx4 v[0:1], off
	v_lshl_add_u64 v[0:1], v[4:5], 0, s[2:3]
	s_mov_b32 m0, s25
	v_lshlrev_b32_e32 v3, 2, v9
	global_load_lds_dwordx4 v[0:1], off
	v_and_b32_e32 v0, 15, v9
	v_and_b32_e32 v1, 48, v9
	v_lshlrev_b32_e32 v2, 6, v0
	v_and_b32_e32 v3, 32, v3
	v_readlane_b32 s0, v246, 52
	v_bitop3_b32 v147, v2, v3, v1 bitop3:0x36
	v_readlane_b32 s2, v244, 30
	v_or_b32_e32 v2, s0, v0
	v_lshlrev_b32_e32 v3, 6, v2
	v_lshlrev_b32_e32 v2, 2, v2
	v_and_b32_e32 v3, 0x3c0, v3
	v_and_b32_e32 v2, 32, v2
	v_readlane_b32 s0, v246, 51
	v_bitop3_b32 v2, v3, v2, v1 bitop3:0x36
	v_readlane_b32 s3, v244, 31
	v_or_b32_e32 v3, s0, v0
	v_lshlrev_b32_e32 v4, 6, v3
	v_lshlrev_b32_e32 v3, 2, v3
	v_and_b32_e32 v4, 0x3c0, v4
	v_and_b32_e32 v3, 32, v3
	v_readlane_b32 s0, v246, 53
	v_bitop3_b32 v3, v4, v3, v1 bitop3:0x36
	s_waitcnt vmcnt(6)
	v_and_b32_e32 v146, 63, v9
	v_or_b32_e32 v4, s0, v0
	v_lshlrev_b32_e32 v5, 6, v4
	v_lshlrev_b32_e32 v4, 2, v4
	v_readlane_b32 s0, v246, 54
	v_and_b32_e32 v5, 0x3c0, v5
	v_and_b32_e32 v4, 32, v4
	v_or_b32_e32 v0, s0, v0
	v_bitop3_b32 v4, v5, v4, v1 bitop3:0x36
	v_lshlrev_b32_e32 v5, 6, v0
	v_lshlrev_b32_e32 v0, 2, v0
	v_and_b32_e32 v5, 0x3c0, v5
	v_and_b32_e32 v0, 32, v0
	v_bitop3_b32 v0, v5, v0, v1 bitop3:0x36
	v_lshlrev_b32_e32 v1, 15, v6
	v_and_b32_e32 v1, 0xffff0000, v1
	v_lshl_add_u32 v1, v7, 12, v1
	v_or_b32_e32 v1, v1, v8
	v_add_u32_sdwa v144, v1, sext(v10) dst_sel:DWORD dst_unused:UNUSED_PAD src0_sel:DWORD src1_sel:WORD_0
	v_readlane_b32 s0, v244, 12
	v_lshl_add_u64 v[130:131], v[144:145], 1, s[2:3]
	s_barrier
	v_add_u32_e32 v144, s0, v2
	v_readlane_b32 s0, v244, 13
	s_nop 1
	v_add_u32_e32 v148, s0, v3
	v_readlane_b32 s0, v244, 14
	s_nop 1
	v_add_u32_e32 v149, s0, v4
	v_readlane_b32 s0, v244, 15
	s_nop 1
	v_add_u32_e32 v150, s0, v0
	v_mov_b32_e32 v0, 0
	v_mov_b32_e32 v1, v0
	v_mov_b32_e32 v2, v0
	v_mov_b32_e32 v3, v0
	v_mov_b32_e32 v4, v0
	v_mov_b32_e32 v5, v0
	v_mov_b32_e32 v6, v0
	v_mov_b32_e32 v7, v0
	v_mov_b32_e32 v8, v0
	v_mov_b32_e32 v9, v0
	v_mov_b32_e32 v10, v0
	v_mov_b32_e32 v11, v0
	v_mov_b32_e32 v12, v0
	v_mov_b32_e32 v13, v0
	v_mov_b32_e32 v14, v0
	v_mov_b32_e32 v15, v0
	v_mov_b32_e32 v16, v0
	v_mov_b32_e32 v17, v0
	v_mov_b32_e32 v18, v0
	v_mov_b32_e32 v19, v0
	v_mov_b32_e32 v20, v0
	v_mov_b32_e32 v21, v0
	v_mov_b32_e32 v22, v0
	v_mov_b32_e32 v23, v0
	v_mov_b32_e32 v24, v0
	v_mov_b32_e32 v25, v0
	v_mov_b32_e32 v26, v0
	v_mov_b32_e32 v27, v0
	v_mov_b32_e32 v28, v0
	v_mov_b32_e32 v29, v0
	v_mov_b32_e32 v30, v0
	v_mov_b32_e32 v31, v0
	v_mov_b32_e32 v32, v0
	v_mov_b32_e32 v33, v0
	v_mov_b32_e32 v34, v0
	v_mov_b32_e32 v35, v0
	v_mov_b32_e32 v36, v0
	v_mov_b32_e32 v37, v0
	v_mov_b32_e32 v38, v0
	v_mov_b32_e32 v39, v0
	v_mov_b32_e32 v40, v0
	v_mov_b32_e32 v41, v0
	v_mov_b32_e32 v42, v0
	v_mov_b32_e32 v43, v0
	v_mov_b32_e32 v44, v0
	v_mov_b32_e32 v45, v0
	v_mov_b32_e32 v46, v0
	v_mov_b32_e32 v47, v0
	v_mov_b32_e32 v48, v0
	v_mov_b32_e32 v49, v0
	v_mov_b32_e32 v50, v0
	v_mov_b32_e32 v51, v0
	v_mov_b32_e32 v52, v0
	v_mov_b32_e32 v53, v0
	v_mov_b32_e32 v54, v0
	v_mov_b32_e32 v55, v0
	v_mov_b32_e32 v56, v0
	v_mov_b32_e32 v57, v0
	v_mov_b32_e32 v58, v0
	v_mov_b32_e32 v59, v0
	v_mov_b32_e32 v60, v0
	v_mov_b32_e32 v61, v0
	v_mov_b32_e32 v62, v0
	v_mov_b32_e32 v63, v0
	v_mov_b32_e32 v64, v0
	v_mov_b32_e32 v65, v0
	v_mov_b32_e32 v66, v0
	v_mov_b32_e32 v67, v0
	v_mov_b32_e32 v68, v0
	v_mov_b32_e32 v69, v0
	v_mov_b32_e32 v70, v0
	v_mov_b32_e32 v71, v0
	v_mov_b32_e32 v72, v0
	v_mov_b32_e32 v73, v0
	v_mov_b32_e32 v74, v0
	v_mov_b32_e32 v75, v0
	v_mov_b32_e32 v76, v0
	v_mov_b32_e32 v77, v0
	v_mov_b32_e32 v78, v0
	v_mov_b32_e32 v79, v0
	v_mov_b32_e32 v80, v0
	v_mov_b32_e32 v81, v0
	v_mov_b32_e32 v82, v0
	v_mov_b32_e32 v83, v0
	v_mov_b32_e32 v84, v0
	v_mov_b32_e32 v85, v0
	v_mov_b32_e32 v86, v0
	v_mov_b32_e32 v87, v0
	v_mov_b32_e32 v88, v0
	v_mov_b32_e32 v89, v0
	v_mov_b32_e32 v90, v0
	v_mov_b32_e32 v91, v0
	v_mov_b32_e32 v92, v0
	v_mov_b32_e32 v93, v0
	v_mov_b32_e32 v94, v0
	v_mov_b32_e32 v95, v0
	v_mov_b32_e32 v96, v0
	v_mov_b32_e32 v97, v0
	v_mov_b32_e32 v98, v0
	v_mov_b32_e32 v99, v0
	v_mov_b32_e32 v100, v0
	v_mov_b32_e32 v101, v0
	v_mov_b32_e32 v102, v0
	v_mov_b32_e32 v103, v0
	v_mov_b32_e32 v104, v0
	v_mov_b32_e32 v105, v0
	v_mov_b32_e32 v106, v0
	v_mov_b32_e32 v107, v0
	v_mov_b32_e32 v108, v0
	v_mov_b32_e32 v109, v0
	v_mov_b32_e32 v110, v0
	v_mov_b32_e32 v111, v0
	v_mov_b32_e32 v112, v0
	v_mov_b32_e32 v113, v0
	v_mov_b32_e32 v114, v0
	v_mov_b32_e32 v115, v0
	v_mov_b32_e32 v116, v0
	v_mov_b32_e32 v117, v0
	v_mov_b32_e32 v118, v0
	v_mov_b32_e32 v119, v0
	v_mov_b32_e32 v120, v0
	v_mov_b32_e32 v121, v0
	v_mov_b32_e32 v122, v0
	v_mov_b32_e32 v123, v0
	v_mov_b32_e32 v124, v0
	v_mov_b32_e32 v125, v0
	v_mov_b32_e32 v126, v0
	v_mov_b32_e32 v127, v0
	s_branch .LBB0_805

;     ...
;   for (int u = vb; u < nunits; u += ustride) {
;     const int tm = u % nM, tn = u / nM + ((tn_skip >= 0 && u / nM >= tn_skip) ? 1 : 0);
;     const int brow = tn * 256, bcol = tm * 256;
;     const int un = u + ustride;
;     const bool has_next = un < nunits;
;     const int tn_n = un / nM + ((tn_skip >= 0 && un / nM >= tn_skip) ? 1 : 0);
;     const int brow_n = has_next ? tn_n * 256 : brow, bcol_n = has_next ? (un % nM) * 256 : bcol;
.LBB0_809:
	s_ashr_i32 s1, s0, 31
	s_lshl_b64 s[2:3], s[0:1], 13
	s_or_b32 s30, s0, 0x80
	s_or_b32 s31, s29, 0x80
	s_or_b32 s34, s27, 0x80
	s_or_b32 s35, s28, 0x80
	v_lshl_add_u64 v[132:133], v[130:131], 0, s[2:3]
	s_mov_b32 s1, 0
	s_waitcnt vmcnt(0)
	s_mov_b64 s[44:45], 0x80000

; __device__ __forceinline__ float bflo(unsigned u) { return __uint_as_float(u << 16); }
; __device__ __forceinline__ float bfhi(unsigned u) { return __uint_as_float(u & 0xffff0000u); }
; __device__ __forceinline__ float sigmoidf_(float x) { return __builtin_amdgcn_rcpf(1.f + __expf(-x)); }
; #define WIDE_STORE(BASE, LD, COFF, O) do { if ((m & 1) == 0) opend[n] = (O); \
;                 else *(uint4*)((BASE) + (size_t)tok * (LD) + (ncw - (COFF))) = swap_pair(opend[n], (O)); } while (0)
;     ...
;               const int nc = brow + ai * 128 + wr * 64 + m * 16 + fq * 4;
;               const int tok = bcol + bj * 128 + wc * 32 + n * 16 + fr;
;               const int ncw = brow + ai * 128 + wr * 64 + ((m & ~1) + (fq & 1)) * 16 + (fq & ~1) * 4;
;     ...
;               f32x4 v = acc[ai][bj][m][n];
;               if (MODE == 0) {
;                 if (tn == 52) {
;                   if (ai == 0) *(float4*)((float*)(ws + OFF_DTR) + (size_t)tok * 128 + (nc - 13312)) = make_float4(v[0], v[1], v[2], v[3]);
;                 } else {
;                   u16* dst; int ld, c0;
;                   if (tn < 16) { dst = (u16*)(ws + OFF_Z); ld = 4096; c0 = 0; }
;                   else if (tn < 40) { dst = (u16*)(ws + OFF_RA); ld = 6144; c0 = 4096; }
;                   else if (tn < 48) { dst = (u16*)(ws + OFF_Q); ld = 2048; c0 = 10240; }
;                   else if (tn < 50) { dst = (u16*)(ws + OFF_K); ld = 512; c0 = 12288; }
;                   else { dst = (u16*)(ws + OFF_V); ld = 512; c0 = 12800; }
;                   uint2 o; o.x = pk2(v[0], v[1]); o.y = pk2(v[2], v[3]);
;                   WIDE_STORE(dst, ld, c0, o);
;                 }
;               } else if (MODE == 1) {
;                 uint2 o; o.x = pk2(sigmoidf_(v[0]), sigmoidf_(v[1])); o.y = pk2(sigmoidf_(v[2]), sigmoidf_(v[3]));
;                 WIDE_STORE((u16*)outp, 4096, 0, o);
;               } else if (MODE == 2) {
;                 const u16* gate = (const u16*)outp;
;                 uint2 ga = *(const uint2*)(gate + (size_t)tok * 4096 + nc);
;                 uint2 p1; p1.x = pk2(v[0] * bflo(ga.x), v[1] * bfhi(ga.x)); p1.y = pk2(v[2] * bflo(ga.y), v[3] * bfhi(ga.y));
;                 *(uint2*)((u16*)(ws + OFF_YB) + (size_t)tok * DM + nc) = p1;
.LBB0_813:
	v_readlane_b32 s2, v243, 57
	v_readlane_b32 s3, v243, 58
	v_readlane_b32 s4, v244, 3
	v_readlane_b32 s5, v244, 4
	s_add_i32 s0, s0, s49
	v_and_b32_e32 v172, 15, v146
	v_or_b32_e32 v172, s54, v172
	v_or_b32_e32 v172, s27, v172
	v_lshrrev_b32_e32 v173, 2, v146
	v_and_b32_e32 v174, -4, v173
	v_add_u32_e32 v174, s0, v174
	v_and_b32_e32 v173, -8, v173
	v_and_b32_e32 v175, 16, v146
	v_add3_u32 v173, v173, v175, s0
	v_lshlrev_b32_e32 v175, 13, v172
	v_lshl_add_u32 v134, v174, 1, v175
	v_add_u32_e32 v135, 0x20000, v134
	v_add_u32_e32 v136, 0x100000, v134
	v_add_u32_e32 v137, 0x120000, v134
	v_lshlrev_b32_e32 v175, 12, v172
	v_lshl_add_u32 v138, v174, 1, v175
	v_add_u32_e32 v139, 0x10000, v138
	v_add_u32_e32 v140, 0x80000, v138
	v_add_u32_e32 v141, 0x90000, v138
	global_load_dwordx2 v[210:211], v134, s[2:3] offset:0
	global_load_dwordx2 v[212:213], v134, s[2:3] offset:32
	global_load_dwordx2 v[214:215], v134, s[2:3] offset:64
	global_load_dwordx2 v[216:217], v134, s[2:3] offset:96
	global_load_dwordx2 v[218:219], v135, s[2:3] offset:0
	global_load_dwordx2 v[220:221], v135, s[2:3] offset:32
	global_load_dwordx2 v[222:223], v135, s[2:3] offset:64
	global_load_dwordx2 v[224:225], v135, s[2:3] offset:96
	global_load_dwordx2 v[226:227], v136, s[2:3] offset:0
	global_load_dwordx2 v[228:229], v136, s[2:3] offset:32
	global_load_dwordx2 v[230:231], v136, s[2:3] offset:64
	global_load_dwordx2 v[232:233], v136, s[2:3] offset:96
	global_load_dwordx2 v[234:235], v137, s[2:3] offset:0
	global_load_dwordx2 v[236:237], v137, s[2:3] offset:32
	global_load_dwordx2 v[238:239], v137, s[2:3] offset:64
	global_load_dwordx2 v[240:241], v137, s[2:3] offset:96
	s_waitcnt vmcnt(15)
	v_lshlrev_b32_e32 v168, 16, v210
	v_and_b32_e32 v169, 0xffff0000, v210
	v_lshlrev_b32_e32 v170, 16, v211
	v_and_b32_e32 v171, 0xffff0000, v211
	v_pk_mul_f32 v[124:125], v[124:125], v[168:169]
	v_pk_mul_f32 v[126:127], v[126:127], v[170:171]
	global_load_dwordx2 v[210:211], v134, s[2:3] offset:256
	s_waitcnt vmcnt(15)
	v_lshlrev_b32_e32 v168, 16, v212
	v_and_b32_e32 v169, 0xffff0000, v212
	v_lshlrev_b32_e32 v170, 16, v213
	v_and_b32_e32 v171, 0xffff0000, v213
	v_pk_mul_f32 v[116:117], v[116:117], v[168:169]
	v_pk_mul_f32 v[118:119], v[118:119], v[170:171]
	global_load_dwordx2 v[212:213], v134, s[2:3] offset:288
	s_waitcnt vmcnt(15)
	v_lshlrev_b32_e32 v168, 16, v214
	v_and_b32_e32 v169, 0xffff0000, v214
	v_lshlrev_b32_e32 v170, 16, v215
	v_and_b32_e32 v171, 0xffff0000, v215
	v_pk_mul_f32 v[108:109], v[108:109], v[168:169]
	v_pk_mul_f32 v[110:111], v[110:111], v[170:171]
	global_load_dwordx2 v[214:215], v134, s[2:3] offset:320
	s_waitcnt vmcnt(15)
	v_lshlrev_b32_e32 v168, 16, v216
	v_and_b32_e32 v169, 0xffff0000, v216
	v_lshlrev_b32_e32 v170, 16, v217
	v_and_b32_e32 v171, 0xffff0000, v217
	v_pk_mul_f32 v[100:101], v[100:101], v[168:169]
	v_pk_mul_f32 v[102:103], v[102:103], v[170:171]
	global_load_dwordx2 v[216:217], v134, s[2:3] offset:352
	s_nop 0
	v_cvt_pk_bf16_f32 v124, v124, v125
	v_cvt_pk_bf16_f32 v125, v126, v127
	v_cvt_pk_bf16_f32 v116, v116, v117
	v_cvt_pk_bf16_f32 v117, v118, v119
	v_cvt_pk_bf16_f32 v108, v108, v109
	v_cvt_pk_bf16_f32 v109, v110, v111
	v_cvt_pk_bf16_f32 v100, v100, v101
	v_cvt_pk_bf16_f32 v101, v102, v103
	global_store_dwordx2 v138, v[124:125], s[4:5] offset:0
	global_store_dwordx2 v138, v[116:117], s[4:5] offset:32
	global_store_dwordx2 v138, v[108:109], s[4:5] offset:64
	global_store_dwordx2 v138, v[100:101], s[4:5] offset:96
	s_waitcnt vmcnt(19)
	v_lshlrev_b32_e32 v168, 16, v218
	v_and_b32_e32 v169, 0xffff0000, v218
	v_lshlrev_b32_e32 v170, 16, v219
	v_and_b32_e32 v171, 0xffff0000, v219
	v_pk_mul_f32 v[120:121], v[120:121], v[168:169]
	v_pk_mul_f32 v[122:123], v[122:123], v[170:171]
	global_load_dwordx2 v[218:219], v135, s[2:3] offset:256
	s_waitcnt vmcnt(19)
	v_lshlrev_b32_e32 v168, 16, v220
	v_and_b32_e32 v169, 0xffff0000, v220
	v_lshlrev_b32_e32 v170, 16, v221
	v_and_b32_e32 v171, 0xffff0000, v221
	v_pk_mul_f32 v[112:113], v[112:113], v[168:169]
	v_pk_mul_f32 v[114:115], v[114:115], v[170:171]
	global_load_dwordx2 v[220:221], v135, s[2:3] offset:288
	s_waitcnt vmcnt(19)
	v_lshlrev_b32_e32 v168, 16, v222
	v_and_b32_e32 v169, 0xffff0000, v222
	v_lshlrev_b32_e32 v170, 16, v223
	v_and_b32_e32 v171, 0xffff0000, v223
	v_pk_mul_f32 v[104:105], v[104:105], v[168:169]
	v_pk_mul_f32 v[106:107], v[106:107], v[170:171]
	global_load_dwordx2 v[222:223], v135, s[2:3] offset:320
	s_waitcnt vmcnt(19)
	v_lshlrev_b32_e32 v168, 16, v224
	v_and_b32_e32 v169, 0xffff0000, v224
	v_lshlrev_b32_e32 v170, 16, v225
	v_and_b32_e32 v171, 0xffff0000, v225
	v_pk_mul_f32 v[96:97], v[96:97], v[168:169]
	v_pk_mul_f32 v[98:99], v[98:99], v[170:171]
	global_load_dwordx2 v[224:225], v135, s[2:3] offset:352
	s_nop 0
	v_cvt_pk_bf16_f32 v120, v120, v121
	v_cvt_pk_bf16_f32 v121, v122, v123
	v_cvt_pk_bf16_f32 v112, v112, v113
	v_cvt_pk_bf16_f32 v113, v114, v115
	v_cvt_pk_bf16_f32 v104, v104, v105
	v_cvt_pk_bf16_f32 v105, v106, v107
	v_cvt_pk_bf16_f32 v96, v96, v97
	v_cvt_pk_bf16_f32 v97, v98, v99
	global_store_dwordx2 v139, v[120:121], s[4:5] offset:0
	global_store_dwordx2 v139, v[112:113], s[4:5] offset:32
	global_store_dwordx2 v139, v[104:105], s[4:5] offset:64
	global_store_dwordx2 v139, v[96:97], s[4:5] offset:96
	s_waitcnt vmcnt(23)
	v_lshlrev_b32_e32 v168, 16, v226
	v_and_b32_e32 v169, 0xffff0000, v226
	v_lshlrev_b32_e32 v170, 16, v227
	v_and_b32_e32 v171, 0xffff0000, v227
	v_pk_mul_f32 v[92:93], v[92:93], v[168:169]
	v_pk_mul_f32 v[94:95], v[94:95], v[170:171]
	global_load_dwordx2 v[226:227], v136, s[2:3] offset:256
	s_waitcnt vmcnt(23)
; __device__ __forceinline__ float bflo(unsigned u) { return __uint_as_float(u << 16); }
; __device__ __forceinline__ float bfhi(unsigned u) { return __uint_as_float(u & 0xffff0000u); }
;     ...
;               } else if (MODE == 2) {
;                 const u16* gate = (const u16*)outp;
;                 uint2 ga = *(const uint2*)(gate + (size_t)tok * 4096 + nc);
;                 uint2 p1; p1.x = pk2(v[0] * bflo(ga.x), v[1] * bfhi(ga.x)); p1.y = pk2(v[2] * bflo(ga.y), v[3] * bfhi(ga.y));
;                 *(uint2*)((u16*)(ws + OFF_YB) + (size_t)tok * DM + nc) = p1;
	v_lshlrev_b32_e32 v168, 16, v228
	v_and_b32_e32 v169, 0xffff0000, v228
	v_lshlrev_b32_e32 v170, 16, v229
	v_and_b32_e32 v171, 0xffff0000, v229
	v_pk_mul_f32 v[84:85], v[84:85], v[168:169]
	v_pk_mul_f32 v[86:87], v[86:87], v[170:171]
	global_load_dwordx2 v[228:229], v136, s[2:3] offset:288
	s_waitcnt vmcnt(23)
	v_lshlrev_b32_e32 v168, 16, v230
	v_and_b32_e32 v169, 0xffff0000, v230
	v_lshlrev_b32_e32 v170, 16, v231
	v_and_b32_e32 v171, 0xffff0000, v231
	v_pk_mul_f32 v[76:77], v[76:77], v[168:169]
	v_pk_mul_f32 v[78:79], v[78:79], v[170:171]
	global_load_dwordx2 v[230:231], v136, s[2:3] offset:320
	s_waitcnt vmcnt(23)
	v_lshlrev_b32_e32 v168, 16, v232
	v_and_b32_e32 v169, 0xffff0000, v232
	v_lshlrev_b32_e32 v170, 16, v233
	v_and_b32_e32 v171, 0xffff0000, v233
	v_pk_mul_f32 v[68:69], v[68:69], v[168:169]
	v_pk_mul_f32 v[70:71], v[70:71], v[170:171]
	global_load_dwordx2 v[232:233], v136, s[2:3] offset:352
	s_nop 0
	v_cvt_pk_bf16_f32 v92, v92, v93
	v_cvt_pk_bf16_f32 v93, v94, v95
	v_cvt_pk_bf16_f32 v84, v84, v85
	v_cvt_pk_bf16_f32 v85, v86, v87
	v_cvt_pk_bf16_f32 v76, v76, v77
	v_cvt_pk_bf16_f32 v77, v78, v79
	v_cvt_pk_bf16_f32 v68, v68, v69
	v_cvt_pk_bf16_f32 v69, v70, v71
	global_store_dwordx2 v140, v[92:93], s[4:5] offset:0
	global_store_dwordx2 v140, v[84:85], s[4:5] offset:32
	global_store_dwordx2 v140, v[76:77], s[4:5] offset:64
	global_store_dwordx2 v140, v[68:69], s[4:5] offset:96
	s_waitcnt vmcnt(27)
	v_lshlrev_b32_e32 v168, 16, v234
	v_and_b32_e32 v169, 0xffff0000, v234
	v_lshlrev_b32_e32 v170, 16, v235
	v_and_b32_e32 v171, 0xffff0000, v235
	v_pk_mul_f32 v[88:89], v[88:89], v[168:169]
	v_pk_mul_f32 v[90:91], v[90:91], v[170:171]
	global_load_dwordx2 v[234:235], v137, s[2:3] offset:256
	s_waitcnt vmcnt(27)
	v_lshlrev_b32_e32 v168, 16, v236
	v_and_b32_e32 v169, 0xffff0000, v236
	v_lshlrev_b32_e32 v170, 16, v237
	v_and_b32_e32 v171, 0xffff0000, v237
	v_pk_mul_f32 v[80:81], v[80:81], v[168:169]
	v_pk_mul_f32 v[82:83], v[82:83], v[170:171]
	global_load_dwordx2 v[236:237], v137, s[2:3] offset:288
	s_waitcnt vmcnt(27)
	v_lshlrev_b32_e32 v168, 16, v238
	v_and_b32_e32 v169, 0xffff0000, v238
	v_lshlrev_b32_e32 v170, 16, v239
	v_and_b32_e32 v171, 0xffff0000, v239
	v_pk_mul_f32 v[72:73], v[72:73], v[168:169]
	v_pk_mul_f32 v[74:75], v[74:75], v[170:171]
	global_load_dwordx2 v[238:239], v137, s[2:3] offset:320
	s_waitcnt vmcnt(27)
	v_lshlrev_b32_e32 v168, 16, v240
	v_and_b32_e32 v169, 0xffff0000, v240
	v_lshlrev_b32_e32 v170, 16, v241
	v_and_b32_e32 v171, 0xffff0000, v241
	v_pk_mul_f32 v[64:65], v[64:65], v[168:169]
	v_pk_mul_f32 v[66:67], v[66:67], v[170:171]
	global_load_dwordx2 v[240:241], v137, s[2:3] offset:352
	s_nop 0
	v_cvt_pk_bf16_f32 v88, v88, v89
	v_cvt_pk_bf16_f32 v89, v90, v91
	v_cvt_pk_bf16_f32 v80, v80, v81
	v_cvt_pk_bf16_f32 v81, v82, v83
	v_cvt_pk_bf16_f32 v72, v72, v73
	v_cvt_pk_bf16_f32 v73, v74, v75
	v_cvt_pk_bf16_f32 v64, v64, v65
	v_cvt_pk_bf16_f32 v65, v66, v67
	global_store_dwordx2 v141, v[88:89], s[4:5] offset:0
	global_store_dwordx2 v141, v[80:81], s[4:5] offset:32
	global_store_dwordx2 v141, v[72:73], s[4:5] offset:64
	global_store_dwordx2 v141, v[64:65], s[4:5] offset:96
	s_waitcnt vmcnt(31)
	v_lshlrev_b32_e32 v168, 16, v210
	v_and_b32_e32 v169, 0xffff0000, v210
	v_lshlrev_b32_e32 v170, 16, v211
	v_and_b32_e32 v171, 0xffff0000, v211
	v_pk_mul_f32 v[60:61], v[60:61], v[168:169]
	v_pk_mul_f32 v[62:63], v[62:63], v[170:171]
	s_waitcnt vmcnt(30)
	v_lshlrev_b32_e32 v168, 16, v212
	v_and_b32_e32 v169, 0xffff0000, v212
	v_lshlrev_b32_e32 v170, 16, v213
	v_and_b32_e32 v171, 0xffff0000, v213
	v_pk_mul_f32 v[52:53], v[52:53], v[168:169]
	v_pk_mul_f32 v[54:55], v[54:55], v[170:171]
	s_waitcnt vmcnt(29)
	v_lshlrev_b32_e32 v168, 16, v214
	v_and_b32_e32 v169, 0xffff0000, v214
	v_lshlrev_b32_e32 v170, 16, v215
	v_and_b32_e32 v171, 0xffff0000, v215
	v_pk_mul_f32 v[44:45], v[44:45], v[168:169]
	v_pk_mul_f32 v[46:47], v[46:47], v[170:171]
	s_waitcnt vmcnt(28)
	v_lshlrev_b32_e32 v168, 16, v216
	v_and_b32_e32 v169, 0xffff0000, v216
	v_lshlrev_b32_e32 v170, 16, v217
	v_and_b32_e32 v171, 0xffff0000, v217
	v_pk_mul_f32 v[36:37], v[36:37], v[168:169]
	v_pk_mul_f32 v[38:39], v[38:39], v[170:171]
	s_nop 0
	v_cvt_pk_bf16_f32 v60, v60, v61
	v_cvt_pk_bf16_f32 v61, v62, v63
	v_cvt_pk_bf16_f32 v52, v52, v53
	v_cvt_pk_bf16_f32 v53, v54, v55
	v_cvt_pk_bf16_f32 v44, v44, v45
	v_cvt_pk_bf16_f32 v45, v46, v47
	v_cvt_pk_bf16_f32 v36, v36, v37
	v_cvt_pk_bf16_f32 v37, v38, v39
	global_store_dwordx2 v138, v[60:61], s[4:5] offset:256
	global_store_dwordx2 v138, v[52:53], s[4:5] offset:288
	global_store_dwordx2 v138, v[44:45], s[4:5] offset:320
	global_store_dwordx2 v138, v[36:37], s[4:5] offset:352
	s_waitcnt vmcnt(27)
	v_lshlrev_b32_e32 v168, 16, v218
	v_and_b32_e32 v169, 0xffff0000, v218
	v_lshlrev_b32_e32 v170, 16, v219
	v_and_b32_e32 v171, 0xffff0000, v219
	v_pk_mul_f32 v[56:57], v[56:57], v[168:169]
	v_pk_mul_f32 v[58:59], v[58:59], v[170:171]
	s_waitcnt vmcnt(26)
	v_lshlrev_b32_e32 v168, 16, v220
	v_and_b32_e32 v169, 0xffff0000, v220
	v_lshlrev_b32_e32 v170, 16, v221
	v_and_b32_e32 v171, 0xffff0000, v221
	v_pk_mul_f32 v[48:49], v[48:49], v[168:169]
	v_pk_mul_f32 v[50:51], v[50:51], v[170:171]
	s_waitcnt vmcnt(25)
	v_lshlrev_b32_e32 v168, 16, v222
	v_and_b32_e32 v169, 0xffff0000, v222
	v_lshlrev_b32_e32 v170, 16, v223
	v_and_b32_e32 v171, 0xffff0000, v223
	v_pk_mul_f32 v[40:41], v[40:41], v[168:169]
	v_pk_mul_f32 v[42:43], v[42:43], v[170:171]
	s_waitcnt vmcnt(24)
; __device__ __forceinline__ float bflo(unsigned u) { return __uint_as_float(u << 16); }
; __device__ __forceinline__ float bfhi(unsigned u) { return __uint_as_float(u & 0xffff0000u); }
;     ...
; #pragma unroll
;     for (int a = 0; a < 2; ++a)
; #pragma unroll
;       for (int b = 0; b < 2; ++b)
; #pragma unroll
;         for (int m = 0; m < 4; ++m)
; #pragma unroll
;           for (int n = 0; n < 2; ++n) acc[a][b][m][n] = f32x4{0.f, 0.f, 0.f, 0.f};
;     ...
;               } else if (MODE == 2) {
;                 const u16* gate = (const u16*)outp;
;                 uint2 ga = *(const uint2*)(gate + (size_t)tok * 4096 + nc);
;                 uint2 p1; p1.x = pk2(v[0] * bflo(ga.x), v[1] * bfhi(ga.x)); p1.y = pk2(v[2] * bflo(ga.y), v[3] * bfhi(ga.y));
;                 *(uint2*)((u16*)(ws + OFF_YB) + (size_t)tok * DM + nc) = p1;
	v_lshlrev_b32_e32 v168, 16, v224
	v_and_b32_e32 v169, 0xffff0000, v224
	v_lshlrev_b32_e32 v170, 16, v225
	v_and_b32_e32 v171, 0xffff0000, v225
	v_pk_mul_f32 v[32:33], v[32:33], v[168:169]
	v_pk_mul_f32 v[34:35], v[34:35], v[170:171]
	s_nop 0
	v_cvt_pk_bf16_f32 v56, v56, v57
	v_cvt_pk_bf16_f32 v57, v58, v59
	v_cvt_pk_bf16_f32 v48, v48, v49
	v_cvt_pk_bf16_f32 v49, v50, v51
	v_cvt_pk_bf16_f32 v40, v40, v41
	v_cvt_pk_bf16_f32 v41, v42, v43
	v_cvt_pk_bf16_f32 v32, v32, v33
	v_cvt_pk_bf16_f32 v33, v34, v35
	global_store_dwordx2 v139, v[56:57], s[4:5] offset:256
	global_store_dwordx2 v139, v[48:49], s[4:5] offset:288
	global_store_dwordx2 v139, v[40:41], s[4:5] offset:320
	global_store_dwordx2 v139, v[32:33], s[4:5] offset:352
	s_waitcnt vmcnt(23)
	v_lshlrev_b32_e32 v168, 16, v226
	v_and_b32_e32 v169, 0xffff0000, v226
	v_lshlrev_b32_e32 v170, 16, v227
	v_and_b32_e32 v171, 0xffff0000, v227
	v_pk_mul_f32 v[28:29], v[28:29], v[168:169]
	v_pk_mul_f32 v[30:31], v[30:31], v[170:171]
	s_waitcnt vmcnt(22)
	v_lshlrev_b32_e32 v168, 16, v228
	v_and_b32_e32 v169, 0xffff0000, v228
	v_lshlrev_b32_e32 v170, 16, v229
	v_and_b32_e32 v171, 0xffff0000, v229
	v_pk_mul_f32 v[20:21], v[20:21], v[168:169]
	v_pk_mul_f32 v[22:23], v[22:23], v[170:171]
	s_waitcnt vmcnt(21)
	v_lshlrev_b32_e32 v168, 16, v230
	v_and_b32_e32 v169, 0xffff0000, v230
	v_lshlrev_b32_e32 v170, 16, v231
	v_and_b32_e32 v171, 0xffff0000, v231
	v_pk_mul_f32 v[12:13], v[12:13], v[168:169]
	v_pk_mul_f32 v[14:15], v[14:15], v[170:171]
	s_waitcnt vmcnt(20)
	v_lshlrev_b32_e32 v168, 16, v232
	v_and_b32_e32 v169, 0xffff0000, v232
	v_lshlrev_b32_e32 v170, 16, v233
	v_and_b32_e32 v171, 0xffff0000, v233
	v_pk_mul_f32 v[4:5], v[4:5], v[168:169]
	v_pk_mul_f32 v[6:7], v[6:7], v[170:171]
	s_nop 0
	v_cvt_pk_bf16_f32 v28, v28, v29
	v_cvt_pk_bf16_f32 v29, v30, v31
	v_cvt_pk_bf16_f32 v20, v20, v21
	v_cvt_pk_bf16_f32 v21, v22, v23
	v_cvt_pk_bf16_f32 v12, v12, v13
	v_cvt_pk_bf16_f32 v13, v14, v15
	v_cvt_pk_bf16_f32 v4, v4, v5
	v_cvt_pk_bf16_f32 v5, v6, v7
	global_store_dwordx2 v140, v[28:29], s[4:5] offset:256
	global_store_dwordx2 v140, v[20:21], s[4:5] offset:288
	global_store_dwordx2 v140, v[12:13], s[4:5] offset:320
	global_store_dwordx2 v140, v[4:5], s[4:5] offset:352
	s_waitcnt vmcnt(19)
	v_lshlrev_b32_e32 v168, 16, v234
	v_and_b32_e32 v169, 0xffff0000, v234
	v_lshlrev_b32_e32 v170, 16, v235
	v_and_b32_e32 v171, 0xffff0000, v235
	v_pk_mul_f32 v[24:25], v[24:25], v[168:169]
	v_pk_mul_f32 v[26:27], v[26:27], v[170:171]
	s_waitcnt vmcnt(18)
	v_lshlrev_b32_e32 v168, 16, v236
	v_and_b32_e32 v169, 0xffff0000, v236
	v_lshlrev_b32_e32 v170, 16, v237
	v_and_b32_e32 v171, 0xffff0000, v237
	v_pk_mul_f32 v[16:17], v[16:17], v[168:169]
	v_pk_mul_f32 v[18:19], v[18:19], v[170:171]
	s_waitcnt vmcnt(17)
	v_lshlrev_b32_e32 v168, 16, v238
	v_and_b32_e32 v169, 0xffff0000, v238
	v_lshlrev_b32_e32 v170, 16, v239
	v_and_b32_e32 v171, 0xffff0000, v239
	v_pk_mul_f32 v[8:9], v[8:9], v[168:169]
	v_pk_mul_f32 v[10:11], v[10:11], v[170:171]
	s_waitcnt vmcnt(16)
	v_lshlrev_b32_e32 v168, 16, v240
	v_and_b32_e32 v169, 0xffff0000, v240
	v_lshlrev_b32_e32 v170, 16, v241
	v_and_b32_e32 v171, 0xffff0000, v241
	v_pk_mul_f32 v[0:1], v[0:1], v[168:169]
	v_pk_mul_f32 v[2:3], v[2:3], v[170:171]
	s_nop 0
	v_cvt_pk_bf16_f32 v24, v24, v25
	v_cvt_pk_bf16_f32 v25, v26, v27
	v_cvt_pk_bf16_f32 v16, v16, v17
	v_cvt_pk_bf16_f32 v17, v18, v19
	v_cvt_pk_bf16_f32 v8, v8, v9
	v_cvt_pk_bf16_f32 v9, v10, v11
	v_cvt_pk_bf16_f32 v0, v0, v1
	v_cvt_pk_bf16_f32 v1, v2, v3
	global_store_dwordx2 v141, v[24:25], s[4:5] offset:256
	global_store_dwordx2 v141, v[16:17], s[4:5] offset:288
	global_store_dwordx2 v141, v[8:9], s[4:5] offset:320
	global_store_dwordx2 v141, v[0:1], s[4:5] offset:352
	s_and_b64 s[0:1], s[56:57], s[8:9]
	s_andn2_b64 vcc, exec, s[0:1]
	s_nop 1
	v_mov_b32_e32 v0, 0
	v_mov_b32_e32 v1, v0
	v_mov_b32_e32 v2, v0
	v_mov_b32_e32 v3, v0
	v_mov_b32_e32 v4, v0
	v_mov_b32_e32 v5, v0
	v_mov_b32_e32 v6, v0
	v_mov_b32_e32 v7, v0
	v_mov_b32_e32 v8, v0
	v_mov_b32_e32 v9, v0
	v_mov_b32_e32 v10, v0
	v_mov_b32_e32 v11, v0
	v_mov_b32_e32 v12, v0
	v_mov_b32_e32 v13, v0
	v_mov_b32_e32 v14, v0
	v_mov_b32_e32 v15, v0
	v_mov_b32_e32 v16, v0
	v_mov_b32_e32 v17, v0
	v_mov_b32_e32 v18, v0
	v_mov_b32_e32 v19, v0
	v_mov_b32_e32 v20, v0
	v_mov_b32_e32 v21, v0
	v_mov_b32_e32 v22, v0
	v_mov_b32_e32 v23, v0
	v_mov_b32_e32 v24, v0
	v_mov_b32_e32 v25, v0
	v_mov_b32_e32 v26, v0
	v_mov_b32_e32 v27, v0
	v_mov_b32_e32 v28, v0
	v_mov_b32_e32 v29, v0
	v_mov_b32_e32 v30, v0
	v_mov_b32_e32 v31, v0
	v_mov_b32_e32 v32, v0
	v_mov_b32_e32 v33, v0
	v_mov_b32_e32 v34, v0
	v_mov_b32_e32 v35, v0
	v_mov_b32_e32 v36, v0
	v_mov_b32_e32 v37, v0
	v_mov_b32_e32 v38, v0
	v_mov_b32_e32 v39, v0
	v_mov_b32_e32 v40, v0
	v_mov_b32_e32 v41, v0
	v_mov_b32_e32 v42, v0
	v_mov_b32_e32 v43, v0
	v_mov_b32_e32 v44, v0
	v_mov_b32_e32 v45, v0
	v_mov_b32_e32 v46, v0
	v_mov_b32_e32 v47, v0
	v_mov_b32_e32 v48, v0
	v_mov_b32_e32 v49, v0
	v_mov_b32_e32 v50, v0
	v_mov_b32_e32 v51, v0
	v_mov_b32_e32 v52, v0
	v_mov_b32_e32 v53, v0
	v_mov_b32_e32 v54, v0
	v_mov_b32_e32 v55, v0
	v_mov_b32_e32 v56, v0
	v_mov_b32_e32 v57, v0
	v_mov_b32_e32 v58, v0
	v_mov_b32_e32 v59, v0
	v_mov_b32_e32 v60, v0
	v_mov_b32_e32 v61, v0
	v_mov_b32_e32 v62, v0
	v_mov_b32_e32 v63, v0
	v_mov_b32_e32 v64, v0
	v_mov_b32_e32 v65, v0
	v_mov_b32_e32 v66, v0
	v_mov_b32_e32 v67, v0
	v_mov_b32_e32 v68, v0
	v_mov_b32_e32 v69, v0
	v_mov_b32_e32 v70, v0
	v_mov_b32_e32 v71, v0
	v_mov_b32_e32 v72, v0
	v_mov_b32_e32 v73, v0
	v_mov_b32_e32 v74, v0
	v_mov_b32_e32 v75, v0
	v_mov_b32_e32 v76, v0
	v_mov_b32_e32 v77, v0
	v_mov_b32_e32 v78, v0
	v_mov_b32_e32 v79, v0
	v_mov_b32_e32 v80, v0
	v_mov_b32_e32 v81, v0
	v_mov_b32_e32 v82, v0
	v_mov_b32_e32 v83, v0
	v_mov_b32_e32 v84, v0
	v_mov_b32_e32 v85, v0
	v_mov_b32_e32 v86, v0
	v_mov_b32_e32 v87, v0
	v_mov_b32_e32 v88, v0
	v_mov_b32_e32 v89, v0
	v_mov_b32_e32 v90, v0
	v_mov_b32_e32 v91, v0
	v_mov_b32_e32 v92, v0
	v_mov_b32_e32 v93, v0
	v_mov_b32_e32 v94, v0
	v_mov_b32_e32 v95, v0
	v_mov_b32_e32 v96, v0
	v_mov_b32_e32 v97, v0
	v_mov_b32_e32 v98, v0
	v_mov_b32_e32 v99, v0
	v_mov_b32_e32 v100, v0
	v_mov_b32_e32 v101, v0
	v_mov_b32_e32 v102, v0
	v_mov_b32_e32 v103, v0
	v_mov_b32_e32 v104, v0
	v_mov_b32_e32 v105, v0
	v_mov_b32_e32 v106, v0
	v_mov_b32_e32 v107, v0
	v_mov_b32_e32 v108, v0
	v_mov_b32_e32 v109, v0
	v_mov_b32_e32 v110, v0
	v_mov_b32_e32 v111, v0
	v_mov_b32_e32 v112, v0
	v_mov_b32_e32 v113, v0
	v_mov_b32_e32 v114, v0
	v_mov_b32_e32 v115, v0
	v_mov_b32_e32 v116, v0
	v_mov_b32_e32 v117, v0
	v_mov_b32_e32 v118, v0
	v_mov_b32_e32 v119, v0
	v_mov_b32_e32 v120, v0
	v_mov_b32_e32 v121, v0
	v_mov_b32_e32 v122, v0
	v_mov_b32_e32 v123, v0
	v_mov_b32_e32 v124, v0
	v_mov_b32_e32 v125, v0
	v_mov_b32_e32 v126, v0
	v_mov_b32_e32 v127, v0
	s_waitcnt vmcnt(0)
	s_cbranch_vccnz .LBB0_804
	s_barrier
	s_branch .LBB0_804

; #define STAGE(P_, BASE, br, kt) do { const u16* _gb = (BASE) + (long)(br) * K + (long)(kt) * BK; \
;     _Pragma("unroll") for (int _i = 0; _i < 2; ++_i) { \
;       __builtin_amdgcn_global_load_lds((const unsigned*)(_gb + (long)_i * 64 * K + lane_off), \
;         (unsigned*)((char*)(P_) + lds_wbase + _i * 8192), 16, 0, 0); } } while (0)
; #define WAIT_V(n) asm volatile("s_waitcnt vmcnt(" #n ")" ::: "memory")
; #define BAR __builtin_amdgcn_s_barrier()
; template <int PRE> ...
;     ...
;   const int wid = wvi, lane = tid & 63, wr = wid >> 2, wc = wid & 3, fr = lane & 15, fq = lane >> 4;
;   bf16x8 At[4][2], B0[2][2], B1[2][2];
;   const int nt = K / BK;
;   const unsigned lds_wbase = wid * 1024;
;   unsigned lane_off;
;   { int _r, _c; stage_rc(tid * 16, _r, _c); lane_off = (unsigned)(_r * K + _c); }
;     ...
;   if (PRE == 2) {
;     STAGE(SB(0, 0), Bt, bcol, 0); STAGE(SA(0, 0), A, brow, 0);
;     STAGE(SB(0, 1), Bt, bcol + HALF, 0); STAGE(SA(0, 1), A, brow + HALF, 0);
;     if (wr == 1) BAR;
;     WAIT_V(4); BAR;
;     STAGE(SB(1, 0), Bt, bcol, 1); STAGE(SA(1, 0), A, brow, 1); STAGE(SB(1, 1), Bt, bcol + HALF, 1);
;     WAIT_V(6); BAR;
;     return;
;   }
;     ...
; #pragma unroll
;     for (int a = 0; a < 2; ++a)
; #pragma unroll
;       for (int b = 0; b < 2; ++b)
; #pragma unroll
;         for (int m = 0; m < 4; ++m)
; #pragma unroll
;           for (int n = 0; n < 2; ++n) acc[a][b][m][n] = f32x4{0.f, 0.f, 0.f, 0.f};
.LBB0_818:
	s_mov_b64 s[2:3], 0x80
	s_add_i32 s20, s10, 0x18000
	v_lshl_add_u64 v[12:13], v[0:1], 0, s[2:3]
	s_mov_b32 m0, s20
	s_mov_b64 s[4:5], 0x40080
	s_add_i32 s21, s10, 0x1a000
	s_waitcnt vmcnt(4)
	s_barrier
	global_load_lds_dwordx4 v[12:13], off
	v_lshl_add_u64 v[0:1], v[0:1], 0, s[4:5]
	s_mov_b32 m0, s21
	s_add_i32 s22, s10, 0x8000
	global_load_lds_dwordx4 v[0:1], off
	v_lshl_add_u64 v[0:1], v[2:3], 0, s[2:3]
	s_mov_b32 m0, s22
	s_add_i32 s23, s10, 0xa000
	global_load_lds_dwordx4 v[0:1], off
	v_lshl_add_u64 v[0:1], v[2:3], 0, s[4:5]
	s_mov_b32 m0, s23
	s_add_i32 s24, s10, 0x1c000
	global_load_lds_dwordx4 v[0:1], off
	v_lshl_add_u64 v[0:1], v[4:5], 0, s[2:3]
	s_mov_b32 m0, s24
	s_add_i32 s25, s10, 0x1e000
	global_load_lds_dwordx4 v[0:1], off
	v_lshl_add_u64 v[0:1], v[4:5], 0, s[4:5]
	s_mov_b32 m0, s25
	v_lshlrev_b32_e32 v3, 2, v9
	global_load_lds_dwordx4 v[0:1], off
	v_and_b32_e32 v0, 15, v9
	v_and_b32_e32 v1, 48, v9
	v_lshlrev_b32_e32 v2, 6, v0
	v_and_b32_e32 v3, 32, v3
	v_readlane_b32 s0, v246, 52
	v_bitop3_b32 v159, v2, v3, v1 bitop3:0x36
	v_readlane_b32 s2, v244, 32
	v_or_b32_e32 v2, s0, v0
	v_lshlrev_b32_e32 v3, 6, v2
	v_lshlrev_b32_e32 v2, 2, v2
	v_and_b32_e32 v3, 0x3c0, v3
	v_and_b32_e32 v2, 32, v2
	v_readlane_b32 s0, v246, 51
	v_bitop3_b32 v2, v3, v2, v1 bitop3:0x36
	v_readlane_b32 s3, v244, 33
	v_or_b32_e32 v3, s0, v0
	v_lshlrev_b32_e32 v4, 6, v3
	v_lshlrev_b32_e32 v3, 2, v3
	v_and_b32_e32 v4, 0x3c0, v4
	v_and_b32_e32 v3, 32, v3
	v_readlane_b32 s0, v246, 53
	v_bitop3_b32 v3, v4, v3, v1 bitop3:0x36
	s_waitcnt vmcnt(6)
	v_and_b32_e32 v158, 63, v9
	v_or_b32_e32 v4, s0, v0
	v_lshlrev_b32_e32 v5, 6, v4
	v_lshlrev_b32_e32 v4, 2, v4
	v_readlane_b32 s0, v246, 54
	v_and_b32_e32 v5, 0x3c0, v5
	v_and_b32_e32 v4, 32, v4
	v_or_b32_e32 v0, s0, v0
	v_bitop3_b32 v4, v5, v4, v1 bitop3:0x36
	v_lshlrev_b32_e32 v5, 6, v0
	v_lshlrev_b32_e32 v0, 2, v0
	v_and_b32_e32 v5, 0x3c0, v5
	v_and_b32_e32 v0, 32, v0
	v_bitop3_b32 v0, v5, v0, v1 bitop3:0x36
	v_lshlrev_b32_e32 v1, 14, v6
	v_and_b32_e32 v1, 0xffff8000, v1
	v_lshl_add_u32 v1, v7, 11, v1
	v_or_b32_e32 v1, v1, v8
	v_add_u32_sdwa v144, v1, sext(v10) dst_sel:DWORD dst_unused:UNUSED_PAD src0_sel:DWORD src1_sel:WORD_0
	v_readlane_b32 s0, v244, 12
	v_lshl_add_u64 v[132:133], v[144:145], 1, s[2:3]
	s_barrier
	v_add_u32_e32 v144, s0, v2
	v_readlane_b32 s0, v244, 13
	s_nop 1
	v_add_u32_e32 v160, s0, v3
	v_readlane_b32 s0, v244, 14
	s_nop 1
	v_add_u32_e32 v161, s0, v4
	v_readlane_b32 s0, v244, 15
	s_nop 1
	v_add_u32_e32 v162, s0, v0
	v_mov_b32_e32 v0, 0
	v_mov_b32_e32 v1, v0
	v_mov_b32_e32 v2, v0
	v_mov_b32_e32 v3, v0
	v_mov_b32_e32 v4, v0
	v_mov_b32_e32 v5, v0
	v_mov_b32_e32 v6, v0
	v_mov_b32_e32 v7, v0
	v_mov_b32_e32 v8, v0
	v_mov_b32_e32 v9, v0
	v_mov_b32_e32 v10, v0
	v_mov_b32_e32 v11, v0
	v_mov_b32_e32 v12, v0
	v_mov_b32_e32 v13, v0
	v_mov_b32_e32 v14, v0
	v_mov_b32_e32 v15, v0
	v_mov_b32_e32 v16, v0
	v_mov_b32_e32 v17, v0
	v_mov_b32_e32 v18, v0
	v_mov_b32_e32 v19, v0
	v_mov_b32_e32 v20, v0
	v_mov_b32_e32 v21, v0
	v_mov_b32_e32 v22, v0
	v_mov_b32_e32 v23, v0
	v_mov_b32_e32 v24, v0
	v_mov_b32_e32 v25, v0
	v_mov_b32_e32 v26, v0
	v_mov_b32_e32 v27, v0
	v_mov_b32_e32 v28, v0
	v_mov_b32_e32 v29, v0
	v_mov_b32_e32 v30, v0
	v_mov_b32_e32 v31, v0
	v_mov_b32_e32 v32, v0
	v_mov_b32_e32 v33, v0
	v_mov_b32_e32 v34, v0
	v_mov_b32_e32 v35, v0
	v_mov_b32_e32 v36, v0
	v_mov_b32_e32 v37, v0
	v_mov_b32_e32 v38, v0
	v_mov_b32_e32 v39, v0
	v_mov_b32_e32 v40, v0
	v_mov_b32_e32 v41, v0
	v_mov_b32_e32 v42, v0
	v_mov_b32_e32 v43, v0
	v_mov_b32_e32 v44, v0
	v_mov_b32_e32 v45, v0
	v_mov_b32_e32 v46, v0
	v_mov_b32_e32 v47, v0
	v_mov_b32_e32 v48, v0
	v_mov_b32_e32 v49, v0
	v_mov_b32_e32 v50, v0
	v_mov_b32_e32 v51, v0
	v_mov_b32_e32 v52, v0
	v_mov_b32_e32 v53, v0
	v_mov_b32_e32 v54, v0
	v_mov_b32_e32 v55, v0
	v_mov_b32_e32 v56, v0
	v_mov_b32_e32 v57, v0
	v_mov_b32_e32 v58, v0
	v_mov_b32_e32 v59, v0
	v_mov_b32_e32 v60, v0
	v_mov_b32_e32 v61, v0
	v_mov_b32_e32 v62, v0
	v_mov_b32_e32 v63, v0
	v_mov_b32_e32 v64, v0
	v_mov_b32_e32 v65, v0
	v_mov_b32_e32 v66, v0
	v_mov_b32_e32 v67, v0
	v_mov_b32_e32 v68, v0
	v_mov_b32_e32 v69, v0
	v_mov_b32_e32 v70, v0
	v_mov_b32_e32 v71, v0
	v_mov_b32_e32 v72, v0
	v_mov_b32_e32 v73, v0
	v_mov_b32_e32 v74, v0
	v_mov_b32_e32 v75, v0
	v_mov_b32_e32 v76, v0
	v_mov_b32_e32 v77, v0
	v_mov_b32_e32 v78, v0
	v_mov_b32_e32 v79, v0
	v_mov_b32_e32 v80, v0
	v_mov_b32_e32 v81, v0
	v_mov_b32_e32 v82, v0
	v_mov_b32_e32 v83, v0
	v_mov_b32_e32 v84, v0
	v_mov_b32_e32 v85, v0
	v_mov_b32_e32 v86, v0
	v_mov_b32_e32 v87, v0
	v_mov_b32_e32 v88, v0
	v_mov_b32_e32 v89, v0
	v_mov_b32_e32 v90, v0
	v_mov_b32_e32 v91, v0
	v_mov_b32_e32 v92, v0
	v_mov_b32_e32 v93, v0
	v_mov_b32_e32 v94, v0
	v_mov_b32_e32 v95, v0
	v_mov_b32_e32 v96, v0
	v_mov_b32_e32 v97, v0
	v_mov_b32_e32 v98, v0
	v_mov_b32_e32 v99, v0
	v_mov_b32_e32 v100, v0
	v_mov_b32_e32 v101, v0
	v_mov_b32_e32 v102, v0
	v_mov_b32_e32 v103, v0
	v_mov_b32_e32 v104, v0
	v_mov_b32_e32 v105, v0
	v_mov_b32_e32 v106, v0
	v_mov_b32_e32 v107, v0
	v_mov_b32_e32 v108, v0
	v_mov_b32_e32 v109, v0
	v_mov_b32_e32 v110, v0
	v_mov_b32_e32 v111, v0
	v_mov_b32_e32 v112, v0
	v_mov_b32_e32 v113, v0
	v_mov_b32_e32 v114, v0
	v_mov_b32_e32 v115, v0
	v_mov_b32_e32 v116, v0
	v_mov_b32_e32 v117, v0
	v_mov_b32_e32 v118, v0
	v_mov_b32_e32 v119, v0
	v_mov_b32_e32 v120, v0
	v_mov_b32_e32 v121, v0
	v_mov_b32_e32 v122, v0
	v_mov_b32_e32 v123, v0
	v_mov_b32_e32 v124, v0
	v_mov_b32_e32 v125, v0
	v_mov_b32_e32 v126, v0
	v_mov_b32_e32 v127, v0
	s_branch .LBB0_820

;     ...
;   for (int u = vb; u < nunits; u += ustride) {
;     const int tm = u % nM, tn = u / nM + ((tn_skip >= 0 && u / nM >= tn_skip) ? 1 : 0);
;     const int brow = tn * 256, bcol = tm * 256;
;     const int un = u + ustride;
;     const bool has_next = un < nunits;
;     const int tn_n = un / nM + ((tn_skip >= 0 && un / nM >= tn_skip) ? 1 : 0);
;     const int brow_n = has_next ? tn_n * 256 : brow, bcol_n = has_next ? (un % nM) * 256 : bcol;
.LBB0_824:
	s_ashr_i32 s1, s0, 31
	s_lshl_b64 s[2:3], s[0:1], 12
	s_or_b32 s30, s0, 0x80
	s_or_b32 s31, s29, 0x80
	s_or_b32 s34, s27, 0x80
	s_or_b32 s35, s28, 0x80
	v_lshl_add_u64 v[128:129], v[132:133], 0, s[2:3]
	s_mov_b32 s1, 0
	s_waitcnt vmcnt(0)

; __device__ __forceinline__ float bflo(unsigned u) { return __uint_as_float(u << 16); }
;     ...
;               const int nc = brow + ai * 128 + wr * 64 + m * 16 + fq * 4;
;               const int tok = bcol + bj * 128 + wc * 32 + n * 16 + fr;
;               const int ncw = brow + ai * 128 + wr * 64 + ((m & ~1) + (fq & 1)) * 16 + (fq & ~1) * 4;
;     ...
;               f32x4 v = acc[ai][bj][m][n];
;               if (MODE == 0) {
;                 if (tn == 52) {
;                   if (ai == 0) *(float4*)((float*)(ws + OFF_DTR) + (size_t)tok * 128 + (nc - 13312)) = make_float4(v[0], v[1], v[2], v[3]);
;                 } else {
;                   u16* dst; int ld, c0;
;                   if (tn < 16) { dst = (u16*)(ws + OFF_Z); ld = 4096; c0 = 0; }
;                   else if (tn < 40) { dst = (u16*)(ws + OFF_RA); ld = 6144; c0 = 4096; }
;                   else if (tn < 48) { dst = (u16*)(ws + OFF_Q); ld = 2048; c0 = 10240; }
;                   else if (tn < 50) { dst = (u16*)(ws + OFF_K); ld = 512; c0 = 12288; }
;                   else { dst = (u16*)(ws + OFF_V); ld = 512; c0 = 12800; }
;                   uint2 o; o.x = pk2(v[0], v[1]); o.y = pk2(v[2], v[3]);
;                   WIDE_STORE(dst, ld, c0, o);
;                 }
;               } else if (MODE == 1) {
;                 uint2 o; o.x = pk2(sigmoidf_(v[0]), sigmoidf_(v[1])); o.y = pk2(sigmoidf_(v[2]), sigmoidf_(v[3]));
;                 WIDE_STORE((u16*)outp, 4096, 0, o);
;               } else if (MODE == 2) {
;                 const u16* gate = (const u16*)outp;
;                 uint2 ga = *(const uint2*)(gate + (size_t)tok * 4096 + nc);
;                 uint2 p1; p1.x = pk2(v[0] * bflo(ga.x), v[1] * bfhi(ga.x)); p1.y = pk2(v[2] * bflo(ga.y), v[3] * bfhi(ga.y));
;                 *(uint2*)((u16*)(ws + OFF_YB) + (size_t)tok * DM + nc) = p1;
;               } else if (MODE == 6) {
;                 const u16* gate = (const u16*)outp;
;                 uint2 gb = *(const uint2*)(gate + (size_t)tok * 4096 + 2048 + nc);
;                 const uint2 p1 = *(const uint2*)((const u16*)(ws + OFF_YB) + (size_t)tok * DM + nc);
;                 uint2 o;
;                 o.x = pk2(bflo(p1.x) + v[0] * bflo(gb.x), bfhi(p1.x) + v[1] * bfhi(gb.x));
;                 o.y = pk2(bflo(p1.y) + v[2] * bflo(gb.y), bfhi(p1.y) + v[3] * bfhi(gb.y));
;                 WIDE_STORE((u16*)(ws + OFF_RB + 128 * MiB), DM, 0, o);
.LBB0_828:
	v_readlane_b32 s28, v243, 57
	v_readlane_b32 s29, v243, 58
	v_readlane_b32 s4, v244, 3
	v_readlane_b32 s5, v244, 4
	s_add_i32 s0, s0, s49
	v_and_b32_e32 v172, 15, v158
	v_or_b32_e32 v172, s54, v172
	v_or_b32_e32 v172, s27, v172
	v_lshrrev_b32_e32 v173, 2, v158
	v_and_b32_e32 v174, -4, v173
	v_add_u32_e32 v174, s0, v174
	v_and_b32_e32 v173, -8, v173
	v_and_b32_e32 v175, 16, v158
	v_add3_u32 v173, v173, v175, s0
	v_lshlrev_b32_e32 v175, 13, v172
	v_lshl_add_u32 v134, v174, 1, v175
	v_add_u32_e32 v134, 0x1000, v134
	v_add_u32_e32 v135, 0x20000, v134
	v_add_u32_e32 v136, 0x100000, v134
	v_add_u32_e32 v137, 0x120000, v134
	v_lshlrev_b32_e32 v175, 12, v172
	v_lshl_add_u32 v138, v174, 1, v175
	v_add_u32_e32 v139, 0x10000, v138
	v_add_u32_e32 v140, 0x80000, v138
	v_add_u32_e32 v141, 0x90000, v138
	v_lshlrev_b32_e32 v175, 12, v172
	v_lshl_add_u32 v190, v173, 1, v175
	v_add_u32_e32 v191, 0x10000, v190
	v_add_u32_e32 v192, 0x80000, v190
	v_add_u32_e32 v193, 0x90000, v190
	global_load_dwordx2 v[210:211], v134, s[28:29] offset:0
	global_load_dwordx2 v[212:213], v138, s[4:5] offset:0
	global_load_dwordx2 v[214:215], v134, s[28:29] offset:32
	global_load_dwordx2 v[216:217], v138, s[4:5] offset:32
	global_load_dwordx2 v[218:219], v134, s[28:29] offset:64
	global_load_dwordx2 v[220:221], v138, s[4:5] offset:64
	global_load_dwordx2 v[222:223], v134, s[28:29] offset:96
	global_load_dwordx2 v[224:225], v138, s[4:5] offset:96
	global_load_dwordx2 v[226:227], v135, s[28:29] offset:0
	global_load_dwordx2 v[228:229], v139, s[4:5] offset:0
	global_load_dwordx2 v[230:231], v135, s[28:29] offset:32
	global_load_dwordx2 v[232:233], v139, s[4:5] offset:32
	global_load_dwordx2 v[234:235], v135, s[28:29] offset:64
	global_load_dwordx2 v[236:237], v139, s[4:5] offset:64
	global_load_dwordx2 v[238:239], v135, s[28:29] offset:96
	global_load_dwordx2 v[240:241], v139, s[4:5] offset:96
	s_waitcnt vmcnt(14)
	v_lshlrev_b32_e32 v168, 16, v210
	v_and_b32_e32 v169, 0xffff0000, v210
	v_lshlrev_b32_e32 v176, 16, v212
	v_and_b32_e32 v177, 0xffff0000, v212
	v_pk_fma_f32 v[124:125], v[124:125], v[168:169], v[176:177]
	v_lshlrev_b32_e32 v170, 16, v211
	v_and_b32_e32 v171, 0xffff0000, v211
	v_lshlrev_b32_e32 v178, 16, v213
	v_and_b32_e32 v179, 0xffff0000, v213
	v_pk_fma_f32 v[126:127], v[126:127], v[170:171], v[178:179]
	global_load_dwordx2 v[210:211], v136, s[28:29] offset:0
	global_load_dwordx2 v[212:213], v140, s[4:5] offset:0
	s_waitcnt vmcnt(14)
	v_lshlrev_b32_e32 v168, 16, v214
	v_and_b32_e32 v169, 0xffff0000, v214
	v_lshlrev_b32_e32 v176, 16, v216
	v_and_b32_e32 v177, 0xffff0000, v216
	v_pk_fma_f32 v[116:117], v[116:117], v[168:169], v[176:177]
	v_lshlrev_b32_e32 v170, 16, v215
	v_and_b32_e32 v171, 0xffff0000, v215
	v_lshlrev_b32_e32 v178, 16, v217
	v_and_b32_e32 v179, 0xffff0000, v217
	v_pk_fma_f32 v[118:119], v[118:119], v[170:171], v[178:179]
	global_load_dwordx2 v[214:215], v136, s[28:29] offset:32
	global_load_dwordx2 v[216:217], v140, s[4:5] offset:32
	s_waitcnt vmcnt(14)
	v_lshlrev_b32_e32 v168, 16, v218
	v_and_b32_e32 v169, 0xffff0000, v218
	v_lshlrev_b32_e32 v176, 16, v220
	v_and_b32_e32 v177, 0xffff0000, v220
	v_pk_fma_f32 v[108:109], v[108:109], v[168:169], v[176:177]
	v_lshlrev_b32_e32 v170, 16, v219
	v_and_b32_e32 v171, 0xffff0000, v219
	v_lshlrev_b32_e32 v178, 16, v221
	v_and_b32_e32 v179, 0xffff0000, v221
	v_pk_fma_f32 v[110:111], v[110:111], v[170:171], v[178:179]
	global_load_dwordx2 v[218:219], v136, s[28:29] offset:64
	global_load_dwordx2 v[220:221], v140, s[4:5] offset:64
	s_waitcnt vmcnt(14)
	v_lshlrev_b32_e32 v168, 16, v222
	v_and_b32_e32 v169, 0xffff0000, v222
	v_lshlrev_b32_e32 v176, 16, v224
	v_and_b32_e32 v177, 0xffff0000, v224
	v_pk_fma_f32 v[100:101], v[100:101], v[168:169], v[176:177]
	v_lshlrev_b32_e32 v170, 16, v223
	v_and_b32_e32 v171, 0xffff0000, v223
	v_lshlrev_b32_e32 v178, 16, v225
	v_and_b32_e32 v179, 0xffff0000, v225
	v_pk_fma_f32 v[102:103], v[102:103], v[170:171], v[178:179]
	global_load_dwordx2 v[222:223], v136, s[28:29] offset:96
	global_load_dwordx2 v[224:225], v140, s[4:5] offset:96
	s_nop 0
	v_cvt_pk_bf16_f32 v124, v124, v125
	v_cvt_pk_bf16_f32 v125, v126, v127
	v_cvt_pk_bf16_f32 v126, v116, v117
	v_cvt_pk_bf16_f32 v127, v118, v119
	v_cvt_pk_bf16_f32 v108, v108, v109
	v_cvt_pk_bf16_f32 v109, v110, v111
	v_cvt_pk_bf16_f32 v110, v100, v101
	v_cvt_pk_bf16_f32 v111, v102, v103
	s_nop 1
	v_permlane16_swap_b32_e32 v124, v126
	v_permlane16_swap_b32_e32 v125, v127
	v_permlane16_swap_b32_e32 v108, v110
	v_permlane16_swap_b32_e32 v109, v111
	global_store_dwordx4 v190, v[124:127], s[72:73] offset:0
	global_store_dwordx4 v190, v[108:111], s[72:73] offset:64
	s_waitcnt vmcnt(16)
	v_lshlrev_b32_e32 v168, 16, v226
	v_and_b32_e32 v169, 0xffff0000, v226
	v_lshlrev_b32_e32 v176, 16, v228
	v_and_b32_e32 v177, 0xffff0000, v228
	v_pk_fma_f32 v[120:121], v[120:121], v[168:169], v[176:177]
	v_lshlrev_b32_e32 v170, 16, v227
	v_and_b32_e32 v171, 0xffff0000, v227
	v_lshlrev_b32_e32 v178, 16, v229
	v_and_b32_e32 v179, 0xffff0000, v229
	v_pk_fma_f32 v[122:123], v[122:123], v[170:171], v[178:179]
	global_load_dwordx2 v[226:227], v137, s[28:29] offset:0
	global_load_dwordx2 v[228:229], v141, s[4:5] offset:0
	s_waitcnt vmcnt(16)
	v_lshlrev_b32_e32 v168, 16, v230
	v_and_b32_e32 v169, 0xffff0000, v230
	v_lshlrev_b32_e32 v176, 16, v232
	v_and_b32_e32 v177, 0xffff0000, v232
	v_pk_fma_f32 v[112:113], v[112:113], v[168:169], v[176:177]
	v_lshlrev_b32_e32 v170, 16, v231
	v_and_b32_e32 v171, 0xffff0000, v231
	v_lshlrev_b32_e32 v178, 16, v233
	v_and_b32_e32 v179, 0xffff0000, v233
	v_pk_fma_f32 v[114:115], v[114:115], v[170:171], v[178:179]
	global_load_dwordx2 v[230:231], v137, s[28:29] offset:32
	global_load_dwordx2 v[232:233], v141, s[4:5] offset:32
	s_waitcnt vmcnt(16)
; __device__ __forceinline__ float bflo(unsigned u) { return __uint_as_float(u << 16); }
; __device__ __forceinline__ float bfhi(unsigned u) { return __uint_as_float(u & 0xffff0000u); }
; #define WIDE_STORE(BASE, LD, COFF, O) do { if ((m & 1) == 0) opend[n] = (O); \
;                 else *(uint4*)((BASE) + (size_t)tok * (LD) + (ncw - (COFF))) = swap_pair(opend[n], (O)); } while (0)
; __device__ __forceinline__ uint4 swap_pair(const uint2 a, const uint2 b) {
;   const auto rx = __builtin_amdgcn_permlane16_swap(a.x, b.x, false, false);
;   const auto ry = __builtin_amdgcn_permlane16_swap(a.y, b.y, false, false);
;   return make_uint4(rx[0], ry[0], rx[1], ry[1]);
; }
;     ...
;               } else if (MODE == 6) {
;                 const u16* gate = (const u16*)outp;
;                 uint2 gb = *(const uint2*)(gate + (size_t)tok * 4096 + 2048 + nc);
;                 const uint2 p1 = *(const uint2*)((const u16*)(ws + OFF_YB) + (size_t)tok * DM + nc);
;                 uint2 o;
;                 o.x = pk2(bflo(p1.x) + v[0] * bflo(gb.x), bfhi(p1.x) + v[1] * bfhi(gb.x));
;                 o.y = pk2(bflo(p1.y) + v[2] * bflo(gb.y), bfhi(p1.y) + v[3] * bfhi(gb.y));
;                 WIDE_STORE((u16*)(ws + OFF_RB + 128 * MiB), DM, 0, o);
	v_lshlrev_b32_e32 v168, 16, v234
	v_and_b32_e32 v169, 0xffff0000, v234
	v_lshlrev_b32_e32 v176, 16, v236
	v_and_b32_e32 v177, 0xffff0000, v236
	v_pk_fma_f32 v[104:105], v[104:105], v[168:169], v[176:177]
	v_lshlrev_b32_e32 v170, 16, v235
	v_and_b32_e32 v171, 0xffff0000, v235
	v_lshlrev_b32_e32 v178, 16, v237
	v_and_b32_e32 v179, 0xffff0000, v237
	v_pk_fma_f32 v[106:107], v[106:107], v[170:171], v[178:179]
	global_load_dwordx2 v[234:235], v137, s[28:29] offset:64
	global_load_dwordx2 v[236:237], v141, s[4:5] offset:64
	s_waitcnt vmcnt(16)
	v_lshlrev_b32_e32 v168, 16, v238
	v_and_b32_e32 v169, 0xffff0000, v238
	v_lshlrev_b32_e32 v176, 16, v240
	v_and_b32_e32 v177, 0xffff0000, v240
	v_pk_fma_f32 v[96:97], v[96:97], v[168:169], v[176:177]
	v_lshlrev_b32_e32 v170, 16, v239
	v_and_b32_e32 v171, 0xffff0000, v239
	v_lshlrev_b32_e32 v178, 16, v241
	v_and_b32_e32 v179, 0xffff0000, v241
	v_pk_fma_f32 v[98:99], v[98:99], v[170:171], v[178:179]
	global_load_dwordx2 v[238:239], v137, s[28:29] offset:96
	global_load_dwordx2 v[240:241], v141, s[4:5] offset:96
	s_nop 0
	v_cvt_pk_bf16_f32 v120, v120, v121
	v_cvt_pk_bf16_f32 v121, v122, v123
	v_cvt_pk_bf16_f32 v122, v112, v113
	v_cvt_pk_bf16_f32 v123, v114, v115
	v_cvt_pk_bf16_f32 v104, v104, v105
	v_cvt_pk_bf16_f32 v105, v106, v107
	v_cvt_pk_bf16_f32 v106, v96, v97
	v_cvt_pk_bf16_f32 v107, v98, v99
	s_nop 1
	v_permlane16_swap_b32_e32 v120, v122
	v_permlane16_swap_b32_e32 v121, v123
	v_permlane16_swap_b32_e32 v104, v106
	v_permlane16_swap_b32_e32 v105, v107
	global_store_dwordx4 v191, v[120:123], s[72:73] offset:0
	global_store_dwordx4 v191, v[104:107], s[72:73] offset:64
	s_waitcnt vmcnt(18)
	v_lshlrev_b32_e32 v168, 16, v210
	v_and_b32_e32 v169, 0xffff0000, v210
	v_lshlrev_b32_e32 v176, 16, v212
	v_and_b32_e32 v177, 0xffff0000, v212
	v_pk_fma_f32 v[92:93], v[92:93], v[168:169], v[176:177]
	v_lshlrev_b32_e32 v170, 16, v211
	v_and_b32_e32 v171, 0xffff0000, v211
	v_lshlrev_b32_e32 v178, 16, v213
	v_and_b32_e32 v179, 0xffff0000, v213
	v_pk_fma_f32 v[94:95], v[94:95], v[170:171], v[178:179]
	global_load_dwordx2 v[210:211], v134, s[28:29] offset:256
	global_load_dwordx2 v[212:213], v138, s[4:5] offset:256
	s_waitcnt vmcnt(18)
	v_lshlrev_b32_e32 v168, 16, v214
	v_and_b32_e32 v169, 0xffff0000, v214
	v_lshlrev_b32_e32 v176, 16, v216
	v_and_b32_e32 v177, 0xffff0000, v216
	v_pk_fma_f32 v[84:85], v[84:85], v[168:169], v[176:177]
	v_lshlrev_b32_e32 v170, 16, v215
	v_and_b32_e32 v171, 0xffff0000, v215
	v_lshlrev_b32_e32 v178, 16, v217
	v_and_b32_e32 v179, 0xffff0000, v217
	v_pk_fma_f32 v[86:87], v[86:87], v[170:171], v[178:179]
	global_load_dwordx2 v[214:215], v134, s[28:29] offset:288
	global_load_dwordx2 v[216:217], v138, s[4:5] offset:288
	s_waitcnt vmcnt(18)
	v_lshlrev_b32_e32 v168, 16, v218
	v_and_b32_e32 v169, 0xffff0000, v218
	v_lshlrev_b32_e32 v176, 16, v220
	v_and_b32_e32 v177, 0xffff0000, v220
	v_pk_fma_f32 v[76:77], v[76:77], v[168:169], v[176:177]
	v_lshlrev_b32_e32 v170, 16, v219
	v_and_b32_e32 v171, 0xffff0000, v219
	v_lshlrev_b32_e32 v178, 16, v221
	v_and_b32_e32 v179, 0xffff0000, v221
	v_pk_fma_f32 v[78:79], v[78:79], v[170:171], v[178:179]
	global_load_dwordx2 v[218:219], v134, s[28:29] offset:320
	global_load_dwordx2 v[220:221], v138, s[4:5] offset:320
	s_waitcnt vmcnt(18)
	v_lshlrev_b32_e32 v168, 16, v222
	v_and_b32_e32 v169, 0xffff0000, v222
	v_lshlrev_b32_e32 v176, 16, v224
	v_and_b32_e32 v177, 0xffff0000, v224
	v_pk_fma_f32 v[68:69], v[68:69], v[168:169], v[176:177]
	v_lshlrev_b32_e32 v170, 16, v223
	v_and_b32_e32 v171, 0xffff0000, v223
	v_lshlrev_b32_e32 v178, 16, v225
	v_and_b32_e32 v179, 0xffff0000, v225
	v_pk_fma_f32 v[70:71], v[70:71], v[170:171], v[178:179]
	global_load_dwordx2 v[222:223], v134, s[28:29] offset:352
	global_load_dwordx2 v[224:225], v138, s[4:5] offset:352
	s_nop 0
	v_cvt_pk_bf16_f32 v92, v92, v93
	v_cvt_pk_bf16_f32 v93, v94, v95
	v_cvt_pk_bf16_f32 v94, v84, v85
	v_cvt_pk_bf16_f32 v95, v86, v87
	v_cvt_pk_bf16_f32 v76, v76, v77
	v_cvt_pk_bf16_f32 v77, v78, v79
	v_cvt_pk_bf16_f32 v78, v68, v69
	v_cvt_pk_bf16_f32 v79, v70, v71
	s_nop 1
	v_permlane16_swap_b32_e32 v92, v94
	v_permlane16_swap_b32_e32 v93, v95
	v_permlane16_swap_b32_e32 v76, v78
	v_permlane16_swap_b32_e32 v77, v79
	global_store_dwordx4 v192, v[92:95], s[72:73] offset:0
	global_store_dwordx4 v192, v[76:79], s[72:73] offset:64
	s_waitcnt vmcnt(18)
	v_lshlrev_b32_e32 v168, 16, v226
	v_and_b32_e32 v169, 0xffff0000, v226
	v_lshlrev_b32_e32 v176, 16, v228
	v_and_b32_e32 v177, 0xffff0000, v228
	v_pk_fma_f32 v[88:89], v[88:89], v[168:169], v[176:177]
	v_lshlrev_b32_e32 v170, 16, v227
	v_and_b32_e32 v171, 0xffff0000, v227
	v_lshlrev_b32_e32 v178, 16, v229
	v_and_b32_e32 v179, 0xffff0000, v229
	v_pk_fma_f32 v[90:91], v[90:91], v[170:171], v[178:179]
	global_load_dwordx2 v[226:227], v135, s[28:29] offset:256
	global_load_dwordx2 v[228:229], v139, s[4:5] offset:256
	s_waitcnt vmcnt(18)
	v_lshlrev_b32_e32 v168, 16, v230
	v_and_b32_e32 v169, 0xffff0000, v230
	v_lshlrev_b32_e32 v176, 16, v232
	v_and_b32_e32 v177, 0xffff0000, v232
	v_pk_fma_f32 v[80:81], v[80:81], v[168:169], v[176:177]
	v_lshlrev_b32_e32 v170, 16, v231
	v_and_b32_e32 v171, 0xffff0000, v231
	v_lshlrev_b32_e32 v178, 16, v233
	v_and_b32_e32 v179, 0xffff0000, v233
	v_pk_fma_f32 v[82:83], v[82:83], v[170:171], v[178:179]
	global_load_dwordx2 v[230:231], v135, s[28:29] offset:288
	global_load_dwordx2 v[232:233], v139, s[4:5] offset:288
	s_waitcnt vmcnt(18)
; __device__ __forceinline__ float bflo(unsigned u) { return __uint_as_float(u << 16); }
; __device__ __forceinline__ float bfhi(unsigned u) { return __uint_as_float(u & 0xffff0000u); }
; #define WIDE_STORE(BASE, LD, COFF, O) do { if ((m & 1) == 0) opend[n] = (O); \
;                 else *(uint4*)((BASE) + (size_t)tok * (LD) + (ncw - (COFF))) = swap_pair(opend[n], (O)); } while (0)
; __device__ __forceinline__ uint4 swap_pair(const uint2 a, const uint2 b) {
;   const auto rx = __builtin_amdgcn_permlane16_swap(a.x, b.x, false, false);
;   const auto ry = __builtin_amdgcn_permlane16_swap(a.y, b.y, false, false);
;   return make_uint4(rx[0], ry[0], rx[1], ry[1]);
; }
;     ...
;               } else if (MODE == 6) {
;                 const u16* gate = (const u16*)outp;
;                 uint2 gb = *(const uint2*)(gate + (size_t)tok * 4096 + 2048 + nc);
;                 const uint2 p1 = *(const uint2*)((const u16*)(ws + OFF_YB) + (size_t)tok * DM + nc);
;                 uint2 o;
;                 o.x = pk2(bflo(p1.x) + v[0] * bflo(gb.x), bfhi(p1.x) + v[1] * bfhi(gb.x));
;                 o.y = pk2(bflo(p1.y) + v[2] * bflo(gb.y), bfhi(p1.y) + v[3] * bfhi(gb.y));
;                 WIDE_STORE((u16*)(ws + OFF_RB + 128 * MiB), DM, 0, o);
	v_lshlrev_b32_e32 v168, 16, v234
	v_and_b32_e32 v169, 0xffff0000, v234
	v_lshlrev_b32_e32 v176, 16, v236
	v_and_b32_e32 v177, 0xffff0000, v236
	v_pk_fma_f32 v[72:73], v[72:73], v[168:169], v[176:177]
	v_lshlrev_b32_e32 v170, 16, v235
	v_and_b32_e32 v171, 0xffff0000, v235
	v_lshlrev_b32_e32 v178, 16, v237
	v_and_b32_e32 v179, 0xffff0000, v237
	v_pk_fma_f32 v[74:75], v[74:75], v[170:171], v[178:179]
	global_load_dwordx2 v[234:235], v135, s[28:29] offset:320
	global_load_dwordx2 v[236:237], v139, s[4:5] offset:320
	s_waitcnt vmcnt(18)
	v_lshlrev_b32_e32 v168, 16, v238
	v_and_b32_e32 v169, 0xffff0000, v238
	v_lshlrev_b32_e32 v176, 16, v240
	v_and_b32_e32 v177, 0xffff0000, v240
	v_pk_fma_f32 v[64:65], v[64:65], v[168:169], v[176:177]
	v_lshlrev_b32_e32 v170, 16, v239
	v_and_b32_e32 v171, 0xffff0000, v239
	v_lshlrev_b32_e32 v178, 16, v241
	v_and_b32_e32 v179, 0xffff0000, v241
	v_pk_fma_f32 v[66:67], v[66:67], v[170:171], v[178:179]
	global_load_dwordx2 v[238:239], v135, s[28:29] offset:352
	global_load_dwordx2 v[240:241], v139, s[4:5] offset:352
	s_nop 0
	v_cvt_pk_bf16_f32 v88, v88, v89
	v_cvt_pk_bf16_f32 v89, v90, v91
	v_cvt_pk_bf16_f32 v90, v80, v81
	v_cvt_pk_bf16_f32 v91, v82, v83
	v_cvt_pk_bf16_f32 v72, v72, v73
	v_cvt_pk_bf16_f32 v73, v74, v75
	v_cvt_pk_bf16_f32 v74, v64, v65
	v_cvt_pk_bf16_f32 v75, v66, v67
	s_nop 1
	v_permlane16_swap_b32_e32 v88, v90
	v_permlane16_swap_b32_e32 v89, v91
	v_permlane16_swap_b32_e32 v72, v74
	v_permlane16_swap_b32_e32 v73, v75
	global_store_dwordx4 v193, v[88:91], s[72:73] offset:0
	global_store_dwordx4 v193, v[72:75], s[72:73] offset:64
	s_waitcnt vmcnt(18)
	v_lshlrev_b32_e32 v168, 16, v210
	v_and_b32_e32 v169, 0xffff0000, v210
	v_lshlrev_b32_e32 v176, 16, v212
	v_and_b32_e32 v177, 0xffff0000, v212
	v_pk_fma_f32 v[60:61], v[60:61], v[168:169], v[176:177]
	v_lshlrev_b32_e32 v170, 16, v211
	v_and_b32_e32 v171, 0xffff0000, v211
	v_lshlrev_b32_e32 v178, 16, v213
	v_and_b32_e32 v179, 0xffff0000, v213
	v_pk_fma_f32 v[62:63], v[62:63], v[170:171], v[178:179]
	global_load_dwordx2 v[210:211], v136, s[28:29] offset:256
	global_load_dwordx2 v[212:213], v140, s[4:5] offset:256
	s_waitcnt vmcnt(18)
	v_lshlrev_b32_e32 v168, 16, v214
	v_and_b32_e32 v169, 0xffff0000, v214
	v_lshlrev_b32_e32 v176, 16, v216
	v_and_b32_e32 v177, 0xffff0000, v216
	v_pk_fma_f32 v[52:53], v[52:53], v[168:169], v[176:177]
	v_lshlrev_b32_e32 v170, 16, v215
	v_and_b32_e32 v171, 0xffff0000, v215
	v_lshlrev_b32_e32 v178, 16, v217
	v_and_b32_e32 v179, 0xffff0000, v217
	v_pk_fma_f32 v[54:55], v[54:55], v[170:171], v[178:179]
	global_load_dwordx2 v[214:215], v136, s[28:29] offset:288
	global_load_dwordx2 v[216:217], v140, s[4:5] offset:288
	s_waitcnt vmcnt(18)
	v_lshlrev_b32_e32 v168, 16, v218
	v_and_b32_e32 v169, 0xffff0000, v218
	v_lshlrev_b32_e32 v176, 16, v220
	v_and_b32_e32 v177, 0xffff0000, v220
	v_pk_fma_f32 v[44:45], v[44:45], v[168:169], v[176:177]
	v_lshlrev_b32_e32 v170, 16, v219
	v_and_b32_e32 v171, 0xffff0000, v219
	v_lshlrev_b32_e32 v178, 16, v221
	v_and_b32_e32 v179, 0xffff0000, v221
	v_pk_fma_f32 v[46:47], v[46:47], v[170:171], v[178:179]
	global_load_dwordx2 v[218:219], v136, s[28:29] offset:320
	global_load_dwordx2 v[220:221], v140, s[4:5] offset:320
	s_waitcnt vmcnt(18)
	v_lshlrev_b32_e32 v168, 16, v222
	v_and_b32_e32 v169, 0xffff0000, v222
	v_lshlrev_b32_e32 v176, 16, v224
	v_and_b32_e32 v177, 0xffff0000, v224
	v_pk_fma_f32 v[36:37], v[36:37], v[168:169], v[176:177]
	v_lshlrev_b32_e32 v170, 16, v223
	v_and_b32_e32 v171, 0xffff0000, v223
	v_lshlrev_b32_e32 v178, 16, v225
	v_and_b32_e32 v179, 0xffff0000, v225
	v_pk_fma_f32 v[38:39], v[38:39], v[170:171], v[178:179]
	global_load_dwordx2 v[222:223], v136, s[28:29] offset:352
	global_load_dwordx2 v[224:225], v140, s[4:5] offset:352
	s_nop 0
	v_cvt_pk_bf16_f32 v60, v60, v61
	v_cvt_pk_bf16_f32 v61, v62, v63
	v_cvt_pk_bf16_f32 v62, v52, v53
	v_cvt_pk_bf16_f32 v63, v54, v55
	v_cvt_pk_bf16_f32 v44, v44, v45
	v_cvt_pk_bf16_f32 v45, v46, v47
	v_cvt_pk_bf16_f32 v46, v36, v37
	v_cvt_pk_bf16_f32 v47, v38, v39
	s_nop 1
	v_permlane16_swap_b32_e32 v60, v62
	v_permlane16_swap_b32_e32 v61, v63
	v_permlane16_swap_b32_e32 v44, v46
	v_permlane16_swap_b32_e32 v45, v47
	global_store_dwordx4 v190, v[60:63], s[72:73] offset:256
	global_store_dwordx4 v190, v[44:47], s[72:73] offset:320
	s_waitcnt vmcnt(18)
	v_lshlrev_b32_e32 v168, 16, v226
	v_and_b32_e32 v169, 0xffff0000, v226
	v_lshlrev_b32_e32 v176, 16, v228
	v_and_b32_e32 v177, 0xffff0000, v228
	v_pk_fma_f32 v[56:57], v[56:57], v[168:169], v[176:177]
	v_lshlrev_b32_e32 v170, 16, v227
	v_and_b32_e32 v171, 0xffff0000, v227
	v_lshlrev_b32_e32 v178, 16, v229
	v_and_b32_e32 v179, 0xffff0000, v229
	v_pk_fma_f32 v[58:59], v[58:59], v[170:171], v[178:179]
	global_load_dwordx2 v[226:227], v137, s[28:29] offset:256
	global_load_dwordx2 v[228:229], v141, s[4:5] offset:256
	s_waitcnt vmcnt(18)
	v_lshlrev_b32_e32 v168, 16, v230
	v_and_b32_e32 v169, 0xffff0000, v230
	v_lshlrev_b32_e32 v176, 16, v232
	v_and_b32_e32 v177, 0xffff0000, v232
	v_pk_fma_f32 v[48:49], v[48:49], v[168:169], v[176:177]
	v_lshlrev_b32_e32 v170, 16, v231
	v_and_b32_e32 v171, 0xffff0000, v231
	v_lshlrev_b32_e32 v178, 16, v233
	v_and_b32_e32 v179, 0xffff0000, v233
	v_pk_fma_f32 v[50:51], v[50:51], v[170:171], v[178:179]
	global_load_dwordx2 v[230:231], v137, s[28:29] offset:288
	global_load_dwordx2 v[232:233], v141, s[4:5] offset:288
	s_waitcnt vmcnt(18)
; __device__ __forceinline__ float bflo(unsigned u) { return __uint_as_float(u << 16); }
; __device__ __forceinline__ float bfhi(unsigned u) { return __uint_as_float(u & 0xffff0000u); }
; #define WIDE_STORE(BASE, LD, COFF, O) do { if ((m & 1) == 0) opend[n] = (O); \
;                 else *(uint4*)((BASE) + (size_t)tok * (LD) + (ncw - (COFF))) = swap_pair(opend[n], (O)); } while (0)
; __device__ __forceinline__ uint4 swap_pair(const uint2 a, const uint2 b) {
;   const auto rx = __builtin_amdgcn_permlane16_swap(a.x, b.x, false, false);
;   const auto ry = __builtin_amdgcn_permlane16_swap(a.y, b.y, false, false);
;   return make_uint4(rx[0], ry[0], rx[1], ry[1]);
; }
;     ...
;               } else if (MODE == 6) {
;                 const u16* gate = (const u16*)outp;
;                 uint2 gb = *(const uint2*)(gate + (size_t)tok * 4096 + 2048 + nc);
;                 const uint2 p1 = *(const uint2*)((const u16*)(ws + OFF_YB) + (size_t)tok * DM + nc);
;                 uint2 o;
;                 o.x = pk2(bflo(p1.x) + v[0] * bflo(gb.x), bfhi(p1.x) + v[1] * bfhi(gb.x));
;                 o.y = pk2(bflo(p1.y) + v[2] * bflo(gb.y), bfhi(p1.y) + v[3] * bfhi(gb.y));
;                 WIDE_STORE((u16*)(ws + OFF_RB + 128 * MiB), DM, 0, o);
	v_lshlrev_b32_e32 v168, 16, v234
	v_and_b32_e32 v169, 0xffff0000, v234
	v_lshlrev_b32_e32 v176, 16, v236
	v_and_b32_e32 v177, 0xffff0000, v236
	v_pk_fma_f32 v[40:41], v[40:41], v[168:169], v[176:177]
	v_lshlrev_b32_e32 v170, 16, v235
	v_and_b32_e32 v171, 0xffff0000, v235
	v_lshlrev_b32_e32 v178, 16, v237
	v_and_b32_e32 v179, 0xffff0000, v237
	v_pk_fma_f32 v[42:43], v[42:43], v[170:171], v[178:179]
	global_load_dwordx2 v[234:235], v137, s[28:29] offset:320
	global_load_dwordx2 v[236:237], v141, s[4:5] offset:320
	s_waitcnt vmcnt(18)
	v_lshlrev_b32_e32 v168, 16, v238
	v_and_b32_e32 v169, 0xffff0000, v238
	v_lshlrev_b32_e32 v176, 16, v240
	v_and_b32_e32 v177, 0xffff0000, v240
	v_pk_fma_f32 v[32:33], v[32:33], v[168:169], v[176:177]
	v_lshlrev_b32_e32 v170, 16, v239
	v_and_b32_e32 v171, 0xffff0000, v239
	v_lshlrev_b32_e32 v178, 16, v241
	v_and_b32_e32 v179, 0xffff0000, v241
	v_pk_fma_f32 v[34:35], v[34:35], v[170:171], v[178:179]
	global_load_dwordx2 v[238:239], v137, s[28:29] offset:352
	global_load_dwordx2 v[240:241], v141, s[4:5] offset:352
	s_nop 0
	v_cvt_pk_bf16_f32 v56, v56, v57
	v_cvt_pk_bf16_f32 v57, v58, v59
	v_cvt_pk_bf16_f32 v58, v48, v49
	v_cvt_pk_bf16_f32 v59, v50, v51
	v_cvt_pk_bf16_f32 v40, v40, v41
	v_cvt_pk_bf16_f32 v41, v42, v43
	v_cvt_pk_bf16_f32 v42, v32, v33
	v_cvt_pk_bf16_f32 v43, v34, v35
	s_nop 1
	v_permlane16_swap_b32_e32 v56, v58
	v_permlane16_swap_b32_e32 v57, v59
	v_permlane16_swap_b32_e32 v40, v42
	v_permlane16_swap_b32_e32 v41, v43
	global_store_dwordx4 v191, v[56:59], s[72:73] offset:256
	global_store_dwordx4 v191, v[40:43], s[72:73] offset:320
	s_waitcnt vmcnt(18)
	v_lshlrev_b32_e32 v168, 16, v210
	v_and_b32_e32 v169, 0xffff0000, v210
	v_lshlrev_b32_e32 v176, 16, v212
	v_and_b32_e32 v177, 0xffff0000, v212
	v_pk_fma_f32 v[28:29], v[28:29], v[168:169], v[176:177]
	v_lshlrev_b32_e32 v170, 16, v211
	v_and_b32_e32 v171, 0xffff0000, v211
	v_lshlrev_b32_e32 v178, 16, v213
	v_and_b32_e32 v179, 0xffff0000, v213
	v_pk_fma_f32 v[30:31], v[30:31], v[170:171], v[178:179]
	s_waitcnt vmcnt(16)
	v_lshlrev_b32_e32 v168, 16, v214
	v_and_b32_e32 v169, 0xffff0000, v214
	v_lshlrev_b32_e32 v176, 16, v216
	v_and_b32_e32 v177, 0xffff0000, v216
	v_pk_fma_f32 v[20:21], v[20:21], v[168:169], v[176:177]
	v_lshlrev_b32_e32 v170, 16, v215
	v_and_b32_e32 v171, 0xffff0000, v215
	v_lshlrev_b32_e32 v178, 16, v217
	v_and_b32_e32 v179, 0xffff0000, v217
	v_pk_fma_f32 v[22:23], v[22:23], v[170:171], v[178:179]
	s_waitcnt vmcnt(14)
	v_lshlrev_b32_e32 v168, 16, v218
	v_and_b32_e32 v169, 0xffff0000, v218
	v_lshlrev_b32_e32 v176, 16, v220
	v_and_b32_e32 v177, 0xffff0000, v220
	v_pk_fma_f32 v[12:13], v[12:13], v[168:169], v[176:177]
	v_lshlrev_b32_e32 v170, 16, v219
	v_and_b32_e32 v171, 0xffff0000, v219
	v_lshlrev_b32_e32 v178, 16, v221
	v_and_b32_e32 v179, 0xffff0000, v221
	v_pk_fma_f32 v[14:15], v[14:15], v[170:171], v[178:179]
	s_waitcnt vmcnt(12)
	v_lshlrev_b32_e32 v168, 16, v222
	v_and_b32_e32 v169, 0xffff0000, v222
	v_lshlrev_b32_e32 v176, 16, v224
	v_and_b32_e32 v177, 0xffff0000, v224
	v_pk_fma_f32 v[4:5], v[4:5], v[168:169], v[176:177]
	v_lshlrev_b32_e32 v170, 16, v223
	v_and_b32_e32 v171, 0xffff0000, v223
	v_lshlrev_b32_e32 v178, 16, v225
	v_and_b32_e32 v179, 0xffff0000, v225
	v_pk_fma_f32 v[6:7], v[6:7], v[170:171], v[178:179]
	s_nop 0
	v_cvt_pk_bf16_f32 v28, v28, v29
	v_cvt_pk_bf16_f32 v29, v30, v31
	v_cvt_pk_bf16_f32 v30, v20, v21
	v_cvt_pk_bf16_f32 v31, v22, v23
	v_cvt_pk_bf16_f32 v12, v12, v13
	v_cvt_pk_bf16_f32 v13, v14, v15
	v_cvt_pk_bf16_f32 v14, v4, v5
	v_cvt_pk_bf16_f32 v15, v6, v7
	s_nop 1
	v_permlane16_swap_b32_e32 v28, v30
	v_permlane16_swap_b32_e32 v29, v31
	v_permlane16_swap_b32_e32 v12, v14
	v_permlane16_swap_b32_e32 v13, v15
	global_store_dwordx4 v192, v[28:31], s[72:73] offset:256
	global_store_dwordx4 v192, v[12:15], s[72:73] offset:320
	s_waitcnt vmcnt(10)
	v_lshlrev_b32_e32 v168, 16, v226
	v_and_b32_e32 v169, 0xffff0000, v226
	v_lshlrev_b32_e32 v176, 16, v228
	v_and_b32_e32 v177, 0xffff0000, v228
	v_pk_fma_f32 v[24:25], v[24:25], v[168:169], v[176:177]
	v_lshlrev_b32_e32 v170, 16, v227
	v_and_b32_e32 v171, 0xffff0000, v227
	v_lshlrev_b32_e32 v178, 16, v229
	v_and_b32_e32 v179, 0xffff0000, v229
	v_pk_fma_f32 v[26:27], v[26:27], v[170:171], v[178:179]
	s_waitcnt vmcnt(8)
	v_lshlrev_b32_e32 v168, 16, v230
	v_and_b32_e32 v169, 0xffff0000, v230
	v_lshlrev_b32_e32 v176, 16, v232
	v_and_b32_e32 v177, 0xffff0000, v232
	v_pk_fma_f32 v[16:17], v[16:17], v[168:169], v[176:177]
	v_lshlrev_b32_e32 v170, 16, v231
	v_and_b32_e32 v171, 0xffff0000, v231
	v_lshlrev_b32_e32 v178, 16, v233
	v_and_b32_e32 v179, 0xffff0000, v233
	v_pk_fma_f32 v[18:19], v[18:19], v[170:171], v[178:179]
	s_waitcnt vmcnt(6)
; __device__ __forceinline__ float bflo(unsigned u) { return __uint_as_float(u << 16); }
; __device__ __forceinline__ float bfhi(unsigned u) { return __uint_as_float(u & 0xffff0000u); }
; #define WIDE_STORE(BASE, LD, COFF, O) do { if ((m & 1) == 0) opend[n] = (O); \
;                 else *(uint4*)((BASE) + (size_t)tok * (LD) + (ncw - (COFF))) = swap_pair(opend[n], (O)); } while (0)
;     ...
; #pragma unroll
;     for (int a = 0; a < 2; ++a)
; #pragma unroll
;       for (int b = 0; b < 2; ++b)
; #pragma unroll
;         for (int m = 0; m < 4; ++m)
; #pragma unroll
;           for (int n = 0; n < 2; ++n) acc[a][b][m][n] = f32x4{0.f, 0.f, 0.f, 0.f};
;     ...
;               } else if (MODE == 6) {
;                 const u16* gate = (const u16*)outp;
;                 uint2 gb = *(const uint2*)(gate + (size_t)tok * 4096 + 2048 + nc);
;                 const uint2 p1 = *(const uint2*)((const u16*)(ws + OFF_YB) + (size_t)tok * DM + nc);
;                 uint2 o;
;                 o.x = pk2(bflo(p1.x) + v[0] * bflo(gb.x), bfhi(p1.x) + v[1] * bfhi(gb.x));
;                 o.y = pk2(bflo(p1.y) + v[2] * bflo(gb.y), bfhi(p1.y) + v[3] * bfhi(gb.y));
;                 WIDE_STORE((u16*)(ws + OFF_RB + 128 * MiB), DM, 0, o);
	v_lshlrev_b32_e32 v168, 16, v234
	v_and_b32_e32 v169, 0xffff0000, v234
	v_lshlrev_b32_e32 v176, 16, v236
	v_and_b32_e32 v177, 0xffff0000, v236
	v_pk_fma_f32 v[8:9], v[8:9], v[168:169], v[176:177]
	v_lshlrev_b32_e32 v170, 16, v235
	v_and_b32_e32 v171, 0xffff0000, v235
	v_lshlrev_b32_e32 v178, 16, v237
	v_and_b32_e32 v179, 0xffff0000, v237
	v_pk_fma_f32 v[10:11], v[10:11], v[170:171], v[178:179]
	s_waitcnt vmcnt(4)
	v_lshlrev_b32_e32 v168, 16, v238
	v_and_b32_e32 v169, 0xffff0000, v238
	v_lshlrev_b32_e32 v176, 16, v240
	v_and_b32_e32 v177, 0xffff0000, v240
	v_pk_fma_f32 v[0:1], v[0:1], v[168:169], v[176:177]
	v_lshlrev_b32_e32 v170, 16, v239
	v_and_b32_e32 v171, 0xffff0000, v239
	v_lshlrev_b32_e32 v178, 16, v241
	v_and_b32_e32 v179, 0xffff0000, v241
	v_pk_fma_f32 v[2:3], v[2:3], v[170:171], v[178:179]
	s_nop 0
	v_cvt_pk_bf16_f32 v24, v24, v25
	v_cvt_pk_bf16_f32 v25, v26, v27
	v_cvt_pk_bf16_f32 v26, v16, v17
	v_cvt_pk_bf16_f32 v27, v18, v19
	v_cvt_pk_bf16_f32 v8, v8, v9
	v_cvt_pk_bf16_f32 v9, v10, v11
	v_cvt_pk_bf16_f32 v10, v0, v1
	v_cvt_pk_bf16_f32 v11, v2, v3
	s_nop 1
	v_permlane16_swap_b32_e32 v24, v26
	v_permlane16_swap_b32_e32 v25, v27
	v_permlane16_swap_b32_e32 v8, v10
	v_permlane16_swap_b32_e32 v9, v11
	global_store_dwordx4 v193, v[24:27], s[72:73] offset:256
	global_store_dwordx4 v193, v[8:11], s[72:73] offset:320
	s_and_b64 s[0:1], s[56:57], s[8:9]
	s_andn2_b64 vcc, exec, s[0:1]
	s_nop 1
	v_mov_b32_e32 v0, 0
	v_mov_b32_e32 v1, v0
	v_mov_b32_e32 v2, v0
	v_mov_b32_e32 v3, v0
	v_mov_b32_e32 v4, v0
	v_mov_b32_e32 v5, v0
	v_mov_b32_e32 v6, v0
	v_mov_b32_e32 v7, v0
	v_mov_b32_e32 v8, v0
	v_mov_b32_e32 v9, v0
	v_mov_b32_e32 v10, v0
	v_mov_b32_e32 v11, v0
	v_mov_b32_e32 v12, v0
	v_mov_b32_e32 v13, v0
	v_mov_b32_e32 v14, v0
	v_mov_b32_e32 v15, v0
	v_mov_b32_e32 v16, v0
	v_mov_b32_e32 v17, v0
	v_mov_b32_e32 v18, v0
	v_mov_b32_e32 v19, v0
	v_mov_b32_e32 v20, v0
	v_mov_b32_e32 v21, v0
	v_mov_b32_e32 v22, v0
	v_mov_b32_e32 v23, v0
	v_mov_b32_e32 v24, v0
	v_mov_b32_e32 v25, v0
	v_mov_b32_e32 v26, v0
	v_mov_b32_e32 v27, v0
	v_mov_b32_e32 v28, v0
	v_mov_b32_e32 v29, v0
	v_mov_b32_e32 v30, v0
	v_mov_b32_e32 v31, v0
	v_mov_b32_e32 v32, v0
	v_mov_b32_e32 v33, v0
	v_mov_b32_e32 v34, v0
	v_mov_b32_e32 v35, v0
	v_mov_b32_e32 v36, v0
	v_mov_b32_e32 v37, v0
	v_mov_b32_e32 v38, v0
	v_mov_b32_e32 v39, v0
	v_mov_b32_e32 v40, v0
	v_mov_b32_e32 v41, v0
	v_mov_b32_e32 v42, v0
	v_mov_b32_e32 v43, v0
	v_mov_b32_e32 v44, v0
	v_mov_b32_e32 v45, v0
	v_mov_b32_e32 v46, v0
	v_mov_b32_e32 v47, v0
	v_mov_b32_e32 v48, v0
	v_mov_b32_e32 v49, v0
	v_mov_b32_e32 v50, v0
	v_mov_b32_e32 v51, v0
	v_mov_b32_e32 v52, v0
	v_mov_b32_e32 v53, v0
	v_mov_b32_e32 v54, v0
	v_mov_b32_e32 v55, v0
	v_mov_b32_e32 v56, v0
	v_mov_b32_e32 v57, v0
	v_mov_b32_e32 v58, v0
	v_mov_b32_e32 v59, v0
	v_mov_b32_e32 v60, v0
	v_mov_b32_e32 v61, v0
	v_mov_b32_e32 v62, v0
	v_mov_b32_e32 v63, v0
	v_mov_b32_e32 v64, v0
	v_mov_b32_e32 v65, v0
	v_mov_b32_e32 v66, v0
	v_mov_b32_e32 v67, v0
	v_mov_b32_e32 v68, v0
	v_mov_b32_e32 v69, v0
	v_mov_b32_e32 v70, v0
	v_mov_b32_e32 v71, v0
	v_mov_b32_e32 v72, v0
	v_mov_b32_e32 v73, v0
	v_mov_b32_e32 v74, v0
	v_mov_b32_e32 v75, v0
	v_mov_b32_e32 v76, v0
	v_mov_b32_e32 v77, v0
	v_mov_b32_e32 v78, v0
	v_mov_b32_e32 v79, v0
	v_mov_b32_e32 v80, v0
	v_mov_b32_e32 v81, v0
	v_mov_b32_e32 v82, v0
	v_mov_b32_e32 v83, v0
	v_mov_b32_e32 v84, v0
	v_mov_b32_e32 v85, v0
	v_mov_b32_e32 v86, v0
	v_mov_b32_e32 v87, v0
	v_mov_b32_e32 v88, v0
	v_mov_b32_e32 v89, v0
	v_mov_b32_e32 v90, v0
	v_mov_b32_e32 v91, v0
	v_mov_b32_e32 v92, v0
	v_mov_b32_e32 v93, v0
	v_mov_b32_e32 v94, v0
	v_mov_b32_e32 v95, v0
	v_mov_b32_e32 v96, v0
	v_mov_b32_e32 v97, v0
	v_mov_b32_e32 v98, v0
	v_mov_b32_e32 v99, v0
	v_mov_b32_e32 v100, v0
	v_mov_b32_e32 v101, v0
	v_mov_b32_e32 v102, v0
	v_mov_b32_e32 v103, v0
	v_mov_b32_e32 v104, v0
	v_mov_b32_e32 v105, v0
	v_mov_b32_e32 v106, v0
	v_mov_b32_e32 v107, v0
	v_mov_b32_e32 v108, v0
	v_mov_b32_e32 v109, v0
	v_mov_b32_e32 v110, v0
	v_mov_b32_e32 v111, v0
	v_mov_b32_e32 v112, v0
	v_mov_b32_e32 v113, v0
	v_mov_b32_e32 v114, v0
	v_mov_b32_e32 v115, v0
	v_mov_b32_e32 v116, v0
	v_mov_b32_e32 v117, v0
	v_mov_b32_e32 v118, v0
	v_mov_b32_e32 v119, v0
	v_mov_b32_e32 v120, v0
	v_mov_b32_e32 v121, v0
	v_mov_b32_e32 v122, v0
	v_mov_b32_e32 v123, v0
	v_mov_b32_e32 v124, v0
	v_mov_b32_e32 v125, v0
	v_mov_b32_e32 v126, v0
	v_mov_b32_e32 v127, v0
	s_waitcnt vmcnt(0)
	s_cbranch_vccnz .LBB0_819
	s_barrier
	s_branch .LBB0_819

; #define STAGE(P_, BASE, br, kt) do { const u16* _gb = (BASE) + (long)(br) * K + (long)(kt) * BK; \
;     _Pragma("unroll") for (int _i = 0; _i < 2; ++_i) { \
;       __builtin_amdgcn_global_load_lds((const unsigned*)(_gb + (long)_i * 64 * K + lane_off), \
;         (unsigned*)((char*)(P_) + lds_wbase + _i * 8192), 16, 0, 0); } } while (0)
; #define WAIT_V(n) asm volatile("s_waitcnt vmcnt(" #n ")" ::: "memory")
; #define BAR __builtin_amdgcn_s_barrier()
; __device__ __forceinline__ const float* pass_xin(const Params& P, int pass) {
;   const float* base = (pass == 0) ? P.x_prompt : P.x_sample;
;   const unsigned off = (pass == 0) ? 0u : (unsigned)(pass - 1) * (unsigned)(PT * DM);
;   return lptr(base + off);
; }
; template <int PRE> ...
;     ...
;   const int wid = wvi, lane = tid & 63, wr = wid >> 2, wc = wid & 3, fr = lane & 15, fq = lane >> 4;
;   bf16x8 At[4][2], B0[2][2], B1[2][2];
;   const int nt = K / BK;
;   const unsigned lds_wbase = wid * 1024;
;   unsigned lane_off;
;   { int _r, _c; stage_rc(tid * 16, _r, _c); lane_off = (unsigned)(_r * K + _c); }
;     ...
;   if (PRE == 2) {
;     STAGE(SB(0, 0), Bt, bcol, 0); STAGE(SA(0, 0), A, brow, 0);
;     STAGE(SB(0, 1), Bt, bcol + HALF, 0); STAGE(SA(0, 1), A, brow + HALF, 0);
;     if (wr == 1) BAR;
;     WAIT_V(4); BAR;
;     STAGE(SB(1, 0), Bt, bcol, 1); STAGE(SA(1, 0), A, brow, 1); STAGE(SB(1, 1), Bt, bcol + HALF, 1);
;     WAIT_V(6); BAR;
;     return;
;   }
.LBB0_885:
	v_readlane_b32 s4, v243, 47
	v_readlane_b32 s5, v243, 48
	s_lshl_b64 s[4:5], s[4:5], 2
	s_waitcnt lgkmcnt(0)
	s_add_u32 s6, s0, s4
	s_addc_u32 s7, s1, s5
	s_mov_b64 s[0:1], 0x80
	s_add_i32 s22, s12, 0x18000
	v_lshl_add_u64 v[12:13], v[0:1], 0, s[0:1]
	s_mov_b32 m0, s22
	s_mov_b64 s[4:5], 0x40080
	s_add_i32 s23, s12, 0x1a000
	s_waitcnt vmcnt(4)
	s_barrier
	global_load_lds_dwordx4 v[12:13], off
	v_lshl_add_u64 v[0:1], v[0:1], 0, s[4:5]
	s_mov_b32 m0, s23
	s_add_i32 s24, s12, 0x8000
	global_load_lds_dwordx4 v[0:1], off
	v_lshl_add_u64 v[0:1], v[2:3], 0, s[0:1]
	s_mov_b32 m0, s24
	s_add_i32 s25, s12, 0xa000
	global_load_lds_dwordx4 v[0:1], off
	v_lshl_add_u64 v[0:1], v[2:3], 0, s[4:5]
	s_mov_b32 m0, s25
	s_add_i32 s26, s12, 0x1c000
	global_load_lds_dwordx4 v[0:1], off
	v_lshl_add_u64 v[0:1], v[4:5], 0, s[0:1]
	s_mov_b32 m0, s26
	s_add_i32 s27, s12, 0x1e000
	global_load_lds_dwordx4 v[0:1], off
	v_lshl_add_u64 v[0:1], v[4:5], 0, s[4:5]
	s_mov_b32 m0, s27
	v_lshlrev_b32_e32 v3, 2, v7
	global_load_lds_dwordx4 v[0:1], off
	v_and_b32_e32 v0, 15, v7
	v_and_b32_e32 v1, 48, v7
	v_lshlrev_b32_e32 v2, 6, v0
	v_and_b32_e32 v3, 32, v3
	v_readlane_b32 s0, v246, 52
	v_bitop3_b32 v147, v2, v3, v1 bitop3:0x36
	s_waitcnt vmcnt(6)
	v_and_b32_e32 v146, 63, v7
	v_or_b32_e32 v2, s0, v0
	v_lshlrev_b32_e32 v3, 6, v2
	v_lshlrev_b32_e32 v2, 2, v2
	v_and_b32_e32 v3, 0x3c0, v3
	v_and_b32_e32 v2, 32, v2
	v_readlane_b32 s0, v246, 51
	v_bitop3_b32 v2, v3, v2, v1 bitop3:0x36
	s_barrier
	v_or_b32_e32 v3, s0, v0
	v_lshlrev_b32_e32 v4, 6, v3
	v_lshlrev_b32_e32 v3, 2, v3
	v_and_b32_e32 v4, 0x3c0, v4
	v_and_b32_e32 v3, 32, v3
	v_readlane_b32 s0, v246, 53
	v_bitop3_b32 v3, v4, v3, v1 bitop3:0x36
	s_nop 0
	v_or_b32_e32 v4, s0, v0
	v_lshlrev_b32_e32 v5, 6, v4
	v_lshlrev_b32_e32 v4, 2, v4
	v_readlane_b32 s0, v246, 54
	v_and_b32_e32 v5, 0x3c0, v5
	v_and_b32_e32 v4, 32, v4
	v_or_b32_e32 v0, s0, v0
	v_bitop3_b32 v4, v5, v4, v1 bitop3:0x36
	v_lshlrev_b32_e32 v5, 6, v0
	v_lshlrev_b32_e32 v0, 2, v0
	v_and_b32_e32 v5, 0x3c0, v5
	v_and_b32_e32 v0, 32, v0
	v_bitop3_b32 v0, v5, v0, v1 bitop3:0x36
	v_lshlrev_b32_e32 v1, 14, v6
	v_and_b32_e32 v1, 0xffff8000, v1
	v_lshl_add_u32 v1, v8, 11, v1
	v_or_b32_e32 v1, v1, v9
	v_readlane_b32 s0, v244, 34
	v_add_u32_sdwa v144, v1, sext(v10) dst_sel:DWORD dst_unused:UNUSED_PAD src0_sel:DWORD src1_sel:WORD_0
	v_readlane_b32 s1, v244, 35
	s_nop 1
	v_lshl_add_u64 v[130:131], v[144:145], 1, s[0:1]
	v_readlane_b32 s0, v244, 12
	s_nop 1
	v_add_u32_e32 v144, s0, v2
	v_readlane_b32 s0, v244, 13
	s_nop 1
	v_add_u32_e32 v148, s0, v3
	v_readlane_b32 s0, v244, 14
	s_nop 1
	v_add_u32_e32 v149, s0, v4
	v_readlane_b32 s0, v244, 15
	s_nop 1
	v_add_u32_e32 v150, s0, v0
	v_mov_b32_e32 v0, 0
	v_mov_b32_e32 v1, v0
	v_mov_b32_e32 v2, v0
	v_mov_b32_e32 v3, v0
	v_mov_b32_e32 v4, v0
	v_mov_b32_e32 v5, v0
	v_mov_b32_e32 v6, v0
	v_mov_b32_e32 v7, v0
	v_mov_b32_e32 v8, v0
	v_mov_b32_e32 v9, v0
	v_mov_b32_e32 v10, v0
	v_mov_b32_e32 v11, v0
	v_mov_b32_e32 v12, v0
	v_mov_b32_e32 v13, v0
	v_mov_b32_e32 v14, v0
	v_mov_b32_e32 v15, v0
	v_mov_b32_e32 v16, v0
	v_mov_b32_e32 v17, v0
	v_mov_b32_e32 v18, v0
	v_mov_b32_e32 v19, v0
	v_mov_b32_e32 v20, v0
	v_mov_b32_e32 v21, v0
	v_mov_b32_e32 v22, v0
	v_mov_b32_e32 v23, v0
	v_mov_b32_e32 v24, v0
	v_mov_b32_e32 v25, v0
	v_mov_b32_e32 v26, v0
	v_mov_b32_e32 v27, v0
	v_mov_b32_e32 v28, v0
	v_mov_b32_e32 v29, v0
	v_mov_b32_e32 v30, v0
	v_mov_b32_e32 v31, v0
	v_mov_b32_e32 v32, v0
	v_mov_b32_e32 v33, v0
	v_mov_b32_e32 v34, v0
	v_mov_b32_e32 v35, v0
	v_mov_b32_e32 v36, v0
	v_mov_b32_e32 v37, v0
	v_mov_b32_e32 v38, v0
	v_mov_b32_e32 v39, v0
	v_mov_b32_e32 v40, v0
	v_mov_b32_e32 v41, v0
	v_mov_b32_e32 v42, v0
	v_mov_b32_e32 v43, v0
	v_mov_b32_e32 v44, v0
	v_mov_b32_e32 v45, v0
	v_mov_b32_e32 v46, v0
	v_mov_b32_e32 v47, v0
	v_mov_b32_e32 v48, v0
	v_mov_b32_e32 v49, v0
	v_mov_b32_e32 v50, v0
	v_mov_b32_e32 v51, v0
	v_mov_b32_e32 v52, v0
	v_mov_b32_e32 v53, v0
	v_mov_b32_e32 v54, v0
	v_mov_b32_e32 v55, v0
	v_mov_b32_e32 v56, v0
	v_mov_b32_e32 v57, v0
	v_mov_b32_e32 v58, v0
	v_mov_b32_e32 v59, v0
	v_mov_b32_e32 v60, v0
	v_mov_b32_e32 v61, v0
	v_mov_b32_e32 v62, v0
	v_mov_b32_e32 v63, v0
	v_mov_b32_e32 v64, v0
	v_mov_b32_e32 v65, v0
	v_mov_b32_e32 v66, v0
	v_mov_b32_e32 v67, v0
	v_mov_b32_e32 v68, v0
	v_mov_b32_e32 v69, v0
	v_mov_b32_e32 v70, v0
	v_mov_b32_e32 v71, v0
	v_mov_b32_e32 v72, v0
	v_mov_b32_e32 v73, v0
	v_mov_b32_e32 v74, v0
	v_mov_b32_e32 v75, v0
	v_mov_b32_e32 v76, v0
	v_mov_b32_e32 v77, v0
	v_mov_b32_e32 v78, v0
	v_mov_b32_e32 v79, v0
	v_mov_b32_e32 v80, v0
	v_mov_b32_e32 v81, v0
	v_mov_b32_e32 v82, v0
	v_mov_b32_e32 v83, v0
	v_mov_b32_e32 v84, v0
	v_mov_b32_e32 v85, v0
	v_mov_b32_e32 v86, v0
	v_mov_b32_e32 v87, v0
	v_mov_b32_e32 v88, v0
	v_mov_b32_e32 v89, v0
	v_mov_b32_e32 v90, v0
	v_mov_b32_e32 v91, v0
	v_mov_b32_e32 v92, v0
	v_mov_b32_e32 v93, v0
	v_mov_b32_e32 v94, v0
	v_mov_b32_e32 v95, v0
	v_mov_b32_e32 v96, v0
	v_mov_b32_e32 v97, v0
	v_mov_b32_e32 v98, v0
	v_mov_b32_e32 v99, v0
	v_mov_b32_e32 v100, v0
	v_mov_b32_e32 v101, v0
	v_mov_b32_e32 v102, v0
	v_mov_b32_e32 v103, v0
	v_mov_b32_e32 v104, v0
	v_mov_b32_e32 v105, v0
	v_mov_b32_e32 v106, v0
	v_mov_b32_e32 v107, v0
	v_mov_b32_e32 v108, v0
	v_mov_b32_e32 v109, v0
	v_mov_b32_e32 v110, v0
	v_mov_b32_e32 v111, v0
	v_mov_b32_e32 v112, v0
	v_mov_b32_e32 v113, v0
	v_mov_b32_e32 v114, v0
	v_mov_b32_e32 v115, v0
	v_mov_b32_e32 v116, v0
	v_mov_b32_e32 v117, v0
	v_mov_b32_e32 v118, v0
	v_mov_b32_e32 v119, v0
	v_mov_b32_e32 v120, v0
	v_mov_b32_e32 v121, v0
	v_mov_b32_e32 v122, v0
	v_mov_b32_e32 v123, v0
	v_mov_b32_e32 v124, v0
	v_mov_b32_e32 v125, v0
	v_mov_b32_e32 v126, v0
	v_mov_b32_e32 v127, v0
	s_branch .LBB0_887

;     ...
;   for (int u = vb; u < nunits; u += ustride) {
;     const int tm = u % nM, tn = u / nM + ((tn_skip >= 0 && u / nM >= tn_skip) ? 1 : 0);
;     const int brow = tn * 256, bcol = tm * 256;
;     const int un = u + ustride;
;     const bool has_next = un < nunits;
;     const int tn_n = un / nM + ((tn_skip >= 0 && un / nM >= tn_skip) ? 1 : 0);
;     const int brow_n = has_next ? tn_n * 256 : brow, bcol_n = has_next ? (un % nM) * 256 : bcol;
.LBB0_891:
	s_ashr_i32 s1, s0, 31
	s_lshl_b64 s[2:3], s[0:1], 12
	s_or_b32 s34, s0, 0x80
	s_or_b32 s35, s31, 0x80
	s_or_b32 s36, s29, 0x80
	s_or_b32 s37, s30, 0x80
	v_lshl_add_u64 v[132:133], v[130:131], 0, s[2:3]
	s_mov_b32 s1, 0
	s_waitcnt vmcnt(0)

;     ...
;               const int nc = brow + ai * 128 + wr * 64 + m * 16 + fq * 4;
;               const int tok = bcol + bj * 128 + wc * 32 + n * 16 + fr;
;               const int ncw = brow + ai * 128 + wr * 64 + ((m & ~1) + (fq & 1)) * 16 + (fq & ~1) * 4;
;     ...
;               f32x4 v = acc[ai][bj][m][n];
;               if (MODE == 0) {
;                 if (tn == 52) {
;                   if (ai == 0) *(float4*)((float*)(ws + OFF_DTR) + (size_t)tok * 128 + (nc - 13312)) = make_float4(v[0], v[1], v[2], v[3]);
;                 } else {
;                   u16* dst; int ld, c0;
;                   if (tn < 16) { dst = (u16*)(ws + OFF_Z); ld = 4096; c0 = 0; }
;                   else if (tn < 40) { dst = (u16*)(ws + OFF_RA); ld = 6144; c0 = 4096; }
;                   else if (tn < 48) { dst = (u16*)(ws + OFF_Q); ld = 2048; c0 = 10240; }
;                   else if (tn < 50) { dst = (u16*)(ws + OFF_K); ld = 512; c0 = 12288; }
;                   else { dst = (u16*)(ws + OFF_V); ld = 512; c0 = 12800; }
;                   uint2 o; o.x = pk2(v[0], v[1]); o.y = pk2(v[2], v[3]);
;                   WIDE_STORE(dst, ld, c0, o);
;                 }
;               } else if (MODE == 1) {
;                 uint2 o; o.x = pk2(sigmoidf_(v[0]), sigmoidf_(v[1])); o.y = pk2(sigmoidf_(v[2]), sigmoidf_(v[3]));
;                 WIDE_STORE((u16*)outp, 4096, 0, o);
;               } else if (MODE == 2) {
;                 const u16* gate = (const u16*)outp;
;                 uint2 ga = *(const uint2*)(gate + (size_t)tok * 4096 + nc);
;                 uint2 p1; p1.x = pk2(v[0] * bflo(ga.x), v[1] * bfhi(ga.x)); p1.y = pk2(v[2] * bflo(ga.y), v[3] * bfhi(ga.y));
;                 *(uint2*)((u16*)(ws + OFF_YB) + (size_t)tok * DM + nc) = p1;
;               } else if (MODE == 6) {
;                 const u16* gate = (const u16*)outp;
;                 uint2 gb = *(const uint2*)(gate + (size_t)tok * 4096 + 2048 + nc);
;                 const uint2 p1 = *(const uint2*)((const u16*)(ws + OFF_YB) + (size_t)tok * DM + nc);
;                 uint2 o;
;                 o.x = pk2(bflo(p1.x) + v[0] * bflo(gb.x), bfhi(p1.x) + v[1] * bfhi(gb.x));
;                 o.y = pk2(bflo(p1.y) + v[2] * bflo(gb.y), bfhi(p1.y) + v[3] * bfhi(gb.y));
;                 WIDE_STORE((u16*)(ws + OFF_RB + 128 * MiB), DM, 0, o);
;               } else if (MODE == 3) {
.LBB0_895:
	v_readlane_b32 s2, v245, 25
	v_readlane_b32 s3, v245, 26
	s_add_i32 s0, s0, s49
	v_and_b32_e32 v192, 15, v146
	v_or_b32_e32 v192, s54, v192
	v_or_b32_e32 v192, s29, v192
	v_lshrrev_b32_e32 v193, 2, v146
	v_and_b32_e32 v194, -4, v193
	v_add_u32_e32 v194, s0, v194
	v_and_b32_e32 v193, -8, v193
	v_and_b32_e32 v195, 16, v146
	v_add3_u32 v193, v193, v195, s0
	v_lshlrev_b32_e32 v195, 13, v192
	v_lshl_add_u32 v138, v194, 2, v195
	v_add_u32_e32 v139, 0x20000, v138
	v_add_u32_e32 v140, 0x100000, v138
	v_add_u32_e32 v141, 0x120000, v138
	v_lshlrev_b32_e32 v195, 12, v192
	v_lshl_add_u32 v142, v193, 1, v195
	v_add_u32_e32 v143, 0x10000, v142
	v_add_u32_e32 v190, 0x80000, v142
	v_add_u32_e32 v191, 0x90000, v142
	global_load_dwordx4 v[210:213], v138, s[6:7] offset:0 nt
	global_load_dwordx4 v[214:217], v138, s[6:7] offset:64 nt
	global_load_dwordx4 v[218:221], v138, s[6:7] offset:128 nt
	global_load_dwordx4 v[222:225], v138, s[6:7] offset:192 nt
	global_load_dwordx4 v[226:229], v139, s[6:7] offset:0 nt
	global_load_dwordx4 v[230:233], v139, s[6:7] offset:64 nt
	global_load_dwordx4 v[234:237], v139, s[6:7] offset:128 nt
	global_load_dwordx4 v[238:241], v139, s[6:7] offset:192 nt
	global_load_dwordx4 v[168:171], v140, s[6:7] offset:0 nt
	global_load_dwordx4 v[172:175], v140, s[6:7] offset:64 nt
	global_load_dwordx4 v[176:179], v140, s[6:7] offset:128 nt
	global_load_dwordx4 v[180:183], v140, s[6:7] offset:192 nt
	global_load_dwordx4 v[152:155], v141, s[6:7] offset:0 nt
	global_load_dwordx4 v[156:159], v141, s[6:7] offset:64 nt
	global_load_dwordx4 v[160:163], v141, s[6:7] offset:128 nt
	global_load_dwordx4 v[134:137], v141, s[6:7] offset:192 nt
	s_waitcnt vmcnt(15)
	v_pk_add_f32 v[124:125], v[124:125], v[210:211]
	v_pk_add_f32 v[126:127], v[126:127], v[212:213]
	global_load_dwordx4 v[210:213], v138, s[6:7] offset:512 nt
	s_waitcnt vmcnt(15)
	v_pk_add_f32 v[116:117], v[116:117], v[214:215]
	v_pk_add_f32 v[118:119], v[118:119], v[216:217]
	global_load_dwordx4 v[214:217], v138, s[6:7] offset:576 nt
	s_waitcnt vmcnt(15)
	v_pk_add_f32 v[108:109], v[108:109], v[218:219]
	v_pk_add_f32 v[110:111], v[110:111], v[220:221]
	global_load_dwordx4 v[218:221], v138, s[6:7] offset:640 nt
	s_waitcnt vmcnt(15)
	v_pk_add_f32 v[100:101], v[100:101], v[222:223]
	v_pk_add_f32 v[102:103], v[102:103], v[224:225]
	global_load_dwordx4 v[222:225], v138, s[6:7] offset:704 nt
	s_waitcnt vmcnt(15)
	v_pk_add_f32 v[120:121], v[120:121], v[226:227]
	v_pk_add_f32 v[122:123], v[122:123], v[228:229]
	global_load_dwordx4 v[226:229], v139, s[6:7] offset:512 nt
	s_waitcnt vmcnt(15)
	v_pk_add_f32 v[112:113], v[112:113], v[230:231]
	v_pk_add_f32 v[114:115], v[114:115], v[232:233]
	global_load_dwordx4 v[230:233], v139, s[6:7] offset:576 nt
	s_waitcnt vmcnt(15)
	v_pk_add_f32 v[104:105], v[104:105], v[234:235]
	v_pk_add_f32 v[106:107], v[106:107], v[236:237]
	global_load_dwordx4 v[234:237], v139, s[6:7] offset:640 nt
	s_waitcnt vmcnt(15)
	v_pk_add_f32 v[96:97], v[96:97], v[238:239]
	v_pk_add_f32 v[98:99], v[98:99], v[240:241]
	global_load_dwordx4 v[238:241], v139, s[6:7] offset:704 nt
	s_waitcnt vmcnt(15)
	v_pk_add_f32 v[92:93], v[92:93], v[168:169]
	v_pk_add_f32 v[94:95], v[94:95], v[170:171]
	global_load_dwordx4 v[168:171], v140, s[6:7] offset:512 nt
	s_waitcnt vmcnt(15)
	v_pk_add_f32 v[84:85], v[84:85], v[172:173]
	v_pk_add_f32 v[86:87], v[86:87], v[174:175]
	global_load_dwordx4 v[172:175], v140, s[6:7] offset:576 nt
	s_waitcnt vmcnt(15)
	v_pk_add_f32 v[76:77], v[76:77], v[176:177]
	v_pk_add_f32 v[78:79], v[78:79], v[178:179]
	global_load_dwordx4 v[176:179], v140, s[6:7] offset:640 nt
	s_waitcnt vmcnt(15)
	v_pk_add_f32 v[68:69], v[68:69], v[180:181]
	v_pk_add_f32 v[70:71], v[70:71], v[182:183]
	global_load_dwordx4 v[180:183], v140, s[6:7] offset:704 nt
	s_waitcnt vmcnt(15)
	v_pk_add_f32 v[88:89], v[88:89], v[152:153]
	v_pk_add_f32 v[90:91], v[90:91], v[154:155]
	global_load_dwordx4 v[152:155], v141, s[6:7] offset:512 nt
	s_waitcnt vmcnt(15)
	v_pk_add_f32 v[80:81], v[80:81], v[156:157]
	v_pk_add_f32 v[82:83], v[82:83], v[158:159]
	global_load_dwordx4 v[156:159], v141, s[6:7] offset:576 nt
	s_waitcnt vmcnt(15)
	v_pk_add_f32 v[72:73], v[72:73], v[160:161]
	v_pk_add_f32 v[74:75], v[74:75], v[162:163]
	global_load_dwordx4 v[160:163], v141, s[6:7] offset:640 nt
	s_waitcnt vmcnt(15)
	v_pk_add_f32 v[64:65], v[64:65], v[134:135]
	v_pk_add_f32 v[66:67], v[66:67], v[136:137]
	global_load_dwordx4 v[134:137], v141, s[6:7] offset:704 nt
	v_cvt_pk_bf16_f32 v124, v124, v125
	v_cvt_pk_bf16_f32 v125, v126, v127
	v_cvt_pk_bf16_f32 v126, v116, v117
	v_cvt_pk_bf16_f32 v127, v118, v119
	v_cvt_pk_bf16_f32 v108, v108, v109
	v_cvt_pk_bf16_f32 v109, v110, v111
	v_cvt_pk_bf16_f32 v110, v100, v101
	v_cvt_pk_bf16_f32 v111, v102, v103
	s_nop 1
	v_permlane16_swap_b32_e32 v124, v126
	v_permlane16_swap_b32_e32 v125, v127
	v_permlane16_swap_b32_e32 v108, v110
	v_permlane16_swap_b32_e32 v109, v111
	global_store_dwordx4 v142, v[124:127], s[2:3] offset:0
	global_store_dwordx4 v142, v[108:111], s[2:3] offset:64
	v_cvt_pk_bf16_f32 v120, v120, v121
	v_cvt_pk_bf16_f32 v121, v122, v123
	v_cvt_pk_bf16_f32 v122, v112, v113
	v_cvt_pk_bf16_f32 v123, v114, v115
	v_cvt_pk_bf16_f32 v104, v104, v105
	v_cvt_pk_bf16_f32 v105, v106, v107
	v_cvt_pk_bf16_f32 v106, v96, v97
	v_cvt_pk_bf16_f32 v107, v98, v99
	s_nop 1
	v_permlane16_swap_b32_e32 v120, v122
	v_permlane16_swap_b32_e32 v121, v123
	v_permlane16_swap_b32_e32 v104, v106
	v_permlane16_swap_b32_e32 v105, v107
	global_store_dwordx4 v143, v[120:123], s[2:3] offset:0
	global_store_dwordx4 v143, v[104:107], s[2:3] offset:64
	v_cvt_pk_bf16_f32 v92, v92, v93
	v_cvt_pk_bf16_f32 v93, v94, v95
	v_cvt_pk_bf16_f32 v94, v84, v85
	v_cvt_pk_bf16_f32 v95, v86, v87
	v_cvt_pk_bf16_f32 v76, v76, v77
	v_cvt_pk_bf16_f32 v77, v78, v79
	v_cvt_pk_bf16_f32 v78, v68, v69
	v_cvt_pk_bf16_f32 v79, v70, v71
	s_nop 1
	v_permlane16_swap_b32_e32 v92, v94
	v_permlane16_swap_b32_e32 v93, v95
	v_permlane16_swap_b32_e32 v76, v78
	v_permlane16_swap_b32_e32 v77, v79
	global_store_dwordx4 v190, v[92:95], s[2:3] offset:0
	global_store_dwordx4 v190, v[76:79], s[2:3] offset:64
	v_cvt_pk_bf16_f32 v88, v88, v89
	v_cvt_pk_bf16_f32 v89, v90, v91
	v_cvt_pk_bf16_f32 v90, v80, v81
	v_cvt_pk_bf16_f32 v91, v82, v83
	v_cvt_pk_bf16_f32 v72, v72, v73
	v_cvt_pk_bf16_f32 v73, v74, v75
	v_cvt_pk_bf16_f32 v74, v64, v65
	v_cvt_pk_bf16_f32 v75, v66, v67
	s_nop 1
	v_permlane16_swap_b32_e32 v88, v90
	v_permlane16_swap_b32_e32 v89, v91
	v_permlane16_swap_b32_e32 v72, v74
	v_permlane16_swap_b32_e32 v73, v75
	global_store_dwordx4 v191, v[88:91], s[2:3] offset:0
	global_store_dwordx4 v191, v[72:75], s[2:3] offset:64
	s_waitcnt vmcnt(23)
; #define WIDE_STORE(BASE, LD, COFF, O) do { if ((m & 1) == 0) opend[n] = (O); \
;                 else *(uint4*)((BASE) + (size_t)tok * (LD) + (ncw - (COFF))) = swap_pair(opend[n], (O)); } while (0)
;     ...
; #pragma unroll
;     for (int a = 0; a < 2; ++a)
; #pragma unroll
;       for (int b = 0; b < 2; ++b)
; #pragma unroll
;         for (int m = 0; m < 4; ++m)
; #pragma unroll
;           for (int n = 0; n < 2; ++n) acc[a][b][m][n] = f32x4{0.f, 0.f, 0.f, 0.f};
;     ...
;               } else if (MODE == 3) {
;                 float4 r = ldnt4(xin + (size_t)tok * DM + nc);
;                 uint2 hb; hb.x = pk2(r.x + v[0], r.y + v[1]); hb.y = pk2(r.z + v[2], r.w + v[3]);
;                 WIDE_STORE((u16*)(ws + OFF_RB), DM, 0, hb);
	v_pk_add_f32 v[60:61], v[60:61], v[210:211]
	v_pk_add_f32 v[62:63], v[62:63], v[212:213]
	s_waitcnt vmcnt(22)
	v_pk_add_f32 v[52:53], v[52:53], v[214:215]
	v_pk_add_f32 v[54:55], v[54:55], v[216:217]
	s_waitcnt vmcnt(21)
	v_pk_add_f32 v[44:45], v[44:45], v[218:219]
	v_pk_add_f32 v[46:47], v[46:47], v[220:221]
	s_waitcnt vmcnt(20)
	v_pk_add_f32 v[36:37], v[36:37], v[222:223]
	v_pk_add_f32 v[38:39], v[38:39], v[224:225]
	s_waitcnt vmcnt(19)
	v_pk_add_f32 v[56:57], v[56:57], v[226:227]
	v_pk_add_f32 v[58:59], v[58:59], v[228:229]
	s_waitcnt vmcnt(18)
	v_pk_add_f32 v[48:49], v[48:49], v[230:231]
	v_pk_add_f32 v[50:51], v[50:51], v[232:233]
	s_waitcnt vmcnt(17)
	v_pk_add_f32 v[40:41], v[40:41], v[234:235]
	v_pk_add_f32 v[42:43], v[42:43], v[236:237]
	s_waitcnt vmcnt(16)
	v_pk_add_f32 v[32:33], v[32:33], v[238:239]
	v_pk_add_f32 v[34:35], v[34:35], v[240:241]
	s_waitcnt vmcnt(15)
	v_pk_add_f32 v[28:29], v[28:29], v[168:169]
	v_pk_add_f32 v[30:31], v[30:31], v[170:171]
	s_waitcnt vmcnt(14)
	v_pk_add_f32 v[20:21], v[20:21], v[172:173]
	v_pk_add_f32 v[22:23], v[22:23], v[174:175]
	s_waitcnt vmcnt(13)
	v_pk_add_f32 v[12:13], v[12:13], v[176:177]
	v_pk_add_f32 v[14:15], v[14:15], v[178:179]
	s_waitcnt vmcnt(12)
	v_pk_add_f32 v[4:5], v[4:5], v[180:181]
	v_pk_add_f32 v[6:7], v[6:7], v[182:183]
	s_waitcnt vmcnt(11)
	v_pk_add_f32 v[24:25], v[24:25], v[152:153]
	v_pk_add_f32 v[26:27], v[26:27], v[154:155]
	s_waitcnt vmcnt(10)
	v_pk_add_f32 v[16:17], v[16:17], v[156:157]
	v_pk_add_f32 v[18:19], v[18:19], v[158:159]
	s_waitcnt vmcnt(9)
	v_pk_add_f32 v[8:9], v[8:9], v[160:161]
	v_pk_add_f32 v[10:11], v[10:11], v[162:163]
	s_waitcnt vmcnt(8)
	v_pk_add_f32 v[0:1], v[0:1], v[134:135]
	v_pk_add_f32 v[2:3], v[2:3], v[136:137]
	v_cvt_pk_bf16_f32 v60, v60, v61
	v_cvt_pk_bf16_f32 v61, v62, v63
	v_cvt_pk_bf16_f32 v62, v52, v53
	v_cvt_pk_bf16_f32 v63, v54, v55
	v_cvt_pk_bf16_f32 v44, v44, v45
	v_cvt_pk_bf16_f32 v45, v46, v47
	v_cvt_pk_bf16_f32 v46, v36, v37
	v_cvt_pk_bf16_f32 v47, v38, v39
	s_nop 1
	v_permlane16_swap_b32_e32 v60, v62
	v_permlane16_swap_b32_e32 v61, v63
	v_permlane16_swap_b32_e32 v44, v46
	v_permlane16_swap_b32_e32 v45, v47
	global_store_dwordx4 v142, v[60:63], s[2:3] offset:256
	global_store_dwordx4 v142, v[44:47], s[2:3] offset:320
	v_cvt_pk_bf16_f32 v56, v56, v57
	v_cvt_pk_bf16_f32 v57, v58, v59
	v_cvt_pk_bf16_f32 v58, v48, v49
	v_cvt_pk_bf16_f32 v59, v50, v51
	v_cvt_pk_bf16_f32 v40, v40, v41
	v_cvt_pk_bf16_f32 v41, v42, v43
	v_cvt_pk_bf16_f32 v42, v32, v33
	v_cvt_pk_bf16_f32 v43, v34, v35
	s_nop 1
	v_permlane16_swap_b32_e32 v56, v58
	v_permlane16_swap_b32_e32 v57, v59
	v_permlane16_swap_b32_e32 v40, v42
	v_permlane16_swap_b32_e32 v41, v43
	global_store_dwordx4 v143, v[56:59], s[2:3] offset:256
	global_store_dwordx4 v143, v[40:43], s[2:3] offset:320
	v_cvt_pk_bf16_f32 v28, v28, v29
	v_cvt_pk_bf16_f32 v29, v30, v31
	v_cvt_pk_bf16_f32 v30, v20, v21
	v_cvt_pk_bf16_f32 v31, v22, v23
	v_cvt_pk_bf16_f32 v12, v12, v13
	v_cvt_pk_bf16_f32 v13, v14, v15
	v_cvt_pk_bf16_f32 v14, v4, v5
	v_cvt_pk_bf16_f32 v15, v6, v7
	s_nop 1
	v_permlane16_swap_b32_e32 v28, v30
	v_permlane16_swap_b32_e32 v29, v31
	v_permlane16_swap_b32_e32 v12, v14
	v_permlane16_swap_b32_e32 v13, v15
	global_store_dwordx4 v190, v[28:31], s[2:3] offset:256
	global_store_dwordx4 v190, v[12:15], s[2:3] offset:320
	v_cvt_pk_bf16_f32 v24, v24, v25
	v_cvt_pk_bf16_f32 v25, v26, v27
	v_cvt_pk_bf16_f32 v26, v16, v17
	v_cvt_pk_bf16_f32 v27, v18, v19
	v_cvt_pk_bf16_f32 v8, v8, v9
	v_cvt_pk_bf16_f32 v9, v10, v11
	v_cvt_pk_bf16_f32 v10, v0, v1
	v_cvt_pk_bf16_f32 v11, v2, v3
	s_nop 1
	v_permlane16_swap_b32_e32 v24, v26
	v_permlane16_swap_b32_e32 v25, v27
	v_permlane16_swap_b32_e32 v8, v10
	v_permlane16_swap_b32_e32 v9, v11
	global_store_dwordx4 v191, v[24:27], s[2:3] offset:256
	global_store_dwordx4 v191, v[8:11], s[2:3] offset:320
	s_and_b64 s[0:1], s[56:57], s[10:11]
	s_andn2_b64 vcc, exec, s[0:1]
	s_nop 1
	v_mov_b32_e32 v0, 0
	v_mov_b32_e32 v1, v0
	v_mov_b32_e32 v2, v0
	v_mov_b32_e32 v3, v0
	v_mov_b32_e32 v4, v0
	v_mov_b32_e32 v5, v0
	v_mov_b32_e32 v6, v0
	v_mov_b32_e32 v7, v0
	v_mov_b32_e32 v8, v0
	v_mov_b32_e32 v9, v0
	v_mov_b32_e32 v10, v0
	v_mov_b32_e32 v11, v0
	v_mov_b32_e32 v12, v0
	v_mov_b32_e32 v13, v0
	v_mov_b32_e32 v14, v0
	v_mov_b32_e32 v15, v0
	v_mov_b32_e32 v16, v0
	v_mov_b32_e32 v17, v0
	v_mov_b32_e32 v18, v0
	v_mov_b32_e32 v19, v0
	v_mov_b32_e32 v20, v0
	v_mov_b32_e32 v21, v0
	v_mov_b32_e32 v22, v0
	v_mov_b32_e32 v23, v0
	v_mov_b32_e32 v24, v0
	v_mov_b32_e32 v25, v0
	v_mov_b32_e32 v26, v0
	v_mov_b32_e32 v27, v0
	v_mov_b32_e32 v28, v0
	v_mov_b32_e32 v29, v0
	v_mov_b32_e32 v30, v0
	v_mov_b32_e32 v31, v0
	v_mov_b32_e32 v32, v0
	v_mov_b32_e32 v33, v0
	v_mov_b32_e32 v34, v0
	v_mov_b32_e32 v35, v0
	v_mov_b32_e32 v36, v0
	v_mov_b32_e32 v37, v0
	v_mov_b32_e32 v38, v0
	v_mov_b32_e32 v39, v0
	v_mov_b32_e32 v40, v0
	v_mov_b32_e32 v41, v0
	v_mov_b32_e32 v42, v0
	v_mov_b32_e32 v43, v0
	v_mov_b32_e32 v44, v0
	v_mov_b32_e32 v45, v0
	v_mov_b32_e32 v46, v0
	v_mov_b32_e32 v47, v0
	v_mov_b32_e32 v48, v0
	v_mov_b32_e32 v49, v0
	v_mov_b32_e32 v50, v0
	v_mov_b32_e32 v51, v0
	v_mov_b32_e32 v52, v0
	v_mov_b32_e32 v53, v0
	v_mov_b32_e32 v54, v0
	v_mov_b32_e32 v55, v0
	v_mov_b32_e32 v56, v0
	v_mov_b32_e32 v57, v0
	v_mov_b32_e32 v58, v0
	v_mov_b32_e32 v59, v0
	v_mov_b32_e32 v60, v0
	v_mov_b32_e32 v61, v0
	v_mov_b32_e32 v62, v0
	v_mov_b32_e32 v63, v0
	v_mov_b32_e32 v64, v0
	v_mov_b32_e32 v65, v0
	v_mov_b32_e32 v66, v0
	v_mov_b32_e32 v67, v0
	v_mov_b32_e32 v68, v0
	v_mov_b32_e32 v69, v0
	v_mov_b32_e32 v70, v0
	v_mov_b32_e32 v71, v0
	v_mov_b32_e32 v72, v0
	v_mov_b32_e32 v73, v0
	v_mov_b32_e32 v74, v0
	v_mov_b32_e32 v75, v0
	v_mov_b32_e32 v76, v0
	v_mov_b32_e32 v77, v0
	v_mov_b32_e32 v78, v0
	v_mov_b32_e32 v79, v0
	v_mov_b32_e32 v80, v0
	v_mov_b32_e32 v81, v0
	v_mov_b32_e32 v82, v0
	v_mov_b32_e32 v83, v0
	v_mov_b32_e32 v84, v0
	v_mov_b32_e32 v85, v0
	v_mov_b32_e32 v86, v0
	v_mov_b32_e32 v87, v0
	v_mov_b32_e32 v88, v0
	v_mov_b32_e32 v89, v0
	v_mov_b32_e32 v90, v0
	v_mov_b32_e32 v91, v0
	v_mov_b32_e32 v92, v0
	v_mov_b32_e32 v93, v0
	v_mov_b32_e32 v94, v0
	v_mov_b32_e32 v95, v0
	v_mov_b32_e32 v96, v0
	v_mov_b32_e32 v97, v0
	v_mov_b32_e32 v98, v0
	v_mov_b32_e32 v99, v0
	v_mov_b32_e32 v100, v0
	v_mov_b32_e32 v101, v0
	v_mov_b32_e32 v102, v0
	v_mov_b32_e32 v103, v0
	v_mov_b32_e32 v104, v0
	v_mov_b32_e32 v105, v0
	v_mov_b32_e32 v106, v0
	v_mov_b32_e32 v107, v0
	v_mov_b32_e32 v108, v0
	v_mov_b32_e32 v109, v0
	v_mov_b32_e32 v110, v0
	v_mov_b32_e32 v111, v0
	v_mov_b32_e32 v112, v0
	v_mov_b32_e32 v113, v0
	v_mov_b32_e32 v114, v0
	v_mov_b32_e32 v115, v0
	v_mov_b32_e32 v116, v0
	v_mov_b32_e32 v117, v0
	v_mov_b32_e32 v118, v0
	v_mov_b32_e32 v119, v0
	v_mov_b32_e32 v120, v0
	v_mov_b32_e32 v121, v0
	v_mov_b32_e32 v122, v0
	v_mov_b32_e32 v123, v0
	v_mov_b32_e32 v124, v0
	v_mov_b32_e32 v125, v0
	v_mov_b32_e32 v126, v0
	v_mov_b32_e32 v127, v0
	s_waitcnt vmcnt(0)
	s_cbranch_vccnz .LBB0_886
	s_barrier
	s_branch .LBB0_886

; #define STAGE(P_, BASE, br, kt) do { const u16* _gb = (BASE) + (long)(br) * K + (long)(kt) * BK; \
;     _Pragma("unroll") for (int _i = 0; _i < 2; ++_i) { \
;       __builtin_amdgcn_global_load_lds((const unsigned*)(_gb + (long)_i * 64 * K + lane_off), \
;         (unsigned*)((char*)(P_) + lds_wbase + _i * 8192), 16, 0, 0); } } while (0)
; #define WAIT_V(n) asm volatile("s_waitcnt vmcnt(" #n ")" ::: "memory")
; #define BAR __builtin_amdgcn_s_barrier()
; template <int PRE> ...
;     ...
;   const int wid = wvi, lane = tid & 63, wr = wid >> 2, wc = wid & 3, fr = lane & 15, fq = lane >> 4;
;   bf16x8 At[4][2], B0[2][2], B1[2][2];
;   const int nt = K / BK;
;   const unsigned lds_wbase = wid * 1024;
;   unsigned lane_off;
;   { int _r, _c; stage_rc(tid * 16, _r, _c); lane_off = (unsigned)(_r * K + _c); }
;     ...
;   if (PRE == 2) {
;     STAGE(SB(0, 0), Bt, bcol, 0); STAGE(SA(0, 0), A, brow, 0);
;     STAGE(SB(0, 1), Bt, bcol + HALF, 0); STAGE(SA(0, 1), A, brow + HALF, 0);
;     if (wr == 1) BAR;
;     WAIT_V(4); BAR;
;     STAGE(SB(1, 0), Bt, bcol, 1); STAGE(SA(1, 0), A, brow, 1); STAGE(SB(1, 1), Bt, bcol + HALF, 1);
;     WAIT_V(6); BAR;
;     return;
;   }
;     ...
; #pragma unroll
;     for (int a = 0; a < 2; ++a)
; #pragma unroll
;       for (int b = 0; b < 2; ++b)
; #pragma unroll
;         for (int m = 0; m < 4; ++m)
; #pragma unroll
;           for (int n = 0; n < 2; ++n) acc[a][b][m][n] = f32x4{0.f, 0.f, 0.f, 0.f};
.LBB0_1008:
	s_mov_b64 s[2:3], 0x80
	s_add_i32 s20, s10, 0x18000
	v_lshl_add_u64 v[12:13], v[0:1], 0, s[2:3]
	s_mov_b32 m0, s20
	s_mov_b64 s[4:5], 0x40080
	s_add_i32 s21, s10, 0x1a000
	s_waitcnt vmcnt(4)
	s_barrier
	global_load_lds_dwordx4 v[12:13], off
	v_lshl_add_u64 v[0:1], v[0:1], 0, s[4:5]
	s_mov_b32 m0, s21
	s_add_i32 s22, s10, 0x8000
	global_load_lds_dwordx4 v[0:1], off
	v_lshl_add_u64 v[0:1], v[2:3], 0, s[2:3]
	s_mov_b32 m0, s22
	s_add_i32 s23, s10, 0xa000
	global_load_lds_dwordx4 v[0:1], off
	v_lshl_add_u64 v[0:1], v[2:3], 0, s[4:5]
	s_mov_b32 m0, s23
	s_add_i32 s24, s10, 0x1c000
	global_load_lds_dwordx4 v[0:1], off
	v_lshl_add_u64 v[0:1], v[4:5], 0, s[2:3]
	s_mov_b32 m0, s24
	s_add_i32 s25, s10, 0x1e000
	global_load_lds_dwordx4 v[0:1], off
	v_lshl_add_u64 v[0:1], v[4:5], 0, s[4:5]
	s_mov_b32 m0, s25
	v_lshlrev_b32_e32 v3, 2, v9
	global_load_lds_dwordx4 v[0:1], off
	v_and_b32_e32 v0, 15, v9
	v_and_b32_e32 v1, 48, v9
	v_lshlrev_b32_e32 v2, 6, v0
	v_and_b32_e32 v3, 32, v3
	v_readlane_b32 s0, v246, 52
	v_bitop3_b32 v135, v2, v3, v1 bitop3:0x36
	s_waitcnt vmcnt(6)
	v_readlane_b32 s2, v244, 36
	v_or_b32_e32 v2, s0, v0
	v_lshlrev_b32_e32 v3, 6, v2
	v_lshlrev_b32_e32 v2, 2, v2
	v_and_b32_e32 v3, 0x3c0, v3
	v_and_b32_e32 v2, 32, v2
	v_readlane_b32 s0, v246, 51
	v_bitop3_b32 v2, v3, v2, v1 bitop3:0x36
	v_readlane_b32 s3, v244, 37
	v_or_b32_e32 v3, s0, v0
	v_lshlrev_b32_e32 v4, 6, v3
	v_lshlrev_b32_e32 v3, 2, v3
	v_and_b32_e32 v4, 0x3c0, v4
	v_and_b32_e32 v3, 32, v3
	v_readlane_b32 s0, v246, 53
	v_bitop3_b32 v3, v4, v3, v1 bitop3:0x36
	v_and_b32_e32 v134, 63, v9
	v_or_b32_e32 v4, s0, v0
	v_lshlrev_b32_e32 v5, 6, v4
	v_lshlrev_b32_e32 v4, 2, v4
	v_readlane_b32 s0, v246, 54
	v_and_b32_e32 v5, 0x3c0, v5
	v_and_b32_e32 v4, 32, v4
	v_or_b32_e32 v0, s0, v0
	v_bitop3_b32 v4, v5, v4, v1 bitop3:0x36
	v_lshlrev_b32_e32 v5, 6, v0
	v_lshlrev_b32_e32 v0, 2, v0
	v_and_b32_e32 v5, 0x3c0, v5
	v_and_b32_e32 v0, 32, v0
	v_bitop3_b32 v0, v5, v0, v1 bitop3:0x36
	v_lshlrev_b32_e32 v1, 14, v6
	v_and_b32_e32 v1, 0xffff8000, v1
	v_readlane_b32 s0, v244, 12
	v_lshl_add_u32 v1, v7, 11, v1
	v_or_b32_e32 v1, v1, v8
	v_add_u32_e32 v136, s0, v2
	v_readlane_b32 s0, v244, 13
	v_add_u32_sdwa v144, v1, sext(v10) dst_sel:DWORD dst_unused:UNUSED_PAD src0_sel:DWORD src1_sel:WORD_0
	v_lshl_add_u64 v[130:131], v[144:145], 1, s[2:3]
	v_add_u32_e32 v137, s0, v3
	v_readlane_b32 s0, v244, 14
	s_barrier
	s_nop 0
	v_add_u32_e32 v138, s0, v4
	v_readlane_b32 s0, v244, 15
	s_nop 1
	v_add_u32_e32 v139, s0, v0
	s_waitcnt vmcnt(0)
	v_mov_b32_e32 v0, 0
	v_mov_b32_e32 v1, v0
	v_mov_b32_e32 v2, v0
	v_mov_b32_e32 v3, v0
	v_mov_b32_e32 v8, v0
	v_mov_b32_e32 v9, v0
	v_mov_b32_e32 v10, v0
	v_mov_b32_e32 v11, v0
	v_mov_b32_e32 v16, v0
	v_mov_b32_e32 v17, v0
	v_mov_b32_e32 v18, v0
	v_mov_b32_e32 v19, v0
	v_mov_b32_e32 v24, v0
	v_mov_b32_e32 v25, v0
	v_mov_b32_e32 v26, v0
	v_mov_b32_e32 v27, v0
	v_mov_b32_e32 v32, v0
	v_mov_b32_e32 v33, v0
	v_mov_b32_e32 v34, v0
	v_mov_b32_e32 v35, v0
	v_mov_b32_e32 v40, v0
	v_mov_b32_e32 v41, v0
	v_mov_b32_e32 v42, v0
	v_mov_b32_e32 v43, v0
	v_mov_b32_e32 v48, v0
	v_mov_b32_e32 v49, v0
	v_mov_b32_e32 v50, v0
	v_mov_b32_e32 v51, v0
	v_mov_b32_e32 v56, v0
	v_mov_b32_e32 v57, v0
	v_mov_b32_e32 v58, v0
	v_mov_b32_e32 v59, v0
	v_mov_b32_e32 v64, v0
	v_mov_b32_e32 v65, v0
	v_mov_b32_e32 v66, v0
	v_mov_b32_e32 v67, v0
	v_mov_b32_e32 v72, v0
	v_mov_b32_e32 v73, v0
	v_mov_b32_e32 v74, v0
	v_mov_b32_e32 v75, v0
	v_mov_b32_e32 v80, v0
	v_mov_b32_e32 v81, v0
	v_mov_b32_e32 v82, v0
	v_mov_b32_e32 v83, v0
	v_mov_b32_e32 v88, v0
	v_mov_b32_e32 v89, v0
	v_mov_b32_e32 v90, v0
	v_mov_b32_e32 v91, v0
	v_mov_b32_e32 v96, v0
	v_mov_b32_e32 v97, v0
	v_mov_b32_e32 v98, v0
	v_mov_b32_e32 v99, v0
	v_mov_b32_e32 v104, v0
	v_mov_b32_e32 v105, v0
	v_mov_b32_e32 v106, v0
	v_mov_b32_e32 v107, v0
	v_mov_b32_e32 v112, v0
	v_mov_b32_e32 v113, v0
	v_mov_b32_e32 v114, v0
	v_mov_b32_e32 v115, v0
	v_mov_b32_e32 v120, v0
	v_mov_b32_e32 v121, v0
	v_mov_b32_e32 v122, v0
	v_mov_b32_e32 v123, v0
	v_mov_b32_e32 v4, v0
	v_mov_b32_e32 v5, v0
	v_mov_b32_e32 v6, v0
	v_mov_b32_e32 v7, v0
	v_mov_b32_e32 v12, v0
	v_mov_b32_e32 v13, v0
	v_mov_b32_e32 v14, v0
	v_mov_b32_e32 v15, v0
	v_mov_b32_e32 v20, v0
	v_mov_b32_e32 v21, v0
	v_mov_b32_e32 v22, v0
	v_mov_b32_e32 v23, v0
	v_mov_b32_e32 v28, v0
	v_mov_b32_e32 v29, v0
	v_mov_b32_e32 v30, v0
	v_mov_b32_e32 v31, v0
	v_mov_b32_e32 v36, v0
	v_mov_b32_e32 v37, v0
	v_mov_b32_e32 v38, v0
	v_mov_b32_e32 v39, v0
	v_mov_b32_e32 v44, v0
	v_mov_b32_e32 v45, v0
	v_mov_b32_e32 v46, v0
	v_mov_b32_e32 v47, v0
	v_mov_b32_e32 v52, v0
	v_mov_b32_e32 v53, v0
	v_mov_b32_e32 v54, v0
	v_mov_b32_e32 v55, v0
	v_mov_b32_e32 v60, v0
	v_mov_b32_e32 v61, v0
	v_mov_b32_e32 v62, v0
	v_mov_b32_e32 v63, v0
	v_mov_b32_e32 v68, v0
	v_mov_b32_e32 v69, v0
	v_mov_b32_e32 v70, v0
	v_mov_b32_e32 v71, v0
	v_mov_b32_e32 v76, v0
	v_mov_b32_e32 v77, v0
	v_mov_b32_e32 v78, v0
	v_mov_b32_e32 v79, v0
	v_mov_b32_e32 v84, v0
	v_mov_b32_e32 v85, v0
	v_mov_b32_e32 v86, v0
	v_mov_b32_e32 v87, v0
	v_mov_b32_e32 v92, v0
	v_mov_b32_e32 v93, v0
	v_mov_b32_e32 v94, v0
	v_mov_b32_e32 v95, v0
	v_mov_b32_e32 v100, v0
	v_mov_b32_e32 v101, v0
	v_mov_b32_e32 v102, v0
	v_mov_b32_e32 v103, v0
	v_mov_b32_e32 v108, v0
	v_mov_b32_e32 v109, v0
	v_mov_b32_e32 v110, v0
	v_mov_b32_e32 v111, v0
	v_mov_b32_e32 v116, v0
	v_mov_b32_e32 v117, v0
	v_mov_b32_e32 v118, v0
	v_mov_b32_e32 v119, v0
	v_mov_b32_e32 v124, v0
	v_mov_b32_e32 v125, v0
	v_mov_b32_e32 v126, v0
	v_mov_b32_e32 v127, v0
	s_branch .LBB0_1010

;     ...
;   for (int u = vb; u < nunits; u += ustride) {
;     const int tm = u % nM, tn = u / nM + ((tn_skip >= 0 && u / nM >= tn_skip) ? 1 : 0);
;     const int brow = tn * 256, bcol = tm * 256;
;     const int un = u + ustride;
;     const bool has_next = un < nunits;
;     const int tn_n = un / nM + ((tn_skip >= 0 && un / nM >= tn_skip) ? 1 : 0);
;     const int brow_n = has_next ? tn_n * 256 : brow, bcol_n = has_next ? (un % nM) * 256 : bcol;
.LBB0_1014:
	s_ashr_i32 s1, s0, 31
	s_lshl_b64 s[2:3], s[0:1], 12
	s_or_b32 s31, s0, 0x80
	s_or_b32 s34, s30, 0x80
	s_or_b32 s35, s27, 0x80
	s_or_b32 s36, s29, 0x80
	v_lshl_add_u64 v[132:133], v[130:131], 0, s[2:3]
	s_mov_b32 s1, 0

; __device__ __forceinline__ float siluf_(float x) { return x * __builtin_amdgcn_rcpf(1.f + __expf(-x)); }
;     ...
;     if (MODE == 4) {
;       u16* act = (u16*)(ws + OFF_RA);
;       uint2 opend4[2];
; #pragma unroll
;       for (int bj = 0; bj < 2; ++bj)
; #pragma unroll
;         for (int m = 0; m < 4; ++m)
; #pragma unroll
;           for (int n = 0; n < 2; ++n) {
;             int lane_i = lane_e;
;             asm volatile("" : "+v"(lane_i));
;             const int fr = lane_i & 15, fq = lane_i >> 4;
;             const int nc = tn * 128 + wr * 64 + m * 16 + fq * 4;
;             const int tok = bcol + bj * 128 + wc * 32 + n * 16 + fr;
;             f32x4 g = acc[0][bj][m][n], up = acc[1][bj][m][n];
;             uint2 o;
;             o.x = pk2(siluf_(g[0]) * up[0], siluf_(g[1]) * up[1]);
;             o.y = pk2(siluf_(g[2]) * up[2], siluf_(g[3]) * up[3]);
;             if ((m & 1) == 0) opend4[n] = o;
;             else {
;               const int ncw = tn * 128 + wr * 64 + ((m & ~1) + (fq & 1)) * 16 + (fq & ~1) * 4;
;               *(uint4*)(act + (size_t)tok * DFF + ncw) = swap_pair(opend4[n], o);
;             }
;           }
.LBB0_1018:
	v_mov_b32_e32 v250, 0xbfb8aa3b
	v_mov_b32_e32 v252, 1.0
	s_or_b32 s0, s27, s54
	s_lshl_b32 s1, s28, 7
	s_add_i32 s1, s1, s49
	s_movk_i32 s3, 0x2c00
	v_and_or_b32 v132, v134, 15, s0
	v_and_or_b32 v133, v134, 16, s1
	v_ashrrev_i32_e32 v140, 2, v134
	v_and_b32_e32 v140, -8, v140
	v_add_u32_e32 v133, v133, v140
	v_lshlrev_b32_e32 v133, 1, v133
	v_mad_u32_u24 v247, v132, s3, v133
	v_add_u32_e32 v248, 0x2c000, v247
	v_add_u32_e32 v249, 0x160000, v247
	v_add_u32_e32 v254, 0x18c000, v247
	v_pk_mul_f32 v[132:133], v[124:125], v[250:251] op_sel_hi:[1,0]
	v_pk_mul_f32 v[140:141], v[126:127], v[250:251] op_sel_hi:[1,0]
	v_exp_f32_e32 v132, v132
	v_exp_f32_e32 v133, v133
	v_exp_f32_e32 v140, v140
	v_exp_f32_e32 v141, v141
	v_pk_add_f32 v[132:133], v[132:133], v[252:253] op_sel_hi:[1,0]
	v_pk_add_f32 v[140:141], v[140:141], v[252:253] op_sel_hi:[1,0]
	v_rcp_f32_e32 v132, v132
	v_rcp_f32_e32 v133, v133
	v_rcp_f32_e32 v140, v140
	v_rcp_f32_e32 v141, v141
	v_pk_mul_f32 v[124:125], v[124:125], v[132:133]
	v_pk_mul_f32 v[126:127], v[126:127], v[140:141]
	v_pk_mul_f32 v[124:125], v[124:125], v[120:121]
	v_pk_mul_f32 v[126:127], v[126:127], v[122:123]
	v_cvt_pk_bf16_f32 v124, v124, v125
	v_cvt_pk_bf16_f32 v125, v126, v127
	v_pk_mul_f32 v[132:133], v[108:109], v[250:251] op_sel_hi:[1,0]
	v_pk_mul_f32 v[140:141], v[110:111], v[250:251] op_sel_hi:[1,0]
	v_exp_f32_e32 v132, v132
	v_exp_f32_e32 v133, v133
	v_exp_f32_e32 v140, v140
	v_exp_f32_e32 v141, v141
	v_pk_add_f32 v[132:133], v[132:133], v[252:253] op_sel_hi:[1,0]
	v_pk_add_f32 v[140:141], v[140:141], v[252:253] op_sel_hi:[1,0]
	v_rcp_f32_e32 v132, v132
	v_rcp_f32_e32 v133, v133
	v_rcp_f32_e32 v140, v140
	v_rcp_f32_e32 v141, v141
	v_pk_mul_f32 v[108:109], v[108:109], v[132:133]
	v_pk_mul_f32 v[110:111], v[110:111], v[140:141]
	v_pk_mul_f32 v[108:109], v[108:109], v[104:105]
	v_pk_mul_f32 v[110:111], v[110:111], v[106:107]
	v_cvt_pk_bf16_f32 v126, v108, v109
	v_cvt_pk_bf16_f32 v127, v110, v111
	s_nop 1
	v_permlane16_swap_b32_e32 v125, v127
	v_permlane16_swap_b32_e32 v124, v126
	global_store_dwordx4 v247, v[124:127], s[66:67]
	v_pk_mul_f32 v[132:133], v[116:117], v[250:251] op_sel_hi:[1,0]
	v_pk_mul_f32 v[140:141], v[118:119], v[250:251] op_sel_hi:[1,0]
	v_exp_f32_e32 v132, v132
	v_exp_f32_e32 v133, v133
	v_exp_f32_e32 v140, v140
	v_exp_f32_e32 v141, v141
	v_pk_add_f32 v[132:133], v[132:133], v[252:253] op_sel_hi:[1,0]
	v_pk_add_f32 v[140:141], v[140:141], v[252:253] op_sel_hi:[1,0]
	v_rcp_f32_e32 v132, v132
	v_rcp_f32_e32 v133, v133
	v_rcp_f32_e32 v140, v140
	v_rcp_f32_e32 v141, v141
	v_pk_mul_f32 v[116:117], v[116:117], v[132:133]
	v_pk_mul_f32 v[118:119], v[118:119], v[140:141]
	v_pk_mul_f32 v[116:117], v[116:117], v[112:113]
	v_pk_mul_f32 v[118:119], v[118:119], v[114:115]
	v_cvt_pk_bf16_f32 v116, v116, v117
	v_cvt_pk_bf16_f32 v117, v118, v119
	v_pk_mul_f32 v[132:133], v[100:101], v[250:251] op_sel_hi:[1,0]
	v_pk_mul_f32 v[140:141], v[102:103], v[250:251] op_sel_hi:[1,0]
	v_exp_f32_e32 v132, v132
	v_exp_f32_e32 v133, v133
	v_exp_f32_e32 v140, v140
	v_exp_f32_e32 v141, v141
	v_pk_add_f32 v[132:133], v[132:133], v[252:253] op_sel_hi:[1,0]
	v_pk_add_f32 v[140:141], v[140:141], v[252:253] op_sel_hi:[1,0]
	v_rcp_f32_e32 v132, v132
	v_rcp_f32_e32 v133, v133
	v_rcp_f32_e32 v140, v140
	v_rcp_f32_e32 v141, v141
	v_pk_mul_f32 v[100:101], v[100:101], v[132:133]
	v_pk_mul_f32 v[102:103], v[102:103], v[140:141]
	v_pk_mul_f32 v[100:101], v[100:101], v[96:97]
	v_pk_mul_f32 v[102:103], v[102:103], v[98:99]
	v_cvt_pk_bf16_f32 v118, v100, v101
	v_cvt_pk_bf16_f32 v119, v102, v103
	s_nop 1
	v_permlane16_swap_b32_e32 v117, v119
	v_permlane16_swap_b32_e32 v116, v118
	global_store_dwordx4 v248, v[116:119], s[66:67]
	v_pk_mul_f32 v[132:133], v[92:93], v[250:251] op_sel_hi:[1,0]
	v_pk_mul_f32 v[140:141], v[94:95], v[250:251] op_sel_hi:[1,0]
	v_exp_f32_e32 v132, v132
	v_exp_f32_e32 v133, v133
	v_exp_f32_e32 v140, v140
	v_exp_f32_e32 v141, v141
	v_pk_add_f32 v[132:133], v[132:133], v[252:253] op_sel_hi:[1,0]
	v_pk_add_f32 v[140:141], v[140:141], v[252:253] op_sel_hi:[1,0]
	v_rcp_f32_e32 v132, v132
	v_rcp_f32_e32 v133, v133
	v_rcp_f32_e32 v140, v140
	v_rcp_f32_e32 v141, v141
	v_pk_mul_f32 v[92:93], v[92:93], v[132:133]
	v_pk_mul_f32 v[94:95], v[94:95], v[140:141]
	v_pk_mul_f32 v[92:93], v[92:93], v[88:89]
	v_pk_mul_f32 v[94:95], v[94:95], v[90:91]
	v_cvt_pk_bf16_f32 v92, v92, v93
	v_cvt_pk_bf16_f32 v93, v94, v95
	v_pk_mul_f32 v[132:133], v[76:77], v[250:251] op_sel_hi:[1,0]
	v_pk_mul_f32 v[140:141], v[78:79], v[250:251] op_sel_hi:[1,0]
	v_exp_f32_e32 v132, v132
	v_exp_f32_e32 v133, v133
	v_exp_f32_e32 v140, v140
	v_exp_f32_e32 v141, v141
	v_pk_add_f32 v[132:133], v[132:133], v[252:253] op_sel_hi:[1,0]
	v_pk_add_f32 v[140:141], v[140:141], v[252:253] op_sel_hi:[1,0]
	v_rcp_f32_e32 v132, v132
	v_rcp_f32_e32 v133, v133
	v_rcp_f32_e32 v140, v140
	v_rcp_f32_e32 v141, v141
	v_pk_mul_f32 v[76:77], v[76:77], v[132:133]
	v_pk_mul_f32 v[78:79], v[78:79], v[140:141]
	v_pk_mul_f32 v[76:77], v[76:77], v[72:73]
	v_pk_mul_f32 v[78:79], v[78:79], v[74:75]
	v_cvt_pk_bf16_f32 v94, v76, v77
	v_cvt_pk_bf16_f32 v95, v78, v79
	s_nop 1
	v_permlane16_swap_b32_e32 v93, v95
	v_permlane16_swap_b32_e32 v92, v94
	global_store_dwordx4 v247, v[92:95], s[66:67] offset:64
	v_pk_mul_f32 v[132:133], v[84:85], v[250:251] op_sel_hi:[1,0]
	v_pk_mul_f32 v[140:141], v[86:87], v[250:251] op_sel_hi:[1,0]
	v_exp_f32_e32 v132, v132
	v_exp_f32_e32 v133, v133
	v_exp_f32_e32 v140, v140
	v_exp_f32_e32 v141, v141
	v_pk_add_f32 v[132:133], v[132:133], v[252:253] op_sel_hi:[1,0]
	v_pk_add_f32 v[140:141], v[140:141], v[252:253] op_sel_hi:[1,0]
	v_rcp_f32_e32 v132, v132
; __device__ __forceinline__ float siluf_(float x) { return x * __builtin_amdgcn_rcpf(1.f + __expf(-x)); }
;     ...
;     if (MODE == 4) {
;       u16* act = (u16*)(ws + OFF_RA);
;       uint2 opend4[2];
; #pragma unroll
;       for (int bj = 0; bj < 2; ++bj)
; #pragma unroll
;         for (int m = 0; m < 4; ++m)
; #pragma unroll
;           for (int n = 0; n < 2; ++n) {
;             int lane_i = lane_e;
;             asm volatile("" : "+v"(lane_i));
;             const int fr = lane_i & 15, fq = lane_i >> 4;
;             const int nc = tn * 128 + wr * 64 + m * 16 + fq * 4;
;             const int tok = bcol + bj * 128 + wc * 32 + n * 16 + fr;
;             f32x4 g = acc[0][bj][m][n], up = acc[1][bj][m][n];
;             uint2 o;
;             o.x = pk2(siluf_(g[0]) * up[0], siluf_(g[1]) * up[1]);
;             o.y = pk2(siluf_(g[2]) * up[2], siluf_(g[3]) * up[3]);
;             if ((m & 1) == 0) opend4[n] = o;
;             else {
;               const int ncw = tn * 128 + wr * 64 + ((m & ~1) + (fq & 1)) * 16 + (fq & ~1) * 4;
;               *(uint4*)(act + (size_t)tok * DFF + ncw) = swap_pair(opend4[n], o);
;             }
;           }
	v_rcp_f32_e32 v133, v133
	v_rcp_f32_e32 v140, v140
	v_rcp_f32_e32 v141, v141
	v_pk_mul_f32 v[84:85], v[84:85], v[132:133]
	v_pk_mul_f32 v[86:87], v[86:87], v[140:141]
	v_pk_mul_f32 v[84:85], v[84:85], v[80:81]
	v_pk_mul_f32 v[86:87], v[86:87], v[82:83]
	v_cvt_pk_bf16_f32 v84, v84, v85
	v_cvt_pk_bf16_f32 v85, v86, v87
	v_pk_mul_f32 v[132:133], v[68:69], v[250:251] op_sel_hi:[1,0]
	v_pk_mul_f32 v[140:141], v[70:71], v[250:251] op_sel_hi:[1,0]
	v_exp_f32_e32 v132, v132
	v_exp_f32_e32 v133, v133
	v_exp_f32_e32 v140, v140
	v_exp_f32_e32 v141, v141
	v_pk_add_f32 v[132:133], v[132:133], v[252:253] op_sel_hi:[1,0]
	v_pk_add_f32 v[140:141], v[140:141], v[252:253] op_sel_hi:[1,0]
	v_rcp_f32_e32 v132, v132
	v_rcp_f32_e32 v133, v133
	v_rcp_f32_e32 v140, v140
	v_rcp_f32_e32 v141, v141
	v_pk_mul_f32 v[68:69], v[68:69], v[132:133]
	v_pk_mul_f32 v[70:71], v[70:71], v[140:141]
	v_pk_mul_f32 v[68:69], v[68:69], v[64:65]
	v_pk_mul_f32 v[70:71], v[70:71], v[66:67]
	v_cvt_pk_bf16_f32 v86, v68, v69
	v_cvt_pk_bf16_f32 v87, v70, v71
	s_nop 1
	v_permlane16_swap_b32_e32 v85, v87
	v_permlane16_swap_b32_e32 v84, v86
	global_store_dwordx4 v248, v[84:87], s[66:67] offset:64
	v_pk_mul_f32 v[132:133], v[60:61], v[250:251] op_sel_hi:[1,0]
	v_pk_mul_f32 v[140:141], v[62:63], v[250:251] op_sel_hi:[1,0]
	v_exp_f32_e32 v132, v132
	v_exp_f32_e32 v133, v133
	v_exp_f32_e32 v140, v140
	v_exp_f32_e32 v141, v141
	v_pk_add_f32 v[132:133], v[132:133], v[252:253] op_sel_hi:[1,0]
	v_pk_add_f32 v[140:141], v[140:141], v[252:253] op_sel_hi:[1,0]
	v_rcp_f32_e32 v132, v132
	v_rcp_f32_e32 v133, v133
	v_rcp_f32_e32 v140, v140
	v_rcp_f32_e32 v141, v141
	v_pk_mul_f32 v[60:61], v[60:61], v[132:133]
	v_pk_mul_f32 v[62:63], v[62:63], v[140:141]
	v_pk_mul_f32 v[60:61], v[60:61], v[56:57]
	v_pk_mul_f32 v[62:63], v[62:63], v[58:59]
	v_cvt_pk_bf16_f32 v60, v60, v61
	v_cvt_pk_bf16_f32 v61, v62, v63
	v_pk_mul_f32 v[132:133], v[44:45], v[250:251] op_sel_hi:[1,0]
	v_pk_mul_f32 v[140:141], v[46:47], v[250:251] op_sel_hi:[1,0]
	v_exp_f32_e32 v132, v132
	v_exp_f32_e32 v133, v133
	v_exp_f32_e32 v140, v140
	v_exp_f32_e32 v141, v141
	v_pk_add_f32 v[132:133], v[132:133], v[252:253] op_sel_hi:[1,0]
	v_pk_add_f32 v[140:141], v[140:141], v[252:253] op_sel_hi:[1,0]
	v_rcp_f32_e32 v132, v132
	v_rcp_f32_e32 v133, v133
	v_rcp_f32_e32 v140, v140
	v_rcp_f32_e32 v141, v141
	v_pk_mul_f32 v[44:45], v[44:45], v[132:133]
	v_pk_mul_f32 v[46:47], v[46:47], v[140:141]
	v_pk_mul_f32 v[44:45], v[44:45], v[40:41]
	v_pk_mul_f32 v[46:47], v[46:47], v[42:43]
	v_cvt_pk_bf16_f32 v62, v44, v45
	v_cvt_pk_bf16_f32 v63, v46, v47
	s_nop 1
	v_permlane16_swap_b32_e32 v61, v63
	v_permlane16_swap_b32_e32 v60, v62
	global_store_dwordx4 v249, v[60:63], s[66:67]
	v_pk_mul_f32 v[132:133], v[52:53], v[250:251] op_sel_hi:[1,0]
	v_pk_mul_f32 v[140:141], v[54:55], v[250:251] op_sel_hi:[1,0]
	v_exp_f32_e32 v132, v132
	v_exp_f32_e32 v133, v133
	v_exp_f32_e32 v140, v140
	v_exp_f32_e32 v141, v141
	v_pk_add_f32 v[132:133], v[132:133], v[252:253] op_sel_hi:[1,0]
	v_pk_add_f32 v[140:141], v[140:141], v[252:253] op_sel_hi:[1,0]
	v_rcp_f32_e32 v132, v132
	v_rcp_f32_e32 v133, v133
	v_rcp_f32_e32 v140, v140
	v_rcp_f32_e32 v141, v141
	v_pk_mul_f32 v[52:53], v[52:53], v[132:133]
	v_pk_mul_f32 v[54:55], v[54:55], v[140:141]
	v_pk_mul_f32 v[52:53], v[52:53], v[48:49]
	v_pk_mul_f32 v[54:55], v[54:55], v[50:51]
	v_cvt_pk_bf16_f32 v52, v52, v53
	v_cvt_pk_bf16_f32 v53, v54, v55
	v_pk_mul_f32 v[132:133], v[36:37], v[250:251] op_sel_hi:[1,0]
	v_pk_mul_f32 v[140:141], v[38:39], v[250:251] op_sel_hi:[1,0]
	v_exp_f32_e32 v132, v132
	v_exp_f32_e32 v133, v133
	v_exp_f32_e32 v140, v140
	v_exp_f32_e32 v141, v141
	v_pk_add_f32 v[132:133], v[132:133], v[252:253] op_sel_hi:[1,0]
	v_pk_add_f32 v[140:141], v[140:141], v[252:253] op_sel_hi:[1,0]
	v_rcp_f32_e32 v132, v132
	v_rcp_f32_e32 v133, v133
	v_rcp_f32_e32 v140, v140
	v_rcp_f32_e32 v141, v141
	v_pk_mul_f32 v[36:37], v[36:37], v[132:133]
	v_pk_mul_f32 v[38:39], v[38:39], v[140:141]
	v_pk_mul_f32 v[36:37], v[36:37], v[32:33]
	v_pk_mul_f32 v[38:39], v[38:39], v[34:35]
	v_cvt_pk_bf16_f32 v54, v36, v37
	v_cvt_pk_bf16_f32 v55, v38, v39
	s_nop 1
	v_permlane16_swap_b32_e32 v53, v55
	v_permlane16_swap_b32_e32 v52, v54
	global_store_dwordx4 v254, v[52:55], s[66:67]
	v_pk_mul_f32 v[132:133], v[28:29], v[250:251] op_sel_hi:[1,0]
	v_pk_mul_f32 v[140:141], v[30:31], v[250:251] op_sel_hi:[1,0]
	v_exp_f32_e32 v132, v132
	v_exp_f32_e32 v133, v133
	v_exp_f32_e32 v140, v140
	v_exp_f32_e32 v141, v141
	v_pk_add_f32 v[132:133], v[132:133], v[252:253] op_sel_hi:[1,0]
	v_pk_add_f32 v[140:141], v[140:141], v[252:253] op_sel_hi:[1,0]
	v_rcp_f32_e32 v132, v132
	v_rcp_f32_e32 v133, v133
	v_rcp_f32_e32 v140, v140
	v_rcp_f32_e32 v141, v141
	v_pk_mul_f32 v[28:29], v[28:29], v[132:133]
	v_pk_mul_f32 v[30:31], v[30:31], v[140:141]
	v_pk_mul_f32 v[28:29], v[28:29], v[24:25]
	v_pk_mul_f32 v[30:31], v[30:31], v[26:27]
	v_cvt_pk_bf16_f32 v28, v28, v29
	v_cvt_pk_bf16_f32 v29, v30, v31
	v_pk_mul_f32 v[132:133], v[12:13], v[250:251] op_sel_hi:[1,0]
	v_pk_mul_f32 v[140:141], v[14:15], v[250:251] op_sel_hi:[1,0]
	v_exp_f32_e32 v132, v132
	v_exp_f32_e32 v133, v133
	v_exp_f32_e32 v140, v140
	v_exp_f32_e32 v141, v141
	v_pk_add_f32 v[132:133], v[132:133], v[252:253] op_sel_hi:[1,0]
; __device__ __forceinline__ float siluf_(float x) { return x * __builtin_amdgcn_rcpf(1.f + __expf(-x)); }
;     ...
; #pragma unroll
;     for (int a = 0; a < 2; ++a)
; #pragma unroll
;       for (int b = 0; b < 2; ++b)
; #pragma unroll
;         for (int m = 0; m < 4; ++m)
; #pragma unroll
;           for (int n = 0; n < 2; ++n) acc[a][b][m][n] = f32x4{0.f, 0.f, 0.f, 0.f};
;     ...
;     if (MODE == 4) {
;       u16* act = (u16*)(ws + OFF_RA);
;       uint2 opend4[2];
; #pragma unroll
;       for (int bj = 0; bj < 2; ++bj)
; #pragma unroll
;         for (int m = 0; m < 4; ++m)
; #pragma unroll
;           for (int n = 0; n < 2; ++n) {
;             int lane_i = lane_e;
;             asm volatile("" : "+v"(lane_i));
;             const int fr = lane_i & 15, fq = lane_i >> 4;
;             const int nc = tn * 128 + wr * 64 + m * 16 + fq * 4;
;             const int tok = bcol + bj * 128 + wc * 32 + n * 16 + fr;
;             f32x4 g = acc[0][bj][m][n], up = acc[1][bj][m][n];
;             uint2 o;
;             o.x = pk2(siluf_(g[0]) * up[0], siluf_(g[1]) * up[1]);
;             o.y = pk2(siluf_(g[2]) * up[2], siluf_(g[3]) * up[3]);
;             if ((m & 1) == 0) opend4[n] = o;
;             else {
;               const int ncw = tn * 128 + wr * 64 + ((m & ~1) + (fq & 1)) * 16 + (fq & ~1) * 4;
;               *(uint4*)(act + (size_t)tok * DFF + ncw) = swap_pair(opend4[n], o);
;             }
;           }
	v_pk_add_f32 v[140:141], v[140:141], v[252:253] op_sel_hi:[1,0]
	v_rcp_f32_e32 v132, v132
	v_rcp_f32_e32 v133, v133
	v_rcp_f32_e32 v140, v140
	v_rcp_f32_e32 v141, v141
	v_pk_mul_f32 v[12:13], v[12:13], v[132:133]
	v_pk_mul_f32 v[14:15], v[14:15], v[140:141]
	v_pk_mul_f32 v[12:13], v[12:13], v[8:9]
	v_pk_mul_f32 v[14:15], v[14:15], v[10:11]
	v_cvt_pk_bf16_f32 v30, v12, v13
	v_cvt_pk_bf16_f32 v31, v14, v15
	s_nop 1
	v_permlane16_swap_b32_e32 v29, v31
	v_permlane16_swap_b32_e32 v28, v30
	global_store_dwordx4 v249, v[28:31], s[66:67] offset:64
	v_pk_mul_f32 v[132:133], v[20:21], v[250:251] op_sel_hi:[1,0]
	v_pk_mul_f32 v[140:141], v[22:23], v[250:251] op_sel_hi:[1,0]
	v_exp_f32_e32 v132, v132
	v_exp_f32_e32 v133, v133
	v_exp_f32_e32 v140, v140
	v_exp_f32_e32 v141, v141
	v_pk_add_f32 v[132:133], v[132:133], v[252:253] op_sel_hi:[1,0]
	v_pk_add_f32 v[140:141], v[140:141], v[252:253] op_sel_hi:[1,0]
	v_rcp_f32_e32 v132, v132
	v_rcp_f32_e32 v133, v133
	v_rcp_f32_e32 v140, v140
	v_rcp_f32_e32 v141, v141
	v_pk_mul_f32 v[20:21], v[20:21], v[132:133]
	v_pk_mul_f32 v[22:23], v[22:23], v[140:141]
	v_pk_mul_f32 v[20:21], v[20:21], v[16:17]
	v_pk_mul_f32 v[22:23], v[22:23], v[18:19]
	v_cvt_pk_bf16_f32 v20, v20, v21
	v_cvt_pk_bf16_f32 v21, v22, v23
	v_pk_mul_f32 v[132:133], v[4:5], v[250:251] op_sel_hi:[1,0]
	v_pk_mul_f32 v[140:141], v[6:7], v[250:251] op_sel_hi:[1,0]
	v_exp_f32_e32 v132, v132
	v_exp_f32_e32 v133, v133
	v_exp_f32_e32 v140, v140
	v_exp_f32_e32 v141, v141
	v_pk_add_f32 v[132:133], v[132:133], v[252:253] op_sel_hi:[1,0]
	v_pk_add_f32 v[140:141], v[140:141], v[252:253] op_sel_hi:[1,0]
	v_rcp_f32_e32 v132, v132
	v_rcp_f32_e32 v133, v133
	v_rcp_f32_e32 v140, v140
	v_rcp_f32_e32 v141, v141
	v_pk_mul_f32 v[4:5], v[4:5], v[132:133]
	v_pk_mul_f32 v[6:7], v[6:7], v[140:141]
	v_pk_mul_f32 v[4:5], v[4:5], v[0:1]
	v_pk_mul_f32 v[6:7], v[6:7], v[2:3]
	v_cvt_pk_bf16_f32 v22, v4, v5
	v_cvt_pk_bf16_f32 v23, v6, v7
	s_nop 1
	v_permlane16_swap_b32_e32 v21, v23
	v_permlane16_swap_b32_e32 v20, v22
	global_store_dwordx4 v254, v[20:23], s[66:67] offset:64
	s_nop 1
	v_mov_b32_e32 v0, 0
	v_mov_b32_e32 v1, v0
	v_mov_b32_e32 v2, v0
	v_mov_b32_e32 v3, v0
	v_mov_b32_e32 v8, v0
	v_mov_b32_e32 v9, v0
	v_mov_b32_e32 v10, v0
	v_mov_b32_e32 v11, v0
	v_mov_b32_e32 v16, v0
	v_mov_b32_e32 v17, v0
	v_mov_b32_e32 v18, v0
	v_mov_b32_e32 v19, v0
	v_mov_b32_e32 v24, v0
	v_mov_b32_e32 v25, v0
	v_mov_b32_e32 v26, v0
	v_mov_b32_e32 v27, v0
	v_mov_b32_e32 v32, v0
	v_mov_b32_e32 v33, v0
	v_mov_b32_e32 v34, v0
	v_mov_b32_e32 v35, v0
	v_mov_b32_e32 v40, v0
	v_mov_b32_e32 v41, v0
	v_mov_b32_e32 v42, v0
	v_mov_b32_e32 v43, v0
	v_mov_b32_e32 v48, v0
	v_mov_b32_e32 v49, v0
	v_mov_b32_e32 v50, v0
	v_mov_b32_e32 v51, v0
	v_mov_b32_e32 v56, v0
	v_mov_b32_e32 v57, v0
	v_mov_b32_e32 v58, v0
	v_mov_b32_e32 v59, v0
	v_mov_b32_e32 v64, v0
	v_mov_b32_e32 v65, v0
	v_mov_b32_e32 v66, v0
	v_mov_b32_e32 v67, v0
	v_mov_b32_e32 v72, v0
	v_mov_b32_e32 v73, v0
	v_mov_b32_e32 v74, v0
	v_mov_b32_e32 v75, v0
	v_mov_b32_e32 v80, v0
	v_mov_b32_e32 v81, v0
	v_mov_b32_e32 v82, v0
	v_mov_b32_e32 v83, v0
	v_mov_b32_e32 v88, v0
	v_mov_b32_e32 v89, v0
	v_mov_b32_e32 v90, v0
	v_mov_b32_e32 v91, v0
	v_mov_b32_e32 v96, v0
	v_mov_b32_e32 v97, v0
	v_mov_b32_e32 v98, v0
	v_mov_b32_e32 v99, v0
	v_mov_b32_e32 v104, v0
	v_mov_b32_e32 v105, v0
	v_mov_b32_e32 v106, v0
	v_mov_b32_e32 v107, v0
	v_mov_b32_e32 v112, v0
	v_mov_b32_e32 v113, v0
	v_mov_b32_e32 v114, v0
	v_mov_b32_e32 v115, v0
	v_mov_b32_e32 v120, v0
	v_mov_b32_e32 v121, v0
	v_mov_b32_e32 v122, v0
	v_mov_b32_e32 v123, v0
	v_mov_b32_e32 v4, v0
	v_mov_b32_e32 v5, v0
	v_mov_b32_e32 v6, v0
	v_mov_b32_e32 v7, v0
	v_mov_b32_e32 v12, v0
	v_mov_b32_e32 v13, v0
	v_mov_b32_e32 v14, v0
	v_mov_b32_e32 v15, v0
	v_mov_b32_e32 v20, v0
	v_mov_b32_e32 v21, v0
	v_mov_b32_e32 v22, v0
	v_mov_b32_e32 v23, v0
	v_mov_b32_e32 v28, v0
	v_mov_b32_e32 v29, v0
	v_mov_b32_e32 v30, v0
	v_mov_b32_e32 v31, v0
	v_mov_b32_e32 v36, v0
	v_mov_b32_e32 v37, v0
	v_mov_b32_e32 v38, v0
	v_mov_b32_e32 v39, v0
	v_mov_b32_e32 v44, v0
	v_mov_b32_e32 v45, v0
	v_mov_b32_e32 v46, v0
	v_mov_b32_e32 v47, v0
	v_mov_b32_e32 v52, v0
	v_mov_b32_e32 v53, v0
	v_mov_b32_e32 v54, v0
	v_mov_b32_e32 v55, v0
	v_mov_b32_e32 v60, v0
	v_mov_b32_e32 v61, v0
	v_mov_b32_e32 v62, v0
	v_mov_b32_e32 v63, v0
	v_mov_b32_e32 v68, v0
	v_mov_b32_e32 v69, v0
	v_mov_b32_e32 v70, v0
	v_mov_b32_e32 v71, v0
	v_mov_b32_e32 v76, v0
	v_mov_b32_e32 v77, v0
	v_mov_b32_e32 v78, v0
	v_mov_b32_e32 v79, v0
	v_mov_b32_e32 v84, v0
	v_mov_b32_e32 v85, v0
	v_mov_b32_e32 v86, v0
	v_mov_b32_e32 v87, v0
	v_mov_b32_e32 v92, v0
	v_mov_b32_e32 v93, v0
	v_mov_b32_e32 v94, v0
	v_mov_b32_e32 v95, v0
	v_mov_b32_e32 v100, v0
	v_mov_b32_e32 v101, v0
	v_mov_b32_e32 v102, v0
	v_mov_b32_e32 v103, v0
	v_mov_b32_e32 v108, v0
	v_mov_b32_e32 v109, v0
	v_mov_b32_e32 v110, v0
	v_mov_b32_e32 v111, v0
	v_mov_b32_e32 v116, v0
	v_mov_b32_e32 v117, v0
	v_mov_b32_e32 v118, v0
	v_mov_b32_e32 v119, v0
	v_mov_b32_e32 v124, v0
	v_mov_b32_e32 v125, v0
	v_mov_b32_e32 v126, v0
	v_mov_b32_e32 v127, v0
	s_waitcnt vmcnt(0)
	s_and_b64 s[0:1], s[56:57], s[8:9]
	s_andn2_b64 vcc, exec, s[0:1]
	s_cbranch_vccnz .LBB0_1009
	s_barrier
	s_branch .LBB0_1009

; #define STAGE(P_, BASE, br, kt) do { const u16* _gb = (BASE) + (long)(br) * K + (long)(kt) * BK; \
;     _Pragma("unroll") for (int _i = 0; _i < 2; ++_i) { \
;       __builtin_amdgcn_global_load_lds((const unsigned*)(_gb + (long)_i * 64 * K + lane_off), \
;         (unsigned*)((char*)(P_) + lds_wbase + _i * 8192), 16, 0, 0); } } while (0)
; #define WAIT_V(n) asm volatile("s_waitcnt vmcnt(" #n ")" ::: "memory")
; #define BAR __builtin_amdgcn_s_barrier()
; template <int PRE> ...
;     ...
;   const int wid = wvi, lane = tid & 63, wr = wid >> 2, wc = wid & 3, fr = lane & 15, fq = lane >> 4;
;   bf16x8 At[4][2], B0[2][2], B1[2][2];
;   const int nt = K / BK;
;   const unsigned lds_wbase = wid * 1024;
;   unsigned lane_off;
;   { int _r, _c; stage_rc(tid * 16, _r, _c); lane_off = (unsigned)(_r * K + _c); }
;     ...
;   if (PRE == 2) {
;     STAGE(SB(0, 0), Bt, bcol, 0); STAGE(SA(0, 0), A, brow, 0);
;     STAGE(SB(0, 1), Bt, bcol + HALF, 0); STAGE(SA(0, 1), A, brow + HALF, 0);
;     if (wr == 1) BAR;
;     WAIT_V(4); BAR;
;     STAGE(SB(1, 0), Bt, bcol, 1); STAGE(SA(1, 0), A, brow, 1); STAGE(SB(1, 1), Bt, bcol + HALF, 1);
;     WAIT_V(6); BAR;
;     return;
;   }
;     ...
; #pragma unroll
;     for (int a = 0; a < 2; ++a)
; #pragma unroll
;       for (int b = 0; b < 2; ++b)
; #pragma unroll
;         for (int m = 0; m < 4; ++m)
; #pragma unroll
;           for (int n = 0; n < 2; ++n) acc[a][b][m][n] = f32x4{0.f, 0.f, 0.f, 0.f};
.LBB0_1076:
	s_mov_b64 s[6:7], 0x80
	s_add_i32 s14, s2, 0x18000
	v_lshl_add_u64 v[10:11], v[0:1], 0, s[6:7]
	s_mov_b32 m0, s14
	s_mov_b64 s[8:9], 0xb0080
	s_add_i32 s15, s2, 0x1a000
	s_waitcnt vmcnt(4)
	s_barrier
	global_load_lds_dwordx4 v[10:11], off
	v_lshl_add_u64 v[0:1], v[0:1], 0, s[8:9]
	s_mov_b32 m0, s15
	s_add_i32 s16, s2, 0x8000
	global_load_lds_dwordx4 v[0:1], off
	v_lshl_add_u64 v[0:1], v[2:3], 0, s[6:7]
	s_mov_b32 m0, s16
	s_add_i32 s17, s2, 0xa000
	global_load_lds_dwordx4 v[0:1], off
	v_lshl_add_u64 v[0:1], v[2:3], 0, s[8:9]
	s_mov_b32 m0, s17
	s_add_i32 s20, s2, 0x1c000
	global_load_lds_dwordx4 v[0:1], off
	v_lshl_add_u64 v[0:1], v[144:145], 1, s[0:1]
	s_mov_b64 s[0:1], 0x160080
	v_lshl_add_u64 v[2:3], v[0:1], 0, s[0:1]
	s_mov_b32 m0, s20
	s_mov_b64 s[0:1], 0x210080
	s_add_i32 s21, s2, 0x1e000
	global_load_lds_dwordx4 v[2:3], off
	v_lshl_add_u64 v[0:1], v[0:1], 0, s[0:1]
	s_mov_b32 m0, s21
	v_lshlrev_b32_e32 v3, 2, v8
	global_load_lds_dwordx4 v[0:1], off
	v_and_b32_e32 v0, 15, v8
	v_and_b32_e32 v1, 48, v8
	v_lshlrev_b32_e32 v2, 6, v0
	v_and_b32_e32 v3, 32, v3
	v_readlane_b32 s0, v246, 52
	v_bitop3_b32 v151, v2, v3, v1 bitop3:0x36
	v_and_b32_e32 v150, 63, v8
	v_or_b32_e32 v2, s0, v0
	v_lshlrev_b32_e32 v3, 6, v2
	v_lshlrev_b32_e32 v2, 2, v2
	v_and_b32_e32 v3, 0x3c0, v3
	v_and_b32_e32 v2, 32, v2
	v_readlane_b32 s0, v246, 51
	v_bitop3_b32 v2, v3, v2, v1 bitop3:0x36
	s_waitcnt vmcnt(6)
	s_barrier
	v_or_b32_e32 v3, s0, v0
	v_lshlrev_b32_e32 v8, 6, v3
	v_lshlrev_b32_e32 v3, 2, v3
	v_and_b32_e32 v8, 0x3c0, v8
	v_and_b32_e32 v3, 32, v3
	v_readlane_b32 s0, v246, 53
	v_bitop3_b32 v3, v8, v3, v1 bitop3:0x36
	s_nop 0
	v_or_b32_e32 v8, s0, v0
	v_lshlrev_b32_e32 v9, 6, v8
	v_lshlrev_b32_e32 v8, 2, v8
	v_readlane_b32 s0, v246, 54
	v_and_b32_e32 v9, 0x3c0, v9
	v_and_b32_e32 v8, 32, v8
	v_or_b32_e32 v0, s0, v0
	v_bitop3_b32 v8, v9, v8, v1 bitop3:0x36
	v_lshlrev_b32_e32 v9, 6, v0
	v_lshlrev_b32_e32 v0, 2, v0
	v_and_b32_e32 v9, 0x3c0, v9
	v_and_b32_e32 v0, 32, v0
	s_movk_i32 s0, 0x1600
	v_bitop3_b32 v9, v9, v0, v1 bitop3:0x36
	v_lshrrev_b32_e32 v1, 1, v4
	v_mul_lo_u32 v0, v6, s0
	s_mov_b32 s0, 0x16000
	v_mad_u64_u32 v[0:1], s[0:1], v1, s0, v[0:1]
	v_or_b32_e32 v0, v0, v5
	v_readlane_b32 s0, v244, 38
	v_add_u32_sdwa v144, v0, sext(v7) dst_sel:DWORD dst_unused:UNUSED_PAD src0_sel:DWORD src1_sel:WORD_0
	v_readlane_b32 s1, v244, 39
	s_nop 1
	v_lshl_add_u64 v[132:133], v[144:145], 1, s[0:1]
	v_readlane_b32 s0, v244, 12
	s_nop 1
	v_add_u32_e32 v144, s0, v2
	v_readlane_b32 s0, v244, 13
	s_nop 1
	v_add_u32_e32 v152, s0, v3
	v_readlane_b32 s0, v244, 14
	s_nop 1
	v_add_u32_e32 v153, s0, v8
	v_readlane_b32 s0, v244, 15
	s_nop 1
	v_add_u32_e32 v154, s0, v9
	v_mov_b32_e32 v0, 0
	v_mov_b32_e32 v1, v0
	v_mov_b32_e32 v2, v0
	v_mov_b32_e32 v3, v0
	v_mov_b32_e32 v4, v0
	v_mov_b32_e32 v5, v0
	v_mov_b32_e32 v6, v0
	v_mov_b32_e32 v7, v0
	v_mov_b32_e32 v8, v0
	v_mov_b32_e32 v9, v0
	v_mov_b32_e32 v10, v0
	v_mov_b32_e32 v11, v0
	v_mov_b32_e32 v12, v0
	v_mov_b32_e32 v13, v0
	v_mov_b32_e32 v14, v0
	v_mov_b32_e32 v15, v0
	v_mov_b32_e32 v16, v0
	v_mov_b32_e32 v17, v0
	v_mov_b32_e32 v18, v0
	v_mov_b32_e32 v19, v0
	v_mov_b32_e32 v20, v0
	v_mov_b32_e32 v21, v0
	v_mov_b32_e32 v22, v0
	v_mov_b32_e32 v23, v0
	v_mov_b32_e32 v24, v0
	v_mov_b32_e32 v25, v0
	v_mov_b32_e32 v26, v0
	v_mov_b32_e32 v27, v0
	v_mov_b32_e32 v28, v0
	v_mov_b32_e32 v29, v0
	v_mov_b32_e32 v30, v0
	v_mov_b32_e32 v31, v0
	v_mov_b32_e32 v32, v0
	v_mov_b32_e32 v33, v0
	v_mov_b32_e32 v34, v0
	v_mov_b32_e32 v35, v0
	v_mov_b32_e32 v36, v0
	v_mov_b32_e32 v37, v0
	v_mov_b32_e32 v38, v0
	v_mov_b32_e32 v39, v0
	v_mov_b32_e32 v40, v0
	v_mov_b32_e32 v41, v0
	v_mov_b32_e32 v42, v0
	v_mov_b32_e32 v43, v0
	v_mov_b32_e32 v44, v0
	v_mov_b32_e32 v45, v0
	v_mov_b32_e32 v46, v0
	v_mov_b32_e32 v47, v0
	v_mov_b32_e32 v48, v0
	v_mov_b32_e32 v49, v0
	v_mov_b32_e32 v50, v0
	v_mov_b32_e32 v51, v0
	v_mov_b32_e32 v52, v0
	v_mov_b32_e32 v53, v0
	v_mov_b32_e32 v54, v0
	v_mov_b32_e32 v55, v0
	v_mov_b32_e32 v56, v0
	v_mov_b32_e32 v57, v0
	v_mov_b32_e32 v58, v0
	v_mov_b32_e32 v59, v0
	v_mov_b32_e32 v60, v0
	v_mov_b32_e32 v61, v0
	v_mov_b32_e32 v62, v0
	v_mov_b32_e32 v63, v0
	v_mov_b32_e32 v64, v0
	v_mov_b32_e32 v65, v0
	v_mov_b32_e32 v66, v0
	v_mov_b32_e32 v67, v0
	v_mov_b32_e32 v68, v0
	v_mov_b32_e32 v69, v0
	v_mov_b32_e32 v70, v0
	v_mov_b32_e32 v71, v0
	v_mov_b32_e32 v72, v0
	v_mov_b32_e32 v73, v0
	v_mov_b32_e32 v74, v0
	v_mov_b32_e32 v75, v0
	v_mov_b32_e32 v76, v0
	v_mov_b32_e32 v77, v0
	v_mov_b32_e32 v78, v0
	v_mov_b32_e32 v79, v0
	v_mov_b32_e32 v80, v0
	v_mov_b32_e32 v81, v0
	v_mov_b32_e32 v82, v0
	v_mov_b32_e32 v83, v0
	v_mov_b32_e32 v84, v0
	v_mov_b32_e32 v85, v0
	v_mov_b32_e32 v86, v0
	v_mov_b32_e32 v87, v0
	v_mov_b32_e32 v88, v0
	v_mov_b32_e32 v89, v0
	v_mov_b32_e32 v90, v0
	v_mov_b32_e32 v91, v0
	v_mov_b32_e32 v92, v0
	v_mov_b32_e32 v93, v0
	v_mov_b32_e32 v94, v0
	v_mov_b32_e32 v95, v0
	v_mov_b32_e32 v96, v0
	v_mov_b32_e32 v97, v0
	v_mov_b32_e32 v98, v0
	v_mov_b32_e32 v99, v0
	v_mov_b32_e32 v100, v0
	v_mov_b32_e32 v101, v0
	v_mov_b32_e32 v102, v0
	v_mov_b32_e32 v103, v0
	v_mov_b32_e32 v104, v0
	v_mov_b32_e32 v105, v0
	v_mov_b32_e32 v106, v0
	v_mov_b32_e32 v107, v0
	v_mov_b32_e32 v108, v0
	v_mov_b32_e32 v109, v0
	v_mov_b32_e32 v110, v0
	v_mov_b32_e32 v111, v0
	v_mov_b32_e32 v112, v0
	v_mov_b32_e32 v113, v0
	v_mov_b32_e32 v114, v0
	v_mov_b32_e32 v115, v0
	v_mov_b32_e32 v116, v0
	v_mov_b32_e32 v117, v0
	v_mov_b32_e32 v118, v0
	v_mov_b32_e32 v119, v0
	v_mov_b32_e32 v120, v0
	v_mov_b32_e32 v121, v0
	v_mov_b32_e32 v122, v0
	v_mov_b32_e32 v123, v0
	v_mov_b32_e32 v124, v0
	v_mov_b32_e32 v125, v0
	v_mov_b32_e32 v126, v0
	v_mov_b32_e32 v127, v0
	s_branch .LBB0_1078

;     ...
;   for (int u = vb; u < nunits; u += ustride) {
;     const int tm = u % nM, tn = u / nM + ((tn_skip >= 0 && u / nM >= tn_skip) ? 1 : 0);
;     const int brow = tn * 256, bcol = tm * 256;
;     const int un = u + ustride;
;     const bool has_next = un < nunits;
;     const int tn_n = un / nM + ((tn_skip >= 0 && un / nM >= tn_skip) ? 1 : 0);
;     const int brow_n = has_next ? tn_n * 256 : brow, bcol_n = has_next ? (un % nM) * 256 : bcol;
.LBB0_1082:
	s_or_b32 s27, s23, 0x80
	s_or_b32 s28, s26, 0x80
	s_or_b32 s29, s24, 0x80
	s_or_b32 s30, s25, 0x80
	v_mad_i64_i32 v[128:129], s[0:1], s23, v209, v[132:133]
	s_mov_b32 s31, 0
	s_mov_b64 s[40:41], 0xb0000

;     ...
;               const int nc = brow + ai * 128 + wr * 64 + m * 16 + fq * 4;
;               const int tok = bcol + bj * 128 + wc * 32 + n * 16 + fr;
;               const int ncw = brow + ai * 128 + wr * 64 + ((m & ~1) + (fq & 1)) * 16 + (fq & ~1) * 4;
;     ...
;               f32x4 v = acc[ai][bj][m][n];
;               if (MODE == 0) {
;                 if (tn == 52) {
;                   if (ai == 0) *(float4*)((float*)(ws + OFF_DTR) + (size_t)tok * 128 + (nc - 13312)) = make_float4(v[0], v[1], v[2], v[3]);
;                 } else {
;                   u16* dst; int ld, c0;
;                   if (tn < 16) { dst = (u16*)(ws + OFF_Z); ld = 4096; c0 = 0; }
;                   else if (tn < 40) { dst = (u16*)(ws + OFF_RA); ld = 6144; c0 = 4096; }
;                   else if (tn < 48) { dst = (u16*)(ws + OFF_Q); ld = 2048; c0 = 10240; }
;                   else if (tn < 50) { dst = (u16*)(ws + OFF_K); ld = 512; c0 = 12288; }
;                   else { dst = (u16*)(ws + OFF_V); ld = 512; c0 = 12800; }
;                   uint2 o; o.x = pk2(v[0], v[1]); o.y = pk2(v[2], v[3]);
;                   WIDE_STORE(dst, ld, c0, o);
;                 }
;               } else if (MODE == 1) {
;                 uint2 o; o.x = pk2(sigmoidf_(v[0]), sigmoidf_(v[1])); o.y = pk2(sigmoidf_(v[2]), sigmoidf_(v[3]));
;                 WIDE_STORE((u16*)outp, 4096, 0, o);
;               } else if (MODE == 2) {
;                 const u16* gate = (const u16*)outp;
;                 uint2 ga = *(const uint2*)(gate + (size_t)tok * 4096 + nc);
;                 uint2 p1; p1.x = pk2(v[0] * bflo(ga.x), v[1] * bfhi(ga.x)); p1.y = pk2(v[2] * bflo(ga.y), v[3] * bfhi(ga.y));
;                 *(uint2*)((u16*)(ws + OFF_YB) + (size_t)tok * DM + nc) = p1;
;               } else if (MODE == 6) {
;                 const u16* gate = (const u16*)outp;
;                 uint2 gb = *(const uint2*)(gate + (size_t)tok * 4096 + 2048 + nc);
;                 const uint2 p1 = *(const uint2*)((const u16*)(ws + OFF_YB) + (size_t)tok * DM + nc);
;                 uint2 o;
;                 o.x = pk2(bflo(p1.x) + v[0] * bflo(gb.x), bfhi(p1.x) + v[1] * bfhi(gb.x));
;                 o.y = pk2(bflo(p1.y) + v[2] * bflo(gb.y), bfhi(p1.y) + v[3] * bfhi(gb.y));
;                 WIDE_STORE((u16*)(ws + OFF_RB + 128 * MiB), DM, 0, o);
;               } else if (MODE == 3) {
.LBB0_1086:
	v_readlane_b32 s26, v245, 25
	v_readlane_b32 s27, v245, 26
	v_readlane_b32 s34, v243, 2
	v_readlane_b32 s31, v244, 61
	v_readlane_b32 s35, v243, 3
	s_add_i32 s0, s23, s49
	v_and_b32_e32 v172, 15, v150
	v_or_b32_e32 v172, s54, v172
	v_or_b32_e32 v172, s24, v172
	v_lshrrev_b32_e32 v173, 2, v150
	v_and_b32_e32 v174, -4, v173
	v_add_u32_e32 v174, s0, v174
	v_and_b32_e32 v173, -8, v173
	v_and_b32_e32 v175, 16, v150
	v_add3_u32 v173, v173, v175, s0
	v_lshlrev_b32_e32 v175, 12, v172
	v_lshl_add_u32 v134, v174, 1, v175
	v_add_u32_e32 v135, 0x10000, v134
	v_add_u32_e32 v136, 0x80000, v134
	v_add_u32_e32 v137, 0x90000, v134
	v_lshlrev_b32_e32 v175, 12, v172
	v_lshl_add_u32 v138, v173, 1, v175
	v_add_u32_e32 v139, 0x10000, v138
	v_add_u32_e32 v140, 0x80000, v138
	v_add_u32_e32 v141, 0x90000, v138
	global_load_dwordx2 v[210:211], v134, s[26:27] offset:0
	global_load_dwordx2 v[212:213], v134, s[26:27] offset:32
	global_load_dwordx2 v[214:215], v134, s[26:27] offset:64
	global_load_dwordx2 v[216:217], v134, s[26:27] offset:96
	global_load_dwordx2 v[218:219], v135, s[26:27] offset:0
	global_load_dwordx2 v[220:221], v135, s[26:27] offset:32
	global_load_dwordx2 v[222:223], v135, s[26:27] offset:64
	global_load_dwordx2 v[224:225], v135, s[26:27] offset:96
	global_load_dwordx2 v[226:227], v136, s[26:27] offset:0
	global_load_dwordx2 v[228:229], v136, s[26:27] offset:32
	global_load_dwordx2 v[230:231], v136, s[26:27] offset:64
	global_load_dwordx2 v[232:233], v136, s[26:27] offset:96
	global_load_dwordx2 v[234:235], v137, s[26:27] offset:0
	global_load_dwordx2 v[236:237], v137, s[26:27] offset:32
	global_load_dwordx2 v[238:239], v137, s[26:27] offset:64
	global_load_dwordx2 v[240:241], v137, s[26:27] offset:96
	s_waitcnt vmcnt(15)
	v_lshlrev_b32_e32 v168, 16, v210
	v_and_b32_e32 v169, 0xffff0000, v210
	v_lshlrev_b32_e32 v170, 16, v211
	v_and_b32_e32 v171, 0xffff0000, v211
	v_pk_add_f32 v[124:125], v[124:125], v[168:169]
	v_pk_add_f32 v[126:127], v[126:127], v[170:171]
	global_load_dwordx2 v[210:211], v134, s[26:27] offset:256
	s_waitcnt vmcnt(15)
	v_lshlrev_b32_e32 v168, 16, v212
	v_and_b32_e32 v169, 0xffff0000, v212
	v_lshlrev_b32_e32 v170, 16, v213
	v_and_b32_e32 v171, 0xffff0000, v213
	v_pk_add_f32 v[116:117], v[116:117], v[168:169]
	v_pk_add_f32 v[118:119], v[118:119], v[170:171]
	global_load_dwordx2 v[212:213], v134, s[26:27] offset:288
	s_waitcnt vmcnt(15)
	v_lshlrev_b32_e32 v168, 16, v214
	v_and_b32_e32 v169, 0xffff0000, v214
	v_lshlrev_b32_e32 v170, 16, v215
	v_and_b32_e32 v171, 0xffff0000, v215
	v_pk_add_f32 v[108:109], v[108:109], v[168:169]
	v_pk_add_f32 v[110:111], v[110:111], v[170:171]
	global_load_dwordx2 v[214:215], v134, s[26:27] offset:320
	s_waitcnt vmcnt(15)
	v_lshlrev_b32_e32 v168, 16, v216
	v_and_b32_e32 v169, 0xffff0000, v216
	v_lshlrev_b32_e32 v170, 16, v217
	v_and_b32_e32 v171, 0xffff0000, v217
	v_pk_add_f32 v[100:101], v[100:101], v[168:169]
	v_pk_add_f32 v[102:103], v[102:103], v[170:171]
	global_load_dwordx2 v[216:217], v134, s[26:27] offset:352
	s_nop 0
	v_cvt_pk_bf16_f32 v124, v124, v125
	v_cvt_pk_bf16_f32 v125, v126, v127
	v_cvt_pk_bf16_f32 v126, v116, v117
	v_cvt_pk_bf16_f32 v127, v118, v119
	v_cvt_pk_bf16_f32 v108, v108, v109
	v_cvt_pk_bf16_f32 v109, v110, v111
	v_cvt_pk_bf16_f32 v110, v100, v101
	v_cvt_pk_bf16_f32 v111, v102, v103
	s_nop 1
	v_permlane16_swap_b32_e32 v124, v126
	v_permlane16_swap_b32_e32 v125, v127
	v_permlane16_swap_b32_e32 v108, v110
	v_permlane16_swap_b32_e32 v109, v111
	global_store_dwordx4 v138, v[124:127], s[26:27] offset:0
	global_store_dwordx4 v138, v[108:111], s[26:27] offset:64
	s_waitcnt vmcnt(17)
	v_lshlrev_b32_e32 v168, 16, v218
	v_and_b32_e32 v169, 0xffff0000, v218
	v_lshlrev_b32_e32 v170, 16, v219
	v_and_b32_e32 v171, 0xffff0000, v219
	v_pk_add_f32 v[120:121], v[120:121], v[168:169]
	v_pk_add_f32 v[122:123], v[122:123], v[170:171]
	global_load_dwordx2 v[218:219], v135, s[26:27] offset:256
	s_waitcnt vmcnt(17)
	v_lshlrev_b32_e32 v168, 16, v220
	v_and_b32_e32 v169, 0xffff0000, v220
	v_lshlrev_b32_e32 v170, 16, v221
	v_and_b32_e32 v171, 0xffff0000, v221
	v_pk_add_f32 v[112:113], v[112:113], v[168:169]
	v_pk_add_f32 v[114:115], v[114:115], v[170:171]
	global_load_dwordx2 v[220:221], v135, s[26:27] offset:288
	s_waitcnt vmcnt(17)
	v_lshlrev_b32_e32 v168, 16, v222
	v_and_b32_e32 v169, 0xffff0000, v222
	v_lshlrev_b32_e32 v170, 16, v223
	v_and_b32_e32 v171, 0xffff0000, v223
	v_pk_add_f32 v[104:105], v[104:105], v[168:169]
	v_pk_add_f32 v[106:107], v[106:107], v[170:171]
	global_load_dwordx2 v[222:223], v135, s[26:27] offset:320
	s_waitcnt vmcnt(17)
	v_lshlrev_b32_e32 v168, 16, v224
	v_and_b32_e32 v169, 0xffff0000, v224
	v_lshlrev_b32_e32 v170, 16, v225
	v_and_b32_e32 v171, 0xffff0000, v225
	v_pk_add_f32 v[96:97], v[96:97], v[168:169]
	v_pk_add_f32 v[98:99], v[98:99], v[170:171]
	global_load_dwordx2 v[224:225], v135, s[26:27] offset:352
	s_nop 0
	v_cvt_pk_bf16_f32 v120, v120, v121
	v_cvt_pk_bf16_f32 v121, v122, v123
	v_cvt_pk_bf16_f32 v122, v112, v113
	v_cvt_pk_bf16_f32 v123, v114, v115
	v_cvt_pk_bf16_f32 v104, v104, v105
	v_cvt_pk_bf16_f32 v105, v106, v107
	v_cvt_pk_bf16_f32 v106, v96, v97
	v_cvt_pk_bf16_f32 v107, v98, v99
	s_nop 1
	v_permlane16_swap_b32_e32 v120, v122
	v_permlane16_swap_b32_e32 v121, v123
	v_permlane16_swap_b32_e32 v104, v106
	v_permlane16_swap_b32_e32 v105, v107
	global_store_dwordx4 v139, v[120:123], s[26:27] offset:0
	global_store_dwordx4 v139, v[104:107], s[26:27] offset:64
	s_waitcnt vmcnt(19)
	v_lshlrev_b32_e32 v168, 16, v226
	v_and_b32_e32 v169, 0xffff0000, v226
	v_lshlrev_b32_e32 v170, 16, v227
	v_and_b32_e32 v171, 0xffff0000, v227
	v_pk_add_f32 v[92:93], v[92:93], v[168:169]
	v_pk_add_f32 v[94:95], v[94:95], v[170:171]
	global_load_dwordx2 v[226:227], v136, s[26:27] offset:256
	s_waitcnt vmcnt(19)
; __device__ __forceinline__ float bflo(unsigned u) { return __uint_as_float(u << 16); }
; __device__ __forceinline__ float bfhi(unsigned u) { return __uint_as_float(u & 0xffff0000u); }
; #define WIDE_STORE(BASE, LD, COFF, O) do { if ((m & 1) == 0) opend[n] = (O); \
;                 else *(uint4*)((BASE) + (size_t)tok * (LD) + (ncw - (COFF))) = swap_pair(opend[n], (O)); } while (0)
; __device__ __forceinline__ uint4 swap_pair(const uint2 a, const uint2 b) {
;   const auto rx = __builtin_amdgcn_permlane16_swap(a.x, b.x, false, false);
;   const auto ry = __builtin_amdgcn_permlane16_swap(a.y, b.y, false, false);
;   return make_uint4(rx[0], ry[0], rx[1], ry[1]);
; }
;     ...
;                 uint2* ph = (uint2*)((u16*)(ws + OFF_RB) + (size_t)tok * DM + nc);
;                 const uint2 hb = *ph;
;                 uint2 o; o.x = pk2(bflo(hb.x) + v[0], bfhi(hb.x) + v[1]); o.y = pk2(bflo(hb.y) + v[2], bfhi(hb.y) + v[3]);
;                 WIDE_STORE((u16*)(ws + OFF_RB), DM, 0, o);
	v_lshlrev_b32_e32 v168, 16, v228
	v_and_b32_e32 v169, 0xffff0000, v228
	v_lshlrev_b32_e32 v170, 16, v229
	v_and_b32_e32 v171, 0xffff0000, v229
	v_pk_add_f32 v[84:85], v[84:85], v[168:169]
	v_pk_add_f32 v[86:87], v[86:87], v[170:171]
	global_load_dwordx2 v[228:229], v136, s[26:27] offset:288
	s_waitcnt vmcnt(19)
	v_lshlrev_b32_e32 v168, 16, v230
	v_and_b32_e32 v169, 0xffff0000, v230
	v_lshlrev_b32_e32 v170, 16, v231
	v_and_b32_e32 v171, 0xffff0000, v231
	v_pk_add_f32 v[76:77], v[76:77], v[168:169]
	v_pk_add_f32 v[78:79], v[78:79], v[170:171]
	global_load_dwordx2 v[230:231], v136, s[26:27] offset:320
	s_waitcnt vmcnt(19)
	v_lshlrev_b32_e32 v168, 16, v232
	v_and_b32_e32 v169, 0xffff0000, v232
	v_lshlrev_b32_e32 v170, 16, v233
	v_and_b32_e32 v171, 0xffff0000, v233
	v_pk_add_f32 v[68:69], v[68:69], v[168:169]
	v_pk_add_f32 v[70:71], v[70:71], v[170:171]
	global_load_dwordx2 v[232:233], v136, s[26:27] offset:352
	s_nop 0
	v_cvt_pk_bf16_f32 v92, v92, v93
	v_cvt_pk_bf16_f32 v93, v94, v95
	v_cvt_pk_bf16_f32 v94, v84, v85
	v_cvt_pk_bf16_f32 v95, v86, v87
	v_cvt_pk_bf16_f32 v76, v76, v77
	v_cvt_pk_bf16_f32 v77, v78, v79
	v_cvt_pk_bf16_f32 v78, v68, v69
	v_cvt_pk_bf16_f32 v79, v70, v71
	s_nop 1
	v_permlane16_swap_b32_e32 v92, v94
	v_permlane16_swap_b32_e32 v93, v95
	v_permlane16_swap_b32_e32 v76, v78
	v_permlane16_swap_b32_e32 v77, v79
	global_store_dwordx4 v140, v[92:95], s[26:27] offset:0
	global_store_dwordx4 v140, v[76:79], s[26:27] offset:64
	s_waitcnt vmcnt(21)
	v_lshlrev_b32_e32 v168, 16, v234
	v_and_b32_e32 v169, 0xffff0000, v234
	v_lshlrev_b32_e32 v170, 16, v235
	v_and_b32_e32 v171, 0xffff0000, v235
	v_pk_add_f32 v[88:89], v[88:89], v[168:169]
	v_pk_add_f32 v[90:91], v[90:91], v[170:171]
	global_load_dwordx2 v[234:235], v137, s[26:27] offset:256
	s_waitcnt vmcnt(21)
	v_lshlrev_b32_e32 v168, 16, v236
	v_and_b32_e32 v169, 0xffff0000, v236
	v_lshlrev_b32_e32 v170, 16, v237
	v_and_b32_e32 v171, 0xffff0000, v237
	v_pk_add_f32 v[80:81], v[80:81], v[168:169]
	v_pk_add_f32 v[82:83], v[82:83], v[170:171]
	global_load_dwordx2 v[236:237], v137, s[26:27] offset:288
	s_waitcnt vmcnt(21)
	v_lshlrev_b32_e32 v168, 16, v238
	v_and_b32_e32 v169, 0xffff0000, v238
	v_lshlrev_b32_e32 v170, 16, v239
	v_and_b32_e32 v171, 0xffff0000, v239
	v_pk_add_f32 v[72:73], v[72:73], v[168:169]
	v_pk_add_f32 v[74:75], v[74:75], v[170:171]
	global_load_dwordx2 v[238:239], v137, s[26:27] offset:320
	s_waitcnt vmcnt(21)
	v_lshlrev_b32_e32 v168, 16, v240
	v_and_b32_e32 v169, 0xffff0000, v240
	v_lshlrev_b32_e32 v170, 16, v241
	v_and_b32_e32 v171, 0xffff0000, v241
	v_pk_add_f32 v[64:65], v[64:65], v[168:169]
	v_pk_add_f32 v[66:67], v[66:67], v[170:171]
	global_load_dwordx2 v[240:241], v137, s[26:27] offset:352
	s_nop 0
	v_cvt_pk_bf16_f32 v88, v88, v89
	v_cvt_pk_bf16_f32 v89, v90, v91
	v_cvt_pk_bf16_f32 v90, v80, v81
	v_cvt_pk_bf16_f32 v91, v82, v83
	v_cvt_pk_bf16_f32 v72, v72, v73
	v_cvt_pk_bf16_f32 v73, v74, v75
	v_cvt_pk_bf16_f32 v74, v64, v65
	v_cvt_pk_bf16_f32 v75, v66, v67
	s_nop 1
	v_permlane16_swap_b32_e32 v88, v90
	v_permlane16_swap_b32_e32 v89, v91
	v_permlane16_swap_b32_e32 v72, v74
	v_permlane16_swap_b32_e32 v73, v75
	global_store_dwordx4 v141, v[88:91], s[26:27] offset:0
	global_store_dwordx4 v141, v[72:75], s[26:27] offset:64
	s_waitcnt vmcnt(23)
	v_lshlrev_b32_e32 v168, 16, v210
	v_and_b32_e32 v169, 0xffff0000, v210
	v_lshlrev_b32_e32 v170, 16, v211
	v_and_b32_e32 v171, 0xffff0000, v211
	v_pk_add_f32 v[60:61], v[60:61], v[168:169]
	v_pk_add_f32 v[62:63], v[62:63], v[170:171]
	s_waitcnt vmcnt(22)
	v_lshlrev_b32_e32 v168, 16, v212
	v_and_b32_e32 v169, 0xffff0000, v212
	v_lshlrev_b32_e32 v170, 16, v213
	v_and_b32_e32 v171, 0xffff0000, v213
	v_pk_add_f32 v[52:53], v[52:53], v[168:169]
	v_pk_add_f32 v[54:55], v[54:55], v[170:171]
	s_waitcnt vmcnt(21)
	v_lshlrev_b32_e32 v168, 16, v214
	v_and_b32_e32 v169, 0xffff0000, v214
	v_lshlrev_b32_e32 v170, 16, v215
	v_and_b32_e32 v171, 0xffff0000, v215
	v_pk_add_f32 v[44:45], v[44:45], v[168:169]
	v_pk_add_f32 v[46:47], v[46:47], v[170:171]
	s_waitcnt vmcnt(20)
	v_lshlrev_b32_e32 v168, 16, v216
	v_and_b32_e32 v169, 0xffff0000, v216
	v_lshlrev_b32_e32 v170, 16, v217
	v_and_b32_e32 v171, 0xffff0000, v217
	v_pk_add_f32 v[36:37], v[36:37], v[168:169]
	v_pk_add_f32 v[38:39], v[38:39], v[170:171]
	s_nop 0
	v_cvt_pk_bf16_f32 v60, v60, v61
	v_cvt_pk_bf16_f32 v61, v62, v63
	v_cvt_pk_bf16_f32 v62, v52, v53
	v_cvt_pk_bf16_f32 v63, v54, v55
	v_cvt_pk_bf16_f32 v44, v44, v45
	v_cvt_pk_bf16_f32 v45, v46, v47
	v_cvt_pk_bf16_f32 v46, v36, v37
	v_cvt_pk_bf16_f32 v47, v38, v39
	s_nop 1
	v_permlane16_swap_b32_e32 v60, v62
	v_permlane16_swap_b32_e32 v61, v63
	v_permlane16_swap_b32_e32 v44, v46
	v_permlane16_swap_b32_e32 v45, v47
	global_store_dwordx4 v138, v[60:63], s[26:27] offset:256
	global_store_dwordx4 v138, v[44:47], s[26:27] offset:320
	s_waitcnt vmcnt(19)
	v_lshlrev_b32_e32 v168, 16, v218
	v_and_b32_e32 v169, 0xffff0000, v218
	v_lshlrev_b32_e32 v170, 16, v219
	v_and_b32_e32 v171, 0xffff0000, v219
	v_pk_add_f32 v[56:57], v[56:57], v[168:169]
	v_pk_add_f32 v[58:59], v[58:59], v[170:171]
	s_waitcnt vmcnt(18)
	v_lshlrev_b32_e32 v168, 16, v220
	v_and_b32_e32 v169, 0xffff0000, v220
	v_lshlrev_b32_e32 v170, 16, v221
	v_and_b32_e32 v171, 0xffff0000, v221
	v_pk_add_f32 v[48:49], v[48:49], v[168:169]
	v_pk_add_f32 v[50:51], v[50:51], v[170:171]
	s_waitcnt vmcnt(17)
	v_lshlrev_b32_e32 v168, 16, v222
	v_and_b32_e32 v169, 0xffff0000, v222
	v_lshlrev_b32_e32 v170, 16, v223
	v_and_b32_e32 v171, 0xffff0000, v223
	v_pk_add_f32 v[40:41], v[40:41], v[168:169]
	v_pk_add_f32 v[42:43], v[42:43], v[170:171]
	s_waitcnt vmcnt(16)
; __device__ __forceinline__ float bflo(unsigned u) { return __uint_as_float(u << 16); }
; __device__ __forceinline__ float bfhi(unsigned u) { return __uint_as_float(u & 0xffff0000u); }
; #define WIDE_STORE(BASE, LD, COFF, O) do { if ((m & 1) == 0) opend[n] = (O); \
;                 else *(uint4*)((BASE) + (size_t)tok * (LD) + (ncw - (COFF))) = swap_pair(opend[n], (O)); } while (0)
;     ...
; #pragma unroll
;     for (int a = 0; a < 2; ++a)
; #pragma unroll
;       for (int b = 0; b < 2; ++b)
; #pragma unroll
;         for (int m = 0; m < 4; ++m)
; #pragma unroll
;           for (int n = 0; n < 2; ++n) acc[a][b][m][n] = f32x4{0.f, 0.f, 0.f, 0.f};
;     ...
;                 uint2* ph = (uint2*)((u16*)(ws + OFF_RB) + (size_t)tok * DM + nc);
;                 const uint2 hb = *ph;
;                 uint2 o; o.x = pk2(bflo(hb.x) + v[0], bfhi(hb.x) + v[1]); o.y = pk2(bflo(hb.y) + v[2], bfhi(hb.y) + v[3]);
;                 WIDE_STORE((u16*)(ws + OFF_RB), DM, 0, o);
;               }
;     ...
;             }
;     }
;     asm volatile("s_waitcnt vmcnt(0)" ::: "memory");
;     if (has_next && wr == 1) __builtin_amdgcn_s_barrier();
	v_lshlrev_b32_e32 v168, 16, v224
	v_and_b32_e32 v169, 0xffff0000, v224
	v_lshlrev_b32_e32 v170, 16, v225
	v_and_b32_e32 v171, 0xffff0000, v225
	v_pk_add_f32 v[32:33], v[32:33], v[168:169]
	v_pk_add_f32 v[34:35], v[34:35], v[170:171]
	s_nop 0
	v_cvt_pk_bf16_f32 v56, v56, v57
	v_cvt_pk_bf16_f32 v57, v58, v59
	v_cvt_pk_bf16_f32 v58, v48, v49
	v_cvt_pk_bf16_f32 v59, v50, v51
	v_cvt_pk_bf16_f32 v40, v40, v41
	v_cvt_pk_bf16_f32 v41, v42, v43
	v_cvt_pk_bf16_f32 v42, v32, v33
	v_cvt_pk_bf16_f32 v43, v34, v35
	s_nop 1
	v_permlane16_swap_b32_e32 v56, v58
	v_permlane16_swap_b32_e32 v57, v59
	v_permlane16_swap_b32_e32 v40, v42
	v_permlane16_swap_b32_e32 v41, v43
	global_store_dwordx4 v139, v[56:59], s[26:27] offset:256
	global_store_dwordx4 v139, v[40:43], s[26:27] offset:320
	s_waitcnt vmcnt(15)
	v_lshlrev_b32_e32 v168, 16, v226
	v_and_b32_e32 v169, 0xffff0000, v226
	v_lshlrev_b32_e32 v170, 16, v227
	v_and_b32_e32 v171, 0xffff0000, v227
	v_pk_add_f32 v[28:29], v[28:29], v[168:169]
	v_pk_add_f32 v[30:31], v[30:31], v[170:171]
	s_waitcnt vmcnt(14)
	v_lshlrev_b32_e32 v168, 16, v228
	v_and_b32_e32 v169, 0xffff0000, v228
	v_lshlrev_b32_e32 v170, 16, v229
	v_and_b32_e32 v171, 0xffff0000, v229
	v_pk_add_f32 v[20:21], v[20:21], v[168:169]
	v_pk_add_f32 v[22:23], v[22:23], v[170:171]
	s_waitcnt vmcnt(13)
	v_lshlrev_b32_e32 v168, 16, v230
	v_and_b32_e32 v169, 0xffff0000, v230
	v_lshlrev_b32_e32 v170, 16, v231
	v_and_b32_e32 v171, 0xffff0000, v231
	v_pk_add_f32 v[12:13], v[12:13], v[168:169]
	v_pk_add_f32 v[14:15], v[14:15], v[170:171]
	s_waitcnt vmcnt(12)
	v_lshlrev_b32_e32 v168, 16, v232
	v_and_b32_e32 v169, 0xffff0000, v232
	v_lshlrev_b32_e32 v170, 16, v233
	v_and_b32_e32 v171, 0xffff0000, v233
	v_pk_add_f32 v[4:5], v[4:5], v[168:169]
	v_pk_add_f32 v[6:7], v[6:7], v[170:171]
	s_nop 0
	v_cvt_pk_bf16_f32 v28, v28, v29
	v_cvt_pk_bf16_f32 v29, v30, v31
	v_cvt_pk_bf16_f32 v30, v20, v21
	v_cvt_pk_bf16_f32 v31, v22, v23
	v_cvt_pk_bf16_f32 v12, v12, v13
	v_cvt_pk_bf16_f32 v13, v14, v15
	v_cvt_pk_bf16_f32 v14, v4, v5
	v_cvt_pk_bf16_f32 v15, v6, v7
	s_nop 1
	v_permlane16_swap_b32_e32 v28, v30
	v_permlane16_swap_b32_e32 v29, v31
	v_permlane16_swap_b32_e32 v12, v14
	v_permlane16_swap_b32_e32 v13, v15
	global_store_dwordx4 v140, v[28:31], s[26:27] offset:256
	global_store_dwordx4 v140, v[12:15], s[26:27] offset:320
	s_waitcnt vmcnt(11)
	v_lshlrev_b32_e32 v168, 16, v234
	v_and_b32_e32 v169, 0xffff0000, v234
	v_lshlrev_b32_e32 v170, 16, v235
	v_and_b32_e32 v171, 0xffff0000, v235
	v_pk_add_f32 v[24:25], v[24:25], v[168:169]
	v_pk_add_f32 v[26:27], v[26:27], v[170:171]
	s_waitcnt vmcnt(10)
	v_lshlrev_b32_e32 v168, 16, v236
	v_and_b32_e32 v169, 0xffff0000, v236
	v_lshlrev_b32_e32 v170, 16, v237
	v_and_b32_e32 v171, 0xffff0000, v237
	v_pk_add_f32 v[16:17], v[16:17], v[168:169]
	v_pk_add_f32 v[18:19], v[18:19], v[170:171]
	s_waitcnt vmcnt(9)
	v_lshlrev_b32_e32 v168, 16, v238
	v_and_b32_e32 v169, 0xffff0000, v238
	v_lshlrev_b32_e32 v170, 16, v239
	v_and_b32_e32 v171, 0xffff0000, v239
	v_pk_add_f32 v[8:9], v[8:9], v[168:169]
	v_pk_add_f32 v[10:11], v[10:11], v[170:171]
	s_waitcnt vmcnt(8)
	v_lshlrev_b32_e32 v168, 16, v240
	v_and_b32_e32 v169, 0xffff0000, v240
	v_lshlrev_b32_e32 v170, 16, v241
	v_and_b32_e32 v171, 0xffff0000, v241
	v_pk_add_f32 v[0:1], v[0:1], v[168:169]
	v_pk_add_f32 v[2:3], v[2:3], v[170:171]
	s_nop 0
	v_cvt_pk_bf16_f32 v24, v24, v25
	v_cvt_pk_bf16_f32 v25, v26, v27
	v_cvt_pk_bf16_f32 v26, v16, v17
	v_cvt_pk_bf16_f32 v27, v18, v19
	v_cvt_pk_bf16_f32 v8, v8, v9
	v_cvt_pk_bf16_f32 v9, v10, v11
	v_cvt_pk_bf16_f32 v10, v0, v1
	v_cvt_pk_bf16_f32 v11, v2, v3
	s_nop 1
	v_permlane16_swap_b32_e32 v24, v26
	v_permlane16_swap_b32_e32 v25, v27
	v_permlane16_swap_b32_e32 v8, v10
	v_permlane16_swap_b32_e32 v9, v11
	global_store_dwordx4 v141, v[24:27], s[26:27] offset:256
	global_store_dwordx4 v141, v[8:11], s[26:27] offset:320
	s_and_b64 s[0:1], s[56:57], s[8:9]
	s_andn2_b64 vcc, exec, s[0:1]
	s_nop 1
	v_mov_b32_e32 v0, 0
	v_mov_b32_e32 v1, v0
	v_mov_b32_e32 v2, v0
	v_mov_b32_e32 v3, v0
	v_mov_b32_e32 v4, v0
	v_mov_b32_e32 v5, v0
	v_mov_b32_e32 v6, v0
	v_mov_b32_e32 v7, v0
	v_mov_b32_e32 v8, v0
	v_mov_b32_e32 v9, v0
	v_mov_b32_e32 v10, v0
	v_mov_b32_e32 v11, v0
	v_mov_b32_e32 v12, v0
	v_mov_b32_e32 v13, v0
	v_mov_b32_e32 v14, v0
	v_mov_b32_e32 v15, v0
	v_mov_b32_e32 v16, v0
	v_mov_b32_e32 v17, v0
	v_mov_b32_e32 v18, v0
	v_mov_b32_e32 v19, v0
	v_mov_b32_e32 v20, v0
	v_mov_b32_e32 v21, v0
	v_mov_b32_e32 v22, v0
	v_mov_b32_e32 v23, v0
	v_mov_b32_e32 v24, v0
	v_mov_b32_e32 v25, v0
	v_mov_b32_e32 v26, v0
	v_mov_b32_e32 v27, v0
	v_mov_b32_e32 v28, v0
	v_mov_b32_e32 v29, v0
	v_mov_b32_e32 v30, v0
	v_mov_b32_e32 v31, v0
	v_mov_b32_e32 v32, v0
	v_mov_b32_e32 v33, v0
	v_mov_b32_e32 v34, v0
	v_mov_b32_e32 v35, v0
	v_mov_b32_e32 v36, v0
	v_mov_b32_e32 v37, v0
	v_mov_b32_e32 v38, v0
	v_mov_b32_e32 v39, v0
	v_mov_b32_e32 v40, v0
	v_mov_b32_e32 v41, v0
	v_mov_b32_e32 v42, v0
	v_mov_b32_e32 v43, v0
	v_mov_b32_e32 v44, v0
	v_mov_b32_e32 v45, v0
	v_mov_b32_e32 v46, v0
	v_mov_b32_e32 v47, v0
	v_mov_b32_e32 v48, v0
	v_mov_b32_e32 v49, v0
	v_mov_b32_e32 v50, v0
	v_mov_b32_e32 v51, v0
	v_mov_b32_e32 v52, v0
	v_mov_b32_e32 v53, v0
	v_mov_b32_e32 v54, v0
	v_mov_b32_e32 v55, v0
	v_mov_b32_e32 v56, v0
	v_mov_b32_e32 v57, v0
	v_mov_b32_e32 v58, v0
	v_mov_b32_e32 v59, v0
	v_mov_b32_e32 v60, v0
	v_mov_b32_e32 v61, v0
	v_mov_b32_e32 v62, v0
	v_mov_b32_e32 v63, v0
	v_mov_b32_e32 v64, v0
	v_mov_b32_e32 v65, v0
	v_mov_b32_e32 v66, v0
	v_mov_b32_e32 v67, v0
	v_mov_b32_e32 v68, v0
	v_mov_b32_e32 v69, v0
	v_mov_b32_e32 v70, v0
	v_mov_b32_e32 v71, v0
	v_mov_b32_e32 v72, v0
	v_mov_b32_e32 v73, v0
	v_mov_b32_e32 v74, v0
	v_mov_b32_e32 v75, v0
	v_mov_b32_e32 v76, v0
	v_mov_b32_e32 v77, v0
	v_mov_b32_e32 v78, v0
	v_mov_b32_e32 v79, v0
	v_mov_b32_e32 v80, v0
	v_mov_b32_e32 v81, v0
	v_mov_b32_e32 v82, v0
	v_mov_b32_e32 v83, v0
	v_mov_b32_e32 v84, v0
	v_mov_b32_e32 v85, v0
	v_mov_b32_e32 v86, v0
	v_mov_b32_e32 v87, v0
	v_mov_b32_e32 v88, v0
	v_mov_b32_e32 v89, v0
	v_mov_b32_e32 v90, v0
	v_mov_b32_e32 v91, v0
	v_mov_b32_e32 v92, v0
	v_mov_b32_e32 v93, v0
	v_mov_b32_e32 v94, v0
	v_mov_b32_e32 v95, v0
	v_mov_b32_e32 v96, v0
	v_mov_b32_e32 v97, v0
	v_mov_b32_e32 v98, v0
	v_mov_b32_e32 v99, v0
	v_mov_b32_e32 v100, v0
	v_mov_b32_e32 v101, v0
	v_mov_b32_e32 v102, v0
	v_mov_b32_e32 v103, v0
	v_mov_b32_e32 v104, v0
	v_mov_b32_e32 v105, v0
	v_mov_b32_e32 v106, v0
	v_mov_b32_e32 v107, v0
	v_mov_b32_e32 v108, v0
	v_mov_b32_e32 v109, v0
	v_mov_b32_e32 v110, v0
	v_mov_b32_e32 v111, v0
	v_mov_b32_e32 v112, v0
	v_mov_b32_e32 v113, v0
	v_mov_b32_e32 v114, v0
	v_mov_b32_e32 v115, v0
	v_mov_b32_e32 v116, v0
	v_mov_b32_e32 v117, v0
	v_mov_b32_e32 v118, v0
	v_mov_b32_e32 v119, v0
	v_mov_b32_e32 v120, v0
	v_mov_b32_e32 v121, v0
	v_mov_b32_e32 v122, v0
	v_mov_b32_e32 v123, v0
	v_mov_b32_e32 v124, v0
	v_mov_b32_e32 v125, v0
	v_mov_b32_e32 v126, v0
	v_mov_b32_e32 v127, v0
	s_waitcnt vmcnt(0)
	s_cbranch_vccnz .LBB0_1077
	s_barrier
	s_branch .LBB0_1077
